# speedup vs baseline: 1.0127x; 1.0127x over previous
; __device__ __forceinline__ unsigned pack2(float a, float b) { const f32x2_t v = {a, b}; const bf16x2_t r = __builtin_convertvector(v, bf16x2_t); return __builtin_bit_cast(unsigned, r); }
; template <class Epi>
; __device__ __forceinline__ void gemm_tile8(const u16* __restrict__ A, long lda, const u16* __restrict__ Bt, long ldb, int K, char* shmc, Epi epi){
;     ...
; #pragma unroll
;   for(int ai=0;ai<2;++ai)
; #pragma unroll
;     for(int bj=0;bj<2;++bj)
; #pragma unroll
;       for(int m=0;m<4;++m)
; #pragma unroll
;         for(int n=0;n<2;++n) epi(ai*HALF+wr*64+m*16+fr, bj*HALF+wc*32+n*16+fq*4, acc[ai][bj][m][n]);
; __device__ __forceinline__ void ph_proj(const Params& p, int l, char* shm) {
;     ...
;     const int act = ((pn >= 10 && pn < 18) || pn >= 51) ? 1 : ((pn >= 35 && pn < 51) ? 2 : 0);
;     gemm_tile8(p.H + (size_t)brow * DM, DM, W + (size_t)pn * 256 * DM, DM, DM, shm, [&](int r, int c, f32x4 v) {
;       if (pn == 34) {
;         *(f32x4*)(p.KW + (size_t)(brow + r) * 256 + c) = v;
;       } else {
;         float y[4];
; #pragma unroll
;         for (int j = 0; j < 4; ++j) {
;           float xv = v[j];
;           if (act == 1) xv = xv * __builtin_amdgcn_rcpf(1.f + __expf(-xv));
;           else if (act == 2) xv = 0.5f * xv * (1.f + erf_fast(xv * 0.70710678118654752f));
;           y[j] = xv;
;         }
;         *(uint2*)(p.P + (size_t)(brow + r) * NP + pn * 256 + c) = uint2{pack2(y[0], y[1]), pack2(y[2], y[3])};
;       }
;     });
.LBB0_966:
	s_add_i32 s0, s6, -10
	s_cmp_lt_u32 s0, 8
	s_cselect_b64 s[0:1], -1, 0
	s_cmp_gt_i32 s6, 50
	s_cselect_b64 s[10:11], -1, 0
	s_or_b64 s[0:1], s[10:11], s[0:1]
	s_cmp_gt_i32 s6, 34
	s_cselect_b32 s7, 2, 0
	s_and_b64 s[0:1], s[0:1], exec
	v_lshrrev_b32_e32 v32, 2, v32
	s_cselect_b32 s7, 1, s7
	v_and_b32_e32 v32, 12, v32
	s_cmp_lg_u32 s6, 34
	v_readlane_b32 s16, v245, 25
	v_lshl_or_b32 v134, s9, 5, v32
	s_cselect_b64 s[10:11], -1, 0
	s_cmp_eq_u32 s6, 34
	s_mov_b64 s[0:1], -1
	v_readlane_b32 s15, v245, 24
	v_readlane_b32 s17, v245, 26
	v_readlane_b32 s18, v245, 27
	v_readlane_b32 s19, v245, 28
	v_readlane_b32 s20, v245, 29
	v_readlane_b32 s21, v245, 30
	v_readlane_b32 s22, v245, 31
	v_readlane_b32 s23, v245, 32
	v_readlane_b32 s24, v245, 33
	v_readlane_b32 s25, v245, 34
	v_readlane_b32 s26, v245, 35
	v_readlane_b32 s27, v245, 36
	v_readlane_b32 s28, v245, 37
	v_readlane_b32 s29, v245, 38
	v_readlane_b32 s30, v245, 39
	v_readlane_b32 s31, v245, 40
	v_readlane_b32 s14, v245, 48
	s_cbranch_scc1 .Lpj_f32
	v_add_u32_e32 v135, s8, v146
	v_mov_b32_e32 v137, v33
	v_mov_b32_e32 v139, v33
	s_lshl_b32 s0, s6, 9
	s_add_u32 s0, s26, s0
	s_addc_u32 s1, s27, 0
	s_movk_i32 s9, 0x7600
	v_lshlrev_b32_e32 v136, 1, v134
	v_and_b32_e32 v138, 16, v204
	v_lshrrev_b32_e32 v139, 1, v138
	v_add3_u32 v136, v136, v138, v139
	v_mov_b32_e32 v139, v33
	v_mov_b32_e32 v138, v135
	v_mov_b64_e32 v[160:161], s[0:1]
	v_mad_i64_i32 v[160:161], s[10:11], v138, s9, v[160:161]
	v_lshl_add_u64 v[160:161], v[160:161], 0, v[136:137]
	v_add_u32_e32 v138, 16, v135
	v_mov_b64_e32 v[162:163], s[0:1]
	v_mad_i64_i32 v[162:163], s[10:11], v138, s9, v[162:163]
	v_lshl_add_u64 v[162:163], v[162:163], 0, v[136:137]
	v_add_u32_e32 v138, 32, v135
	v_mov_b64_e32 v[164:165], s[0:1]
	v_mad_i64_i32 v[164:165], s[10:11], v138, s9, v[164:165]
	v_lshl_add_u64 v[164:165], v[164:165], 0, v[136:137]
	v_add_u32_e32 v138, 48, v135
	v_mov_b64_e32 v[166:167], s[0:1]
	v_mad_i64_i32 v[166:167], s[10:11], v138, s9, v[166:167]
	v_lshl_add_u64 v[166:167], v[166:167], 0, v[136:137]
	v_add_u32_e32 v138, 0x80, v135
	v_mov_b64_e32 v[168:169], s[0:1]
	v_mad_i64_i32 v[168:169], s[10:11], v138, s9, v[168:169]
	v_lshl_add_u64 v[168:169], v[168:169], 0, v[136:137]
	v_add_u32_e32 v138, 0x90, v135
	v_mov_b64_e32 v[170:171], s[0:1]
	v_mad_i64_i32 v[170:171], s[10:11], v138, s9, v[170:171]
	v_lshl_add_u64 v[170:171], v[170:171], 0, v[136:137]
	v_add_u32_e32 v138, 0xa0, v135
	v_mov_b64_e32 v[172:173], s[0:1]
	v_mad_i64_i32 v[172:173], s[10:11], v138, s9, v[172:173]
	v_lshl_add_u64 v[172:173], v[172:173], 0, v[136:137]
	v_add_u32_e32 v138, 0xb0, v135
	v_mov_b64_e32 v[174:175], s[0:1]
	v_mad_i64_i32 v[174:175], s[10:11], v138, s9, v[174:175]
	v_lshl_add_u64 v[174:175], v[174:175], 0, v[136:137]
	s_cmp_eq_u32 s7, 1
	s_cbranch_scc1 .Lpj_silu
	s_cmp_eq_u32 s7, 2
	s_cbranch_scc1 .Lpj_gelu
	v_cvt_pk_bf16_f32 v140, v126, v127
	v_cvt_pk_bf16_f32 v141, v128, v129
	v_cvt_pk_bf16_f32 v142, v122, v123
	v_cvt_pk_bf16_f32 v143, v124, v125
	v_cvt_pk_bf16_f32 v144, v118, v119
	v_cvt_pk_bf16_f32 v145, v120, v121
	v_cvt_pk_bf16_f32 v146, v114, v115
	v_cvt_pk_bf16_f32 v147, v116, v117
	s_nop 1
	v_permlane16_swap_b32_e32 v140, v142
	v_permlane16_swap_b32_e32 v141, v143
	global_store_dwordx4 v[160:161], v[140:143], off
	v_cvt_pk_bf16_f32 v148, v110, v111
	v_cvt_pk_bf16_f32 v149, v112, v113
	v_cvt_pk_bf16_f32 v150, v106, v107
	v_cvt_pk_bf16_f32 v151, v108, v109
	s_nop 1
	v_permlane16_swap_b32_e32 v144, v146
	v_permlane16_swap_b32_e32 v145, v147
	global_store_dwordx4 v[162:163], v[144:147], off
	v_cvt_pk_bf16_f32 v140, v102, v103
	v_cvt_pk_bf16_f32 v141, v104, v105
	v_cvt_pk_bf16_f32 v142, v98, v99
	v_cvt_pk_bf16_f32 v143, v100, v101
	s_nop 1
	v_permlane16_swap_b32_e32 v148, v150
	v_permlane16_swap_b32_e32 v149, v151
	global_store_dwordx4 v[164:165], v[148:151], off
	v_cvt_pk_bf16_f32 v144, v94, v95
	v_cvt_pk_bf16_f32 v145, v96, v97
	v_cvt_pk_bf16_f32 v146, v90, v91
	v_cvt_pk_bf16_f32 v147, v92, v93
	s_nop 1
	v_permlane16_swap_b32_e32 v140, v142
	v_permlane16_swap_b32_e32 v141, v143
	global_store_dwordx4 v[166:167], v[140:143], off
	v_cvt_pk_bf16_f32 v148, v86, v87
	v_cvt_pk_bf16_f32 v149, v88, v89
	v_cvt_pk_bf16_f32 v150, v82, v83
	v_cvt_pk_bf16_f32 v151, v84, v85
	s_nop 1
	v_permlane16_swap_b32_e32 v144, v146
	v_permlane16_swap_b32_e32 v145, v147
	global_store_dwordx4 v[160:161], v[144:147], off offset:256
	v_cvt_pk_bf16_f32 v140, v78, v79
	v_cvt_pk_bf16_f32 v141, v80, v81
	v_cvt_pk_bf16_f32 v142, v74, v75
	v_cvt_pk_bf16_f32 v143, v76, v77
	s_nop 1
	v_permlane16_swap_b32_e32 v148, v150
	v_permlane16_swap_b32_e32 v149, v151
	global_store_dwordx4 v[162:163], v[148:151], off offset:256
	v_cvt_pk_bf16_f32 v144, v70, v71
	v_cvt_pk_bf16_f32 v145, v72, v73
	v_cvt_pk_bf16_f32 v146, v66, v67
	v_cvt_pk_bf16_f32 v147, v68, v69
	s_nop 1
	v_permlane16_swap_b32_e32 v140, v142
	v_permlane16_swap_b32_e32 v141, v143
	global_store_dwordx4 v[164:165], v[140:143], off offset:256
	v_cvt_pk_bf16_f32 v148, v62, v63
	v_cvt_pk_bf16_f32 v149, v64, v65
	v_cvt_pk_bf16_f32 v150, v58, v59
	v_cvt_pk_bf16_f32 v151, v60, v61
	s_nop 1
	v_permlane16_swap_b32_e32 v144, v146
	v_permlane16_swap_b32_e32 v145, v147
	global_store_dwordx4 v[166:167], v[144:147], off offset:256
	v_cvt_pk_bf16_f32 v140, v54, v55
	v_cvt_pk_bf16_f32 v141, v56, v57
	v_cvt_pk_bf16_f32 v142, v50, v51
	v_cvt_pk_bf16_f32 v143, v52, v53
	s_nop 1
	v_permlane16_swap_b32_e32 v148, v150
	v_permlane16_swap_b32_e32 v149, v151
	global_store_dwordx4 v[168:169], v[148:151], off
	v_cvt_pk_bf16_f32 v144, v46, v47
	v_cvt_pk_bf16_f32 v145, v48, v49
	v_cvt_pk_bf16_f32 v146, v42, v43
	v_cvt_pk_bf16_f32 v147, v44, v45
; __device__ __forceinline__ unsigned pack2(float a, float b) { const f32x2_t v = {a, b}; const bf16x2_t r = __builtin_convertvector(v, bf16x2_t); return __builtin_bit_cast(unsigned, r); }
; __device__ __forceinline__ void ph_proj(const Params& p, int l, char* shm) {
;     ...
;         float y[4];
; #pragma unroll
;         for (int j = 0; j < 4; ++j) {
;           float xv = v[j];
;           if (act == 1) xv = xv * __builtin_amdgcn_rcpf(1.f + __expf(-xv));
;           else if (act == 2) xv = 0.5f * xv * (1.f + erf_fast(xv * 0.70710678118654752f));
;           y[j] = xv;
;         }
;         *(uint2*)(p.P + (size_t)(brow + r) * NP + pn * 256 + c) = uint2{pack2(y[0], y[1]), pack2(y[2], y[3])};
	s_nop 1
	v_permlane16_swap_b32_e32 v140, v142
	v_permlane16_swap_b32_e32 v141, v143
	global_store_dwordx4 v[170:171], v[140:143], off
	v_cvt_pk_bf16_f32 v148, v38, v39
	v_cvt_pk_bf16_f32 v149, v40, v41
	v_cvt_pk_bf16_f32 v150, v34, v35
	v_cvt_pk_bf16_f32 v151, v36, v37
	s_nop 1
	v_permlane16_swap_b32_e32 v144, v146
	v_permlane16_swap_b32_e32 v145, v147
	global_store_dwordx4 v[172:173], v[144:147], off
	v_cvt_pk_bf16_f32 v140, v28, v29
	v_cvt_pk_bf16_f32 v141, v30, v31
	v_cvt_pk_bf16_f32 v142, v24, v25
	v_cvt_pk_bf16_f32 v143, v26, v27
	s_nop 1
	v_permlane16_swap_b32_e32 v148, v150
	v_permlane16_swap_b32_e32 v149, v151
	global_store_dwordx4 v[174:175], v[148:151], off
	v_cvt_pk_bf16_f32 v144, v20, v21
	v_cvt_pk_bf16_f32 v145, v22, v23
	v_cvt_pk_bf16_f32 v146, v16, v17
	v_cvt_pk_bf16_f32 v147, v18, v19
	s_nop 1
	v_permlane16_swap_b32_e32 v140, v142
	v_permlane16_swap_b32_e32 v141, v143
	global_store_dwordx4 v[168:169], v[140:143], off offset:256
	v_cvt_pk_bf16_f32 v148, v12, v13
	v_cvt_pk_bf16_f32 v149, v14, v15
	v_cvt_pk_bf16_f32 v150, v8, v9
	v_cvt_pk_bf16_f32 v151, v10, v11
	s_nop 1
	v_permlane16_swap_b32_e32 v144, v146
	v_permlane16_swap_b32_e32 v145, v147
	global_store_dwordx4 v[170:171], v[144:147], off offset:256
	v_cvt_pk_bf16_f32 v140, v4, v5
	v_cvt_pk_bf16_f32 v141, v6, v7
	v_cvt_pk_bf16_f32 v142, v0, v1
	v_cvt_pk_bf16_f32 v143, v2, v3
	s_nop 1
	v_permlane16_swap_b32_e32 v148, v150
	v_permlane16_swap_b32_e32 v149, v151
	global_store_dwordx4 v[172:173], v[148:151], off offset:256
	s_nop 1
	v_permlane16_swap_b32_e32 v140, v142
	v_permlane16_swap_b32_e32 v141, v143
	global_store_dwordx4 v[174:175], v[140:143], off offset:256
	s_branch .LBB0_958
.Lpj_silu:
	v_mul_f32_e32 v176, 0xbfb8aa3b, v126
	v_mul_f32_e32 v177, 0xbfb8aa3b, v127
	v_mul_f32_e32 v178, 0xbfb8aa3b, v128
	v_mul_f32_e32 v179, 0xbfb8aa3b, v129
	v_exp_f32_e32 v176, v176
	v_exp_f32_e32 v177, v177
	v_exp_f32_e32 v178, v178
	v_exp_f32_e32 v179, v179
	v_add_f32_e32 v176, 1.0, v176
	v_add_f32_e32 v177, 1.0, v177
	v_add_f32_e32 v178, 1.0, v178
	v_add_f32_e32 v179, 1.0, v179
	v_rcp_f32_e32 v176, v176
	v_rcp_f32_e32 v177, v177
	v_rcp_f32_e32 v178, v178
	v_rcp_f32_e32 v179, v179
	v_mul_f32_e32 v176, v126, v176
	v_mul_f32_e32 v177, v127, v177
	v_mul_f32_e32 v178, v128, v178
	v_mul_f32_e32 v179, v129, v179
	v_cvt_pk_bf16_f32 v140, v176, v177
	v_cvt_pk_bf16_f32 v141, v178, v179
	v_mul_f32_e32 v176, 0xbfb8aa3b, v122
	v_mul_f32_e32 v177, 0xbfb8aa3b, v123
	v_mul_f32_e32 v178, 0xbfb8aa3b, v124
	v_mul_f32_e32 v179, 0xbfb8aa3b, v125
	v_exp_f32_e32 v176, v176
	v_exp_f32_e32 v177, v177
	v_exp_f32_e32 v178, v178
	v_exp_f32_e32 v179, v179
	v_add_f32_e32 v176, 1.0, v176
	v_add_f32_e32 v177, 1.0, v177
	v_add_f32_e32 v178, 1.0, v178
	v_add_f32_e32 v179, 1.0, v179
	v_rcp_f32_e32 v176, v176
	v_rcp_f32_e32 v177, v177
	v_rcp_f32_e32 v178, v178
	v_rcp_f32_e32 v179, v179
	v_mul_f32_e32 v176, v122, v176
	v_mul_f32_e32 v177, v123, v177
	v_mul_f32_e32 v178, v124, v178
	v_mul_f32_e32 v179, v125, v179
	v_cvt_pk_bf16_f32 v142, v176, v177
	v_cvt_pk_bf16_f32 v143, v178, v179
	v_mul_f32_e32 v176, 0xbfb8aa3b, v118
	v_mul_f32_e32 v177, 0xbfb8aa3b, v119
	v_mul_f32_e32 v178, 0xbfb8aa3b, v120
	v_mul_f32_e32 v179, 0xbfb8aa3b, v121
	v_exp_f32_e32 v176, v176
	v_exp_f32_e32 v177, v177
	v_exp_f32_e32 v178, v178
	v_exp_f32_e32 v179, v179
	v_add_f32_e32 v176, 1.0, v176
	v_add_f32_e32 v177, 1.0, v177
	v_add_f32_e32 v178, 1.0, v178
	v_add_f32_e32 v179, 1.0, v179
	v_rcp_f32_e32 v176, v176
	v_rcp_f32_e32 v177, v177
	v_rcp_f32_e32 v178, v178
	v_rcp_f32_e32 v179, v179
	v_mul_f32_e32 v176, v118, v176
	v_mul_f32_e32 v177, v119, v177
	v_mul_f32_e32 v178, v120, v178
	v_mul_f32_e32 v179, v121, v179
	v_cvt_pk_bf16_f32 v144, v176, v177
	v_cvt_pk_bf16_f32 v145, v178, v179
	v_mul_f32_e32 v176, 0xbfb8aa3b, v114
	v_mul_f32_e32 v177, 0xbfb8aa3b, v115
	v_mul_f32_e32 v178, 0xbfb8aa3b, v116
	v_mul_f32_e32 v179, 0xbfb8aa3b, v117
	v_exp_f32_e32 v176, v176
	v_exp_f32_e32 v177, v177
	v_exp_f32_e32 v178, v178
	v_exp_f32_e32 v179, v179
	v_add_f32_e32 v176, 1.0, v176
	v_add_f32_e32 v177, 1.0, v177
	v_add_f32_e32 v178, 1.0, v178
	v_add_f32_e32 v179, 1.0, v179
	v_rcp_f32_e32 v176, v176
	v_rcp_f32_e32 v177, v177
	v_rcp_f32_e32 v178, v178
	v_rcp_f32_e32 v179, v179
	v_mul_f32_e32 v176, v114, v176
	v_mul_f32_e32 v177, v115, v177
	v_mul_f32_e32 v178, v116, v178
	v_mul_f32_e32 v179, v117, v179
	v_cvt_pk_bf16_f32 v146, v176, v177
	v_cvt_pk_bf16_f32 v147, v178, v179
	s_nop 1
	v_permlane16_swap_b32_e32 v140, v142
	v_permlane16_swap_b32_e32 v141, v143
	global_store_dwordx4 v[160:161], v[140:143], off
	v_mul_f32_e32 v176, 0xbfb8aa3b, v110
	v_mul_f32_e32 v177, 0xbfb8aa3b, v111
	v_mul_f32_e32 v178, 0xbfb8aa3b, v112
	v_mul_f32_e32 v179, 0xbfb8aa3b, v113
	v_exp_f32_e32 v176, v176
	v_exp_f32_e32 v177, v177
	v_exp_f32_e32 v178, v178
	v_exp_f32_e32 v179, v179
	v_add_f32_e32 v176, 1.0, v176
	v_add_f32_e32 v177, 1.0, v177
	v_add_f32_e32 v178, 1.0, v178
	v_add_f32_e32 v179, 1.0, v179
	v_rcp_f32_e32 v176, v176
	v_rcp_f32_e32 v177, v177
	v_rcp_f32_e32 v178, v178
	v_rcp_f32_e32 v179, v179
	v_mul_f32_e32 v176, v110, v176
	v_mul_f32_e32 v177, v111, v177
	v_mul_f32_e32 v178, v112, v178
	v_mul_f32_e32 v179, v113, v179
	v_cvt_pk_bf16_f32 v148, v176, v177
	v_cvt_pk_bf16_f32 v149, v178, v179
	v_mul_f32_e32 v176, 0xbfb8aa3b, v106
	v_mul_f32_e32 v177, 0xbfb8aa3b, v107
	v_mul_f32_e32 v178, 0xbfb8aa3b, v108
	v_mul_f32_e32 v179, 0xbfb8aa3b, v109
	v_exp_f32_e32 v176, v176
	v_exp_f32_e32 v177, v177
	v_exp_f32_e32 v178, v178
	v_exp_f32_e32 v179, v179
	v_add_f32_e32 v176, 1.0, v176
	v_add_f32_e32 v177, 1.0, v177
	v_add_f32_e32 v178, 1.0, v178
	v_add_f32_e32 v179, 1.0, v179
	v_rcp_f32_e32 v176, v176
; __device__ __forceinline__ unsigned pack2(float a, float b) { const f32x2_t v = {a, b}; const bf16x2_t r = __builtin_convertvector(v, bf16x2_t); return __builtin_bit_cast(unsigned, r); }
; __device__ __forceinline__ void ph_proj(const Params& p, int l, char* shm) {
;     ...
;           if (act == 1) xv = xv * __builtin_amdgcn_rcpf(1.f + __expf(-xv));
;           else if (act == 2) xv = 0.5f * xv * (1.f + erf_fast(xv * 0.70710678118654752f));
;           y[j] = xv;
;         }
;         *(uint2*)(p.P + (size_t)(brow + r) * NP + pn * 256 + c) = uint2{pack2(y[0], y[1]), pack2(y[2], y[3])};
	v_rcp_f32_e32 v177, v177
	v_rcp_f32_e32 v178, v178
	v_rcp_f32_e32 v179, v179
	v_mul_f32_e32 v176, v106, v176
	v_mul_f32_e32 v177, v107, v177
	v_mul_f32_e32 v178, v108, v178
	v_mul_f32_e32 v179, v109, v179
	v_cvt_pk_bf16_f32 v150, v176, v177
	v_cvt_pk_bf16_f32 v151, v178, v179
	s_nop 1
	v_permlane16_swap_b32_e32 v144, v146
	v_permlane16_swap_b32_e32 v145, v147
	global_store_dwordx4 v[162:163], v[144:147], off
	v_mul_f32_e32 v176, 0xbfb8aa3b, v102
	v_mul_f32_e32 v177, 0xbfb8aa3b, v103
	v_mul_f32_e32 v178, 0xbfb8aa3b, v104
	v_mul_f32_e32 v179, 0xbfb8aa3b, v105
	v_exp_f32_e32 v176, v176
	v_exp_f32_e32 v177, v177
	v_exp_f32_e32 v178, v178
	v_exp_f32_e32 v179, v179
	v_add_f32_e32 v176, 1.0, v176
	v_add_f32_e32 v177, 1.0, v177
	v_add_f32_e32 v178, 1.0, v178
	v_add_f32_e32 v179, 1.0, v179
	v_rcp_f32_e32 v176, v176
	v_rcp_f32_e32 v177, v177
	v_rcp_f32_e32 v178, v178
	v_rcp_f32_e32 v179, v179
	v_mul_f32_e32 v176, v102, v176
	v_mul_f32_e32 v177, v103, v177
	v_mul_f32_e32 v178, v104, v178
	v_mul_f32_e32 v179, v105, v179
	v_cvt_pk_bf16_f32 v140, v176, v177
	v_cvt_pk_bf16_f32 v141, v178, v179
	v_mul_f32_e32 v176, 0xbfb8aa3b, v98
	v_mul_f32_e32 v177, 0xbfb8aa3b, v99
	v_mul_f32_e32 v178, 0xbfb8aa3b, v100
	v_mul_f32_e32 v179, 0xbfb8aa3b, v101
	v_exp_f32_e32 v176, v176
	v_exp_f32_e32 v177, v177
	v_exp_f32_e32 v178, v178
	v_exp_f32_e32 v179, v179
	v_add_f32_e32 v176, 1.0, v176
	v_add_f32_e32 v177, 1.0, v177
	v_add_f32_e32 v178, 1.0, v178
	v_add_f32_e32 v179, 1.0, v179
	v_rcp_f32_e32 v176, v176
	v_rcp_f32_e32 v177, v177
	v_rcp_f32_e32 v178, v178
	v_rcp_f32_e32 v179, v179
	v_mul_f32_e32 v176, v98, v176
	v_mul_f32_e32 v177, v99, v177
	v_mul_f32_e32 v178, v100, v178
	v_mul_f32_e32 v179, v101, v179
	v_cvt_pk_bf16_f32 v142, v176, v177
	v_cvt_pk_bf16_f32 v143, v178, v179
	s_nop 1
	v_permlane16_swap_b32_e32 v148, v150
	v_permlane16_swap_b32_e32 v149, v151
	global_store_dwordx4 v[164:165], v[148:151], off
	v_mul_f32_e32 v176, 0xbfb8aa3b, v94
	v_mul_f32_e32 v177, 0xbfb8aa3b, v95
	v_mul_f32_e32 v178, 0xbfb8aa3b, v96
	v_mul_f32_e32 v179, 0xbfb8aa3b, v97
	v_exp_f32_e32 v176, v176
	v_exp_f32_e32 v177, v177
	v_exp_f32_e32 v178, v178
	v_exp_f32_e32 v179, v179
	v_add_f32_e32 v176, 1.0, v176
	v_add_f32_e32 v177, 1.0, v177
	v_add_f32_e32 v178, 1.0, v178
	v_add_f32_e32 v179, 1.0, v179
	v_rcp_f32_e32 v176, v176
	v_rcp_f32_e32 v177, v177
	v_rcp_f32_e32 v178, v178
	v_rcp_f32_e32 v179, v179
	v_mul_f32_e32 v176, v94, v176
	v_mul_f32_e32 v177, v95, v177
	v_mul_f32_e32 v178, v96, v178
	v_mul_f32_e32 v179, v97, v179
	v_cvt_pk_bf16_f32 v144, v176, v177
	v_cvt_pk_bf16_f32 v145, v178, v179
	v_mul_f32_e32 v176, 0xbfb8aa3b, v90
	v_mul_f32_e32 v177, 0xbfb8aa3b, v91
	v_mul_f32_e32 v178, 0xbfb8aa3b, v92
	v_mul_f32_e32 v179, 0xbfb8aa3b, v93
	v_exp_f32_e32 v176, v176
	v_exp_f32_e32 v177, v177
	v_exp_f32_e32 v178, v178
	v_exp_f32_e32 v179, v179
	v_add_f32_e32 v176, 1.0, v176
	v_add_f32_e32 v177, 1.0, v177
	v_add_f32_e32 v178, 1.0, v178
	v_add_f32_e32 v179, 1.0, v179
	v_rcp_f32_e32 v176, v176
	v_rcp_f32_e32 v177, v177
	v_rcp_f32_e32 v178, v178
	v_rcp_f32_e32 v179, v179
	v_mul_f32_e32 v176, v90, v176
	v_mul_f32_e32 v177, v91, v177
	v_mul_f32_e32 v178, v92, v178
	v_mul_f32_e32 v179, v93, v179
	v_cvt_pk_bf16_f32 v146, v176, v177
	v_cvt_pk_bf16_f32 v147, v178, v179
	s_nop 1
	v_permlane16_swap_b32_e32 v140, v142
	v_permlane16_swap_b32_e32 v141, v143
	global_store_dwordx4 v[166:167], v[140:143], off
	v_mul_f32_e32 v176, 0xbfb8aa3b, v86
	v_mul_f32_e32 v177, 0xbfb8aa3b, v87
	v_mul_f32_e32 v178, 0xbfb8aa3b, v88
	v_mul_f32_e32 v179, 0xbfb8aa3b, v89
	v_exp_f32_e32 v176, v176
	v_exp_f32_e32 v177, v177
	v_exp_f32_e32 v178, v178
	v_exp_f32_e32 v179, v179
	v_add_f32_e32 v176, 1.0, v176
	v_add_f32_e32 v177, 1.0, v177
	v_add_f32_e32 v178, 1.0, v178
	v_add_f32_e32 v179, 1.0, v179
	v_rcp_f32_e32 v176, v176
	v_rcp_f32_e32 v177, v177
	v_rcp_f32_e32 v178, v178
	v_rcp_f32_e32 v179, v179
	v_mul_f32_e32 v176, v86, v176
	v_mul_f32_e32 v177, v87, v177
	v_mul_f32_e32 v178, v88, v178
	v_mul_f32_e32 v179, v89, v179
	v_cvt_pk_bf16_f32 v148, v176, v177
	v_cvt_pk_bf16_f32 v149, v178, v179
	v_mul_f32_e32 v176, 0xbfb8aa3b, v82
	v_mul_f32_e32 v177, 0xbfb8aa3b, v83
	v_mul_f32_e32 v178, 0xbfb8aa3b, v84
	v_mul_f32_e32 v179, 0xbfb8aa3b, v85
	v_exp_f32_e32 v176, v176
	v_exp_f32_e32 v177, v177
	v_exp_f32_e32 v178, v178
	v_exp_f32_e32 v179, v179
	v_add_f32_e32 v176, 1.0, v176
	v_add_f32_e32 v177, 1.0, v177
	v_add_f32_e32 v178, 1.0, v178
	v_add_f32_e32 v179, 1.0, v179
	v_rcp_f32_e32 v176, v176
	v_rcp_f32_e32 v177, v177
	v_rcp_f32_e32 v178, v178
	v_rcp_f32_e32 v179, v179
	v_mul_f32_e32 v176, v82, v176
	v_mul_f32_e32 v177, v83, v177
	v_mul_f32_e32 v178, v84, v178
	v_mul_f32_e32 v179, v85, v179
	v_cvt_pk_bf16_f32 v150, v176, v177
	v_cvt_pk_bf16_f32 v151, v178, v179
	s_nop 1
	v_permlane16_swap_b32_e32 v144, v146
	v_permlane16_swap_b32_e32 v145, v147
	global_store_dwordx4 v[160:161], v[144:147], off offset:256
	v_mul_f32_e32 v176, 0xbfb8aa3b, v78
	v_mul_f32_e32 v177, 0xbfb8aa3b, v79
	v_mul_f32_e32 v178, 0xbfb8aa3b, v80
	v_mul_f32_e32 v179, 0xbfb8aa3b, v81
	v_exp_f32_e32 v176, v176
	v_exp_f32_e32 v177, v177
	v_exp_f32_e32 v178, v178
	v_exp_f32_e32 v179, v179
	v_add_f32_e32 v176, 1.0, v176
	v_add_f32_e32 v177, 1.0, v177
	v_add_f32_e32 v178, 1.0, v178
	v_add_f32_e32 v179, 1.0, v179
	v_rcp_f32_e32 v176, v176
	v_rcp_f32_e32 v177, v177
	v_rcp_f32_e32 v178, v178
	v_rcp_f32_e32 v179, v179
	v_mul_f32_e32 v176, v78, v176
	v_mul_f32_e32 v177, v79, v177
	v_mul_f32_e32 v178, v80, v178
	v_mul_f32_e32 v179, v81, v179
	v_cvt_pk_bf16_f32 v140, v176, v177
	v_cvt_pk_bf16_f32 v141, v178, v179
	v_mul_f32_e32 v176, 0xbfb8aa3b, v74
	v_mul_f32_e32 v177, 0xbfb8aa3b, v75
; __device__ __forceinline__ unsigned pack2(float a, float b) { const f32x2_t v = {a, b}; const bf16x2_t r = __builtin_convertvector(v, bf16x2_t); return __builtin_bit_cast(unsigned, r); }
; __device__ __forceinline__ void ph_proj(const Params& p, int l, char* shm) {
;     ...
;           if (act == 1) xv = xv * __builtin_amdgcn_rcpf(1.f + __expf(-xv));
;           else if (act == 2) xv = 0.5f * xv * (1.f + erf_fast(xv * 0.70710678118654752f));
;           y[j] = xv;
;         }
;         *(uint2*)(p.P + (size_t)(brow + r) * NP + pn * 256 + c) = uint2{pack2(y[0], y[1]), pack2(y[2], y[3])};
	v_mul_f32_e32 v178, 0xbfb8aa3b, v76
	v_mul_f32_e32 v179, 0xbfb8aa3b, v77
	v_exp_f32_e32 v176, v176
	v_exp_f32_e32 v177, v177
	v_exp_f32_e32 v178, v178
	v_exp_f32_e32 v179, v179
	v_add_f32_e32 v176, 1.0, v176
	v_add_f32_e32 v177, 1.0, v177
	v_add_f32_e32 v178, 1.0, v178
	v_add_f32_e32 v179, 1.0, v179
	v_rcp_f32_e32 v176, v176
	v_rcp_f32_e32 v177, v177
	v_rcp_f32_e32 v178, v178
	v_rcp_f32_e32 v179, v179
	v_mul_f32_e32 v176, v74, v176
	v_mul_f32_e32 v177, v75, v177
	v_mul_f32_e32 v178, v76, v178
	v_mul_f32_e32 v179, v77, v179
	v_cvt_pk_bf16_f32 v142, v176, v177
	v_cvt_pk_bf16_f32 v143, v178, v179
	s_nop 1
	v_permlane16_swap_b32_e32 v148, v150
	v_permlane16_swap_b32_e32 v149, v151
	global_store_dwordx4 v[162:163], v[148:151], off offset:256
	v_mul_f32_e32 v176, 0xbfb8aa3b, v70
	v_mul_f32_e32 v177, 0xbfb8aa3b, v71
	v_mul_f32_e32 v178, 0xbfb8aa3b, v72
	v_mul_f32_e32 v179, 0xbfb8aa3b, v73
	v_exp_f32_e32 v176, v176
	v_exp_f32_e32 v177, v177
	v_exp_f32_e32 v178, v178
	v_exp_f32_e32 v179, v179
	v_add_f32_e32 v176, 1.0, v176
	v_add_f32_e32 v177, 1.0, v177
	v_add_f32_e32 v178, 1.0, v178
	v_add_f32_e32 v179, 1.0, v179
	v_rcp_f32_e32 v176, v176
	v_rcp_f32_e32 v177, v177
	v_rcp_f32_e32 v178, v178
	v_rcp_f32_e32 v179, v179
	v_mul_f32_e32 v176, v70, v176
	v_mul_f32_e32 v177, v71, v177
	v_mul_f32_e32 v178, v72, v178
	v_mul_f32_e32 v179, v73, v179
	v_cvt_pk_bf16_f32 v144, v176, v177
	v_cvt_pk_bf16_f32 v145, v178, v179
	v_mul_f32_e32 v176, 0xbfb8aa3b, v66
	v_mul_f32_e32 v177, 0xbfb8aa3b, v67
	v_mul_f32_e32 v178, 0xbfb8aa3b, v68
	v_mul_f32_e32 v179, 0xbfb8aa3b, v69
	v_exp_f32_e32 v176, v176
	v_exp_f32_e32 v177, v177
	v_exp_f32_e32 v178, v178
	v_exp_f32_e32 v179, v179
	v_add_f32_e32 v176, 1.0, v176
	v_add_f32_e32 v177, 1.0, v177
	v_add_f32_e32 v178, 1.0, v178
	v_add_f32_e32 v179, 1.0, v179
	v_rcp_f32_e32 v176, v176
	v_rcp_f32_e32 v177, v177
	v_rcp_f32_e32 v178, v178
	v_rcp_f32_e32 v179, v179
	v_mul_f32_e32 v176, v66, v176
	v_mul_f32_e32 v177, v67, v177
	v_mul_f32_e32 v178, v68, v178
	v_mul_f32_e32 v179, v69, v179
	v_cvt_pk_bf16_f32 v146, v176, v177
	v_cvt_pk_bf16_f32 v147, v178, v179
	s_nop 1
	v_permlane16_swap_b32_e32 v140, v142
	v_permlane16_swap_b32_e32 v141, v143
	global_store_dwordx4 v[164:165], v[140:143], off offset:256
	v_mul_f32_e32 v176, 0xbfb8aa3b, v62
	v_mul_f32_e32 v177, 0xbfb8aa3b, v63
	v_mul_f32_e32 v178, 0xbfb8aa3b, v64
	v_mul_f32_e32 v179, 0xbfb8aa3b, v65
	v_exp_f32_e32 v176, v176
	v_exp_f32_e32 v177, v177
	v_exp_f32_e32 v178, v178
	v_exp_f32_e32 v179, v179
	v_add_f32_e32 v176, 1.0, v176
	v_add_f32_e32 v177, 1.0, v177
	v_add_f32_e32 v178, 1.0, v178
	v_add_f32_e32 v179, 1.0, v179
	v_rcp_f32_e32 v176, v176
	v_rcp_f32_e32 v177, v177
	v_rcp_f32_e32 v178, v178
	v_rcp_f32_e32 v179, v179
	v_mul_f32_e32 v176, v62, v176
	v_mul_f32_e32 v177, v63, v177
	v_mul_f32_e32 v178, v64, v178
	v_mul_f32_e32 v179, v65, v179
	v_cvt_pk_bf16_f32 v148, v176, v177
	v_cvt_pk_bf16_f32 v149, v178, v179
	v_mul_f32_e32 v176, 0xbfb8aa3b, v58
	v_mul_f32_e32 v177, 0xbfb8aa3b, v59
	v_mul_f32_e32 v178, 0xbfb8aa3b, v60
	v_mul_f32_e32 v179, 0xbfb8aa3b, v61
	v_exp_f32_e32 v176, v176
	v_exp_f32_e32 v177, v177
	v_exp_f32_e32 v178, v178
	v_exp_f32_e32 v179, v179
	v_add_f32_e32 v176, 1.0, v176
	v_add_f32_e32 v177, 1.0, v177
	v_add_f32_e32 v178, 1.0, v178
	v_add_f32_e32 v179, 1.0, v179
	v_rcp_f32_e32 v176, v176
	v_rcp_f32_e32 v177, v177
	v_rcp_f32_e32 v178, v178
	v_rcp_f32_e32 v179, v179
	v_mul_f32_e32 v176, v58, v176
	v_mul_f32_e32 v177, v59, v177
	v_mul_f32_e32 v178, v60, v178
	v_mul_f32_e32 v179, v61, v179
	v_cvt_pk_bf16_f32 v150, v176, v177
	v_cvt_pk_bf16_f32 v151, v178, v179
	s_nop 1
	v_permlane16_swap_b32_e32 v144, v146
	v_permlane16_swap_b32_e32 v145, v147
	global_store_dwordx4 v[166:167], v[144:147], off offset:256
	v_mul_f32_e32 v176, 0xbfb8aa3b, v54
	v_mul_f32_e32 v177, 0xbfb8aa3b, v55
	v_mul_f32_e32 v178, 0xbfb8aa3b, v56
	v_mul_f32_e32 v179, 0xbfb8aa3b, v57
	v_exp_f32_e32 v176, v176
	v_exp_f32_e32 v177, v177
	v_exp_f32_e32 v178, v178
	v_exp_f32_e32 v179, v179
	v_add_f32_e32 v176, 1.0, v176
	v_add_f32_e32 v177, 1.0, v177
	v_add_f32_e32 v178, 1.0, v178
	v_add_f32_e32 v179, 1.0, v179
	v_rcp_f32_e32 v176, v176
	v_rcp_f32_e32 v177, v177
	v_rcp_f32_e32 v178, v178
	v_rcp_f32_e32 v179, v179
	v_mul_f32_e32 v176, v54, v176
	v_mul_f32_e32 v177, v55, v177
	v_mul_f32_e32 v178, v56, v178
	v_mul_f32_e32 v179, v57, v179
	v_cvt_pk_bf16_f32 v140, v176, v177
	v_cvt_pk_bf16_f32 v141, v178, v179
	v_mul_f32_e32 v176, 0xbfb8aa3b, v50
	v_mul_f32_e32 v177, 0xbfb8aa3b, v51
	v_mul_f32_e32 v178, 0xbfb8aa3b, v52
	v_mul_f32_e32 v179, 0xbfb8aa3b, v53
	v_exp_f32_e32 v176, v176
	v_exp_f32_e32 v177, v177
	v_exp_f32_e32 v178, v178
	v_exp_f32_e32 v179, v179
	v_add_f32_e32 v176, 1.0, v176
	v_add_f32_e32 v177, 1.0, v177
	v_add_f32_e32 v178, 1.0, v178
	v_add_f32_e32 v179, 1.0, v179
	v_rcp_f32_e32 v176, v176
	v_rcp_f32_e32 v177, v177
	v_rcp_f32_e32 v178, v178
	v_rcp_f32_e32 v179, v179
	v_mul_f32_e32 v176, v50, v176
	v_mul_f32_e32 v177, v51, v177
	v_mul_f32_e32 v178, v52, v178
	v_mul_f32_e32 v179, v53, v179
	v_cvt_pk_bf16_f32 v142, v176, v177
	v_cvt_pk_bf16_f32 v143, v178, v179
	s_nop 1
	v_permlane16_swap_b32_e32 v148, v150
	v_permlane16_swap_b32_e32 v149, v151
	global_store_dwordx4 v[168:169], v[148:151], off
	v_mul_f32_e32 v176, 0xbfb8aa3b, v46
	v_mul_f32_e32 v177, 0xbfb8aa3b, v47
	v_mul_f32_e32 v178, 0xbfb8aa3b, v48
	v_mul_f32_e32 v179, 0xbfb8aa3b, v49
	v_exp_f32_e32 v176, v176
	v_exp_f32_e32 v177, v177
	v_exp_f32_e32 v178, v178
	v_exp_f32_e32 v179, v179
	v_add_f32_e32 v176, 1.0, v176
	v_add_f32_e32 v177, 1.0, v177
	v_add_f32_e32 v178, 1.0, v178
	v_add_f32_e32 v179, 1.0, v179
	v_rcp_f32_e32 v176, v176
; __device__ __forceinline__ unsigned pack2(float a, float b) { const f32x2_t v = {a, b}; const bf16x2_t r = __builtin_convertvector(v, bf16x2_t); return __builtin_bit_cast(unsigned, r); }
; __device__ __forceinline__ void ph_proj(const Params& p, int l, char* shm) {
;     ...
;           if (act == 1) xv = xv * __builtin_amdgcn_rcpf(1.f + __expf(-xv));
;           else if (act == 2) xv = 0.5f * xv * (1.f + erf_fast(xv * 0.70710678118654752f));
;           y[j] = xv;
;         }
;         *(uint2*)(p.P + (size_t)(brow + r) * NP + pn * 256 + c) = uint2{pack2(y[0], y[1]), pack2(y[2], y[3])};
	v_rcp_f32_e32 v177, v177
	v_rcp_f32_e32 v178, v178
	v_rcp_f32_e32 v179, v179
	v_mul_f32_e32 v176, v46, v176
	v_mul_f32_e32 v177, v47, v177
	v_mul_f32_e32 v178, v48, v178
	v_mul_f32_e32 v179, v49, v179
	v_cvt_pk_bf16_f32 v144, v176, v177
	v_cvt_pk_bf16_f32 v145, v178, v179
	v_mul_f32_e32 v176, 0xbfb8aa3b, v42
	v_mul_f32_e32 v177, 0xbfb8aa3b, v43
	v_mul_f32_e32 v178, 0xbfb8aa3b, v44
	v_mul_f32_e32 v179, 0xbfb8aa3b, v45
	v_exp_f32_e32 v176, v176
	v_exp_f32_e32 v177, v177
	v_exp_f32_e32 v178, v178
	v_exp_f32_e32 v179, v179
	v_add_f32_e32 v176, 1.0, v176
	v_add_f32_e32 v177, 1.0, v177
	v_add_f32_e32 v178, 1.0, v178
	v_add_f32_e32 v179, 1.0, v179
	v_rcp_f32_e32 v176, v176
	v_rcp_f32_e32 v177, v177
	v_rcp_f32_e32 v178, v178
	v_rcp_f32_e32 v179, v179
	v_mul_f32_e32 v176, v42, v176
	v_mul_f32_e32 v177, v43, v177
	v_mul_f32_e32 v178, v44, v178
	v_mul_f32_e32 v179, v45, v179
	v_cvt_pk_bf16_f32 v146, v176, v177
	v_cvt_pk_bf16_f32 v147, v178, v179
	s_nop 1
	v_permlane16_swap_b32_e32 v140, v142
	v_permlane16_swap_b32_e32 v141, v143
	global_store_dwordx4 v[170:171], v[140:143], off
	v_mul_f32_e32 v176, 0xbfb8aa3b, v38
	v_mul_f32_e32 v177, 0xbfb8aa3b, v39
	v_mul_f32_e32 v178, 0xbfb8aa3b, v40
	v_mul_f32_e32 v179, 0xbfb8aa3b, v41
	v_exp_f32_e32 v176, v176
	v_exp_f32_e32 v177, v177
	v_exp_f32_e32 v178, v178
	v_exp_f32_e32 v179, v179
	v_add_f32_e32 v176, 1.0, v176
	v_add_f32_e32 v177, 1.0, v177
	v_add_f32_e32 v178, 1.0, v178
	v_add_f32_e32 v179, 1.0, v179
	v_rcp_f32_e32 v176, v176
	v_rcp_f32_e32 v177, v177
	v_rcp_f32_e32 v178, v178
	v_rcp_f32_e32 v179, v179
	v_mul_f32_e32 v176, v38, v176
	v_mul_f32_e32 v177, v39, v177
	v_mul_f32_e32 v178, v40, v178
	v_mul_f32_e32 v179, v41, v179
	v_cvt_pk_bf16_f32 v148, v176, v177
	v_cvt_pk_bf16_f32 v149, v178, v179
	v_mul_f32_e32 v176, 0xbfb8aa3b, v34
	v_mul_f32_e32 v177, 0xbfb8aa3b, v35
	v_mul_f32_e32 v178, 0xbfb8aa3b, v36
	v_mul_f32_e32 v179, 0xbfb8aa3b, v37
	v_exp_f32_e32 v176, v176
	v_exp_f32_e32 v177, v177
	v_exp_f32_e32 v178, v178
	v_exp_f32_e32 v179, v179
	v_add_f32_e32 v176, 1.0, v176
	v_add_f32_e32 v177, 1.0, v177
	v_add_f32_e32 v178, 1.0, v178
	v_add_f32_e32 v179, 1.0, v179
	v_rcp_f32_e32 v176, v176
	v_rcp_f32_e32 v177, v177
	v_rcp_f32_e32 v178, v178
	v_rcp_f32_e32 v179, v179
	v_mul_f32_e32 v176, v34, v176
	v_mul_f32_e32 v177, v35, v177
	v_mul_f32_e32 v178, v36, v178
	v_mul_f32_e32 v179, v37, v179
	v_cvt_pk_bf16_f32 v150, v176, v177
	v_cvt_pk_bf16_f32 v151, v178, v179
	s_nop 1
	v_permlane16_swap_b32_e32 v144, v146
	v_permlane16_swap_b32_e32 v145, v147
	global_store_dwordx4 v[172:173], v[144:147], off
	v_mul_f32_e32 v176, 0xbfb8aa3b, v28
	v_mul_f32_e32 v177, 0xbfb8aa3b, v29
	v_mul_f32_e32 v178, 0xbfb8aa3b, v30
	v_mul_f32_e32 v179, 0xbfb8aa3b, v31
	v_exp_f32_e32 v176, v176
	v_exp_f32_e32 v177, v177
	v_exp_f32_e32 v178, v178
	v_exp_f32_e32 v179, v179
	v_add_f32_e32 v176, 1.0, v176
	v_add_f32_e32 v177, 1.0, v177
	v_add_f32_e32 v178, 1.0, v178
	v_add_f32_e32 v179, 1.0, v179
	v_rcp_f32_e32 v176, v176
	v_rcp_f32_e32 v177, v177
	v_rcp_f32_e32 v178, v178
	v_rcp_f32_e32 v179, v179
	v_mul_f32_e32 v176, v28, v176
	v_mul_f32_e32 v177, v29, v177
	v_mul_f32_e32 v178, v30, v178
	v_mul_f32_e32 v179, v31, v179
	v_cvt_pk_bf16_f32 v140, v176, v177
	v_cvt_pk_bf16_f32 v141, v178, v179
	v_mul_f32_e32 v176, 0xbfb8aa3b, v24
	v_mul_f32_e32 v177, 0xbfb8aa3b, v25
	v_mul_f32_e32 v178, 0xbfb8aa3b, v26
	v_mul_f32_e32 v179, 0xbfb8aa3b, v27
	v_exp_f32_e32 v176, v176
	v_exp_f32_e32 v177, v177
	v_exp_f32_e32 v178, v178
	v_exp_f32_e32 v179, v179
	v_add_f32_e32 v176, 1.0, v176
	v_add_f32_e32 v177, 1.0, v177
	v_add_f32_e32 v178, 1.0, v178
	v_add_f32_e32 v179, 1.0, v179
	v_rcp_f32_e32 v176, v176
	v_rcp_f32_e32 v177, v177
	v_rcp_f32_e32 v178, v178
	v_rcp_f32_e32 v179, v179
	v_mul_f32_e32 v176, v24, v176
	v_mul_f32_e32 v177, v25, v177
	v_mul_f32_e32 v178, v26, v178
	v_mul_f32_e32 v179, v27, v179
	v_cvt_pk_bf16_f32 v142, v176, v177
	v_cvt_pk_bf16_f32 v143, v178, v179
	s_nop 1
	v_permlane16_swap_b32_e32 v148, v150
	v_permlane16_swap_b32_e32 v149, v151
	global_store_dwordx4 v[174:175], v[148:151], off
	v_mul_f32_e32 v176, 0xbfb8aa3b, v20
	v_mul_f32_e32 v177, 0xbfb8aa3b, v21
	v_mul_f32_e32 v178, 0xbfb8aa3b, v22
	v_mul_f32_e32 v179, 0xbfb8aa3b, v23
	v_exp_f32_e32 v176, v176
	v_exp_f32_e32 v177, v177
	v_exp_f32_e32 v178, v178
	v_exp_f32_e32 v179, v179
	v_add_f32_e32 v176, 1.0, v176
	v_add_f32_e32 v177, 1.0, v177
	v_add_f32_e32 v178, 1.0, v178
	v_add_f32_e32 v179, 1.0, v179
	v_rcp_f32_e32 v176, v176
	v_rcp_f32_e32 v177, v177
	v_rcp_f32_e32 v178, v178
	v_rcp_f32_e32 v179, v179
	v_mul_f32_e32 v176, v20, v176
	v_mul_f32_e32 v177, v21, v177
	v_mul_f32_e32 v178, v22, v178
	v_mul_f32_e32 v179, v23, v179
	v_cvt_pk_bf16_f32 v144, v176, v177
	v_cvt_pk_bf16_f32 v145, v178, v179
	v_mul_f32_e32 v176, 0xbfb8aa3b, v16
	v_mul_f32_e32 v177, 0xbfb8aa3b, v17
	v_mul_f32_e32 v178, 0xbfb8aa3b, v18
	v_mul_f32_e32 v179, 0xbfb8aa3b, v19
	v_exp_f32_e32 v176, v176
	v_exp_f32_e32 v177, v177
	v_exp_f32_e32 v178, v178
	v_exp_f32_e32 v179, v179
	v_add_f32_e32 v176, 1.0, v176
	v_add_f32_e32 v177, 1.0, v177
	v_add_f32_e32 v178, 1.0, v178
	v_add_f32_e32 v179, 1.0, v179
	v_rcp_f32_e32 v176, v176
	v_rcp_f32_e32 v177, v177
	v_rcp_f32_e32 v178, v178
	v_rcp_f32_e32 v179, v179
	v_mul_f32_e32 v176, v16, v176
	v_mul_f32_e32 v177, v17, v177
	v_mul_f32_e32 v178, v18, v178
	v_mul_f32_e32 v179, v19, v179
	v_cvt_pk_bf16_f32 v146, v176, v177
	v_cvt_pk_bf16_f32 v147, v178, v179
	s_nop 1
	v_permlane16_swap_b32_e32 v140, v142
	v_permlane16_swap_b32_e32 v141, v143
	global_store_dwordx4 v[168:169], v[140:143], off offset:256
	v_mul_f32_e32 v176, 0xbfb8aa3b, v12
	v_mul_f32_e32 v177, 0xbfb8aa3b, v13
; __device__ __forceinline__ unsigned pack2(float a, float b) { const f32x2_t v = {a, b}; const bf16x2_t r = __builtin_convertvector(v, bf16x2_t); return __builtin_bit_cast(unsigned, r); }
; __device__ __forceinline__ float erf_fast(float x) {
;   const float ax = fabsf(x);
;   const float t = __builtin_amdgcn_rcpf(fmaf(0.3275911f, ax, 1.f));
;   float y = fmaf(1.061405429f, t, -1.453152027f);
;   y = fmaf(y, t, 1.421413741f);
;   y = fmaf(y, t, -0.284496736f);
;   y = fmaf(y, t, 0.254829592f);
;   y = 1.f - y * t * __expf(-ax * ax);
;   return copysignf(y, x);
; }
; __device__ __forceinline__ void ph_proj(const Params& p, int l, char* shm) {
;     ...
;           if (act == 1) xv = xv * __builtin_amdgcn_rcpf(1.f + __expf(-xv));
;           else if (act == 2) xv = 0.5f * xv * (1.f + erf_fast(xv * 0.70710678118654752f));
;           y[j] = xv;
;         }
;         *(uint2*)(p.P + (size_t)(brow + r) * NP + pn * 256 + c) = uint2{pack2(y[0], y[1]), pack2(y[2], y[3])};
	v_mul_f32_e32 v178, 0xbfb8aa3b, v14
	v_mul_f32_e32 v179, 0xbfb8aa3b, v15
	v_exp_f32_e32 v176, v176
	v_exp_f32_e32 v177, v177
	v_exp_f32_e32 v178, v178
	v_exp_f32_e32 v179, v179
	v_add_f32_e32 v176, 1.0, v176
	v_add_f32_e32 v177, 1.0, v177
	v_add_f32_e32 v178, 1.0, v178
	v_add_f32_e32 v179, 1.0, v179
	v_rcp_f32_e32 v176, v176
	v_rcp_f32_e32 v177, v177
	v_rcp_f32_e32 v178, v178
	v_rcp_f32_e32 v179, v179
	v_mul_f32_e32 v176, v12, v176
	v_mul_f32_e32 v177, v13, v177
	v_mul_f32_e32 v178, v14, v178
	v_mul_f32_e32 v179, v15, v179
	v_cvt_pk_bf16_f32 v148, v176, v177
	v_cvt_pk_bf16_f32 v149, v178, v179
	v_mul_f32_e32 v176, 0xbfb8aa3b, v8
	v_mul_f32_e32 v177, 0xbfb8aa3b, v9
	v_mul_f32_e32 v178, 0xbfb8aa3b, v10
	v_mul_f32_e32 v179, 0xbfb8aa3b, v11
	v_exp_f32_e32 v176, v176
	v_exp_f32_e32 v177, v177
	v_exp_f32_e32 v178, v178
	v_exp_f32_e32 v179, v179
	v_add_f32_e32 v176, 1.0, v176
	v_add_f32_e32 v177, 1.0, v177
	v_add_f32_e32 v178, 1.0, v178
	v_add_f32_e32 v179, 1.0, v179
	v_rcp_f32_e32 v176, v176
	v_rcp_f32_e32 v177, v177
	v_rcp_f32_e32 v178, v178
	v_rcp_f32_e32 v179, v179
	v_mul_f32_e32 v176, v8, v176
	v_mul_f32_e32 v177, v9, v177
	v_mul_f32_e32 v178, v10, v178
	v_mul_f32_e32 v179, v11, v179
	v_cvt_pk_bf16_f32 v150, v176, v177
	v_cvt_pk_bf16_f32 v151, v178, v179
	s_nop 1
	v_permlane16_swap_b32_e32 v144, v146
	v_permlane16_swap_b32_e32 v145, v147
	global_store_dwordx4 v[170:171], v[144:147], off offset:256
	v_mul_f32_e32 v176, 0xbfb8aa3b, v4
	v_mul_f32_e32 v177, 0xbfb8aa3b, v5
	v_mul_f32_e32 v178, 0xbfb8aa3b, v6
	v_mul_f32_e32 v179, 0xbfb8aa3b, v7
	v_exp_f32_e32 v176, v176
	v_exp_f32_e32 v177, v177
	v_exp_f32_e32 v178, v178
	v_exp_f32_e32 v179, v179
	v_add_f32_e32 v176, 1.0, v176
	v_add_f32_e32 v177, 1.0, v177
	v_add_f32_e32 v178, 1.0, v178
	v_add_f32_e32 v179, 1.0, v179
	v_rcp_f32_e32 v176, v176
	v_rcp_f32_e32 v177, v177
	v_rcp_f32_e32 v178, v178
	v_rcp_f32_e32 v179, v179
	v_mul_f32_e32 v176, v4, v176
	v_mul_f32_e32 v177, v5, v177
	v_mul_f32_e32 v178, v6, v178
	v_mul_f32_e32 v179, v7, v179
	v_cvt_pk_bf16_f32 v140, v176, v177
	v_cvt_pk_bf16_f32 v141, v178, v179
	v_mul_f32_e32 v176, 0xbfb8aa3b, v0
	v_mul_f32_e32 v177, 0xbfb8aa3b, v1
	v_mul_f32_e32 v178, 0xbfb8aa3b, v2
	v_mul_f32_e32 v179, 0xbfb8aa3b, v3
	v_exp_f32_e32 v176, v176
	v_exp_f32_e32 v177, v177
	v_exp_f32_e32 v178, v178
	v_exp_f32_e32 v179, v179
	v_add_f32_e32 v176, 1.0, v176
	v_add_f32_e32 v177, 1.0, v177
	v_add_f32_e32 v178, 1.0, v178
	v_add_f32_e32 v179, 1.0, v179
	v_rcp_f32_e32 v176, v176
	v_rcp_f32_e32 v177, v177
	v_rcp_f32_e32 v178, v178
	v_rcp_f32_e32 v179, v179
	v_mul_f32_e32 v176, v0, v176
	v_mul_f32_e32 v177, v1, v177
	v_mul_f32_e32 v178, v2, v178
	v_mul_f32_e32 v179, v3, v179
	v_cvt_pk_bf16_f32 v142, v176, v177
	v_cvt_pk_bf16_f32 v143, v178, v179
	s_nop 1
	v_permlane16_swap_b32_e32 v148, v150
	v_permlane16_swap_b32_e32 v149, v151
	global_store_dwordx4 v[172:173], v[148:151], off offset:256
	s_nop 1
	v_permlane16_swap_b32_e32 v140, v142
	v_permlane16_swap_b32_e32 v141, v143
	global_store_dwordx4 v[174:175], v[140:143], off offset:256
	s_branch .LBB0_958
.Lpj_gelu:
	s_mov_b32 s9, 0x3ea7ba05
	s_brev_b32 s10, -2
	v_mul_f32_e32 v176, 0x3f3504f3, v126
	v_mul_f32_e32 v177, 0x3f3504f3, v127
	v_mul_f32_e32 v178, 0x3f3504f3, v128
	v_mul_f32_e32 v179, 0x3f3504f3, v129
	v_fma_f32 v180, |v176|, s9, 1.0
	v_fma_f32 v181, |v177|, s9, 1.0
	v_fma_f32 v182, |v178|, s9, 1.0
	v_fma_f32 v183, |v179|, s9, 1.0
	v_rcp_f32_e32 v180, v180
	v_rcp_f32_e32 v181, v181
	v_rcp_f32_e32 v182, v182
	v_rcp_f32_e32 v183, v183
	v_mul_f32_e32 v188, 0.5, v126
	v_mul_f32_e32 v189, 0.5, v127
	v_mul_f32_e32 v190, 0.5, v128
	v_mul_f32_e32 v191, 0.5, v129
	v_fmamk_f32 v184, v180, 0x3f87dc22, v206
	v_fmamk_f32 v185, v181, 0x3f87dc22, v206
	v_fmamk_f32 v186, v182, 0x3f87dc22, v206
	v_fmamk_f32 v187, v183, 0x3f87dc22, v206
	v_fmaak_f32 v184, v184, v180, 0x3fb5f0e3
	v_fmaak_f32 v185, v185, v181, 0x3fb5f0e3
	v_fmaak_f32 v186, v186, v182, 0x3fb5f0e3
	v_fmaak_f32 v187, v187, v183, 0x3fb5f0e3
	v_fmaak_f32 v184, v184, v180, 0xbe91a98e
	v_fmaak_f32 v185, v185, v181, 0xbe91a98e
	v_fmaak_f32 v186, v186, v182, 0xbe91a98e
	v_fmaak_f32 v187, v187, v183, 0xbe91a98e
	v_fmaak_f32 v184, v184, v180, 0x3e827906
	v_fmaak_f32 v185, v185, v181, 0x3e827906
	v_fmaak_f32 v186, v186, v182, 0x3e827906
	v_fmaak_f32 v187, v187, v183, 0x3e827906
	v_mul_f32_e32 v180, v180, v184
	v_mul_f32_e32 v181, v181, v185
	v_mul_f32_e32 v182, v182, v186
	v_mul_f32_e32 v183, v183, v187
	v_mul_f32_e64 v184, |v176|, |v176|
	v_mul_f32_e64 v185, |v177|, |v177|
	v_mul_f32_e64 v186, |v178|, |v178|
	v_mul_f32_e64 v187, |v179|, |v179|
	v_mul_f32_e32 v184, 0xbfb8aa3b, v184
	v_mul_f32_e32 v185, 0xbfb8aa3b, v185
	v_mul_f32_e32 v186, 0xbfb8aa3b, v186
	v_mul_f32_e32 v187, 0xbfb8aa3b, v187
	v_exp_f32_e32 v184, v184
	v_exp_f32_e32 v185, v185
	v_exp_f32_e32 v186, v186
	v_exp_f32_e32 v187, v187
	v_fma_f32 v180, -v184, v180, 1.0
	v_fma_f32 v181, -v185, v181, 1.0
	v_fma_f32 v182, -v186, v182, 1.0
	v_fma_f32 v183, -v187, v183, 1.0
	v_bfi_b32 v176, s10, v180, v176
	v_bfi_b32 v177, s10, v181, v177
	v_bfi_b32 v178, s10, v182, v178
	v_bfi_b32 v179, s10, v183, v179
	v_add_f32_e32 v176, 1.0, v176
	v_add_f32_e32 v177, 1.0, v177
	v_add_f32_e32 v178, 1.0, v178
	v_add_f32_e32 v179, 1.0, v179
	v_mul_f32_e32 v188, v188, v176
	v_mul_f32_e32 v189, v189, v177
	v_mul_f32_e32 v190, v190, v178
	v_mul_f32_e32 v191, v191, v179
	v_cvt_pk_bf16_f32 v140, v188, v189
	v_cvt_pk_bf16_f32 v141, v190, v191
	v_mul_f32_e32 v176, 0x3f3504f3, v122
	v_mul_f32_e32 v177, 0x3f3504f3, v123
	v_mul_f32_e32 v178, 0x3f3504f3, v124
	v_mul_f32_e32 v179, 0x3f3504f3, v125
	v_fma_f32 v180, |v176|, s9, 1.0
	v_fma_f32 v181, |v177|, s9, 1.0
; __device__ __forceinline__ unsigned pack2(float a, float b) { const f32x2_t v = {a, b}; const bf16x2_t r = __builtin_convertvector(v, bf16x2_t); return __builtin_bit_cast(unsigned, r); }
; __device__ __forceinline__ float erf_fast(float x) {
;   const float ax = fabsf(x);
;   const float t = __builtin_amdgcn_rcpf(fmaf(0.3275911f, ax, 1.f));
;   float y = fmaf(1.061405429f, t, -1.453152027f);
;   y = fmaf(y, t, 1.421413741f);
;   y = fmaf(y, t, -0.284496736f);
;   y = fmaf(y, t, 0.254829592f);
;   y = 1.f - y * t * __expf(-ax * ax);
;   return copysignf(y, x);
; }
; __device__ __forceinline__ void ph_proj(const Params& p, int l, char* shm) {
;     ...
;           else if (act == 2) xv = 0.5f * xv * (1.f + erf_fast(xv * 0.70710678118654752f));
;           y[j] = xv;
;         }
;         *(uint2*)(p.P + (size_t)(brow + r) * NP + pn * 256 + c) = uint2{pack2(y[0], y[1]), pack2(y[2], y[3])};
	v_fma_f32 v182, |v178|, s9, 1.0
	v_fma_f32 v183, |v179|, s9, 1.0
	v_rcp_f32_e32 v180, v180
	v_rcp_f32_e32 v181, v181
	v_rcp_f32_e32 v182, v182
	v_rcp_f32_e32 v183, v183
	v_mul_f32_e32 v188, 0.5, v122
	v_mul_f32_e32 v189, 0.5, v123
	v_mul_f32_e32 v190, 0.5, v124
	v_mul_f32_e32 v191, 0.5, v125
	v_fmamk_f32 v184, v180, 0x3f87dc22, v206
	v_fmamk_f32 v185, v181, 0x3f87dc22, v206
	v_fmamk_f32 v186, v182, 0x3f87dc22, v206
	v_fmamk_f32 v187, v183, 0x3f87dc22, v206
	v_fmaak_f32 v184, v184, v180, 0x3fb5f0e3
	v_fmaak_f32 v185, v185, v181, 0x3fb5f0e3
	v_fmaak_f32 v186, v186, v182, 0x3fb5f0e3
	v_fmaak_f32 v187, v187, v183, 0x3fb5f0e3
	v_fmaak_f32 v184, v184, v180, 0xbe91a98e
	v_fmaak_f32 v185, v185, v181, 0xbe91a98e
	v_fmaak_f32 v186, v186, v182, 0xbe91a98e
	v_fmaak_f32 v187, v187, v183, 0xbe91a98e
	v_fmaak_f32 v184, v184, v180, 0x3e827906
	v_fmaak_f32 v185, v185, v181, 0x3e827906
	v_fmaak_f32 v186, v186, v182, 0x3e827906
	v_fmaak_f32 v187, v187, v183, 0x3e827906
	v_mul_f32_e32 v180, v180, v184
	v_mul_f32_e32 v181, v181, v185
	v_mul_f32_e32 v182, v182, v186
	v_mul_f32_e32 v183, v183, v187
	v_mul_f32_e64 v184, |v176|, |v176|
	v_mul_f32_e64 v185, |v177|, |v177|
	v_mul_f32_e64 v186, |v178|, |v178|
	v_mul_f32_e64 v187, |v179|, |v179|
	v_mul_f32_e32 v184, 0xbfb8aa3b, v184
	v_mul_f32_e32 v185, 0xbfb8aa3b, v185
	v_mul_f32_e32 v186, 0xbfb8aa3b, v186
	v_mul_f32_e32 v187, 0xbfb8aa3b, v187
	v_exp_f32_e32 v184, v184
	v_exp_f32_e32 v185, v185
	v_exp_f32_e32 v186, v186
	v_exp_f32_e32 v187, v187
	v_fma_f32 v180, -v184, v180, 1.0
	v_fma_f32 v181, -v185, v181, 1.0
	v_fma_f32 v182, -v186, v182, 1.0
	v_fma_f32 v183, -v187, v183, 1.0
	v_bfi_b32 v176, s10, v180, v176
	v_bfi_b32 v177, s10, v181, v177
	v_bfi_b32 v178, s10, v182, v178
	v_bfi_b32 v179, s10, v183, v179
	v_add_f32_e32 v176, 1.0, v176
	v_add_f32_e32 v177, 1.0, v177
	v_add_f32_e32 v178, 1.0, v178
	v_add_f32_e32 v179, 1.0, v179
	v_mul_f32_e32 v188, v188, v176
	v_mul_f32_e32 v189, v189, v177
	v_mul_f32_e32 v190, v190, v178
	v_mul_f32_e32 v191, v191, v179
	v_cvt_pk_bf16_f32 v142, v188, v189
	v_cvt_pk_bf16_f32 v143, v190, v191
	v_mul_f32_e32 v176, 0x3f3504f3, v118
	v_mul_f32_e32 v177, 0x3f3504f3, v119
	v_mul_f32_e32 v178, 0x3f3504f3, v120
	v_mul_f32_e32 v179, 0x3f3504f3, v121
	v_fma_f32 v180, |v176|, s9, 1.0
	v_fma_f32 v181, |v177|, s9, 1.0
	v_fma_f32 v182, |v178|, s9, 1.0
	v_fma_f32 v183, |v179|, s9, 1.0
	v_rcp_f32_e32 v180, v180
	v_rcp_f32_e32 v181, v181
	v_rcp_f32_e32 v182, v182
	v_rcp_f32_e32 v183, v183
	v_mul_f32_e32 v188, 0.5, v118
	v_mul_f32_e32 v189, 0.5, v119
	v_mul_f32_e32 v190, 0.5, v120
	v_mul_f32_e32 v191, 0.5, v121
	v_fmamk_f32 v184, v180, 0x3f87dc22, v206
	v_fmamk_f32 v185, v181, 0x3f87dc22, v206
	v_fmamk_f32 v186, v182, 0x3f87dc22, v206
	v_fmamk_f32 v187, v183, 0x3f87dc22, v206
	v_fmaak_f32 v184, v184, v180, 0x3fb5f0e3
	v_fmaak_f32 v185, v185, v181, 0x3fb5f0e3
	v_fmaak_f32 v186, v186, v182, 0x3fb5f0e3
	v_fmaak_f32 v187, v187, v183, 0x3fb5f0e3
	v_fmaak_f32 v184, v184, v180, 0xbe91a98e
	v_fmaak_f32 v185, v185, v181, 0xbe91a98e
	v_fmaak_f32 v186, v186, v182, 0xbe91a98e
	v_fmaak_f32 v187, v187, v183, 0xbe91a98e
	v_fmaak_f32 v184, v184, v180, 0x3e827906
	v_fmaak_f32 v185, v185, v181, 0x3e827906
	v_fmaak_f32 v186, v186, v182, 0x3e827906
	v_fmaak_f32 v187, v187, v183, 0x3e827906
	v_mul_f32_e32 v180, v180, v184
	v_mul_f32_e32 v181, v181, v185
	v_mul_f32_e32 v182, v182, v186
	v_mul_f32_e32 v183, v183, v187
	v_mul_f32_e64 v184, |v176|, |v176|
	v_mul_f32_e64 v185, |v177|, |v177|
	v_mul_f32_e64 v186, |v178|, |v178|
	v_mul_f32_e64 v187, |v179|, |v179|
	v_mul_f32_e32 v184, 0xbfb8aa3b, v184
	v_mul_f32_e32 v185, 0xbfb8aa3b, v185
	v_mul_f32_e32 v186, 0xbfb8aa3b, v186
	v_mul_f32_e32 v187, 0xbfb8aa3b, v187
	v_exp_f32_e32 v184, v184
	v_exp_f32_e32 v185, v185
	v_exp_f32_e32 v186, v186
	v_exp_f32_e32 v187, v187
	v_fma_f32 v180, -v184, v180, 1.0
	v_fma_f32 v181, -v185, v181, 1.0
	v_fma_f32 v182, -v186, v182, 1.0
	v_fma_f32 v183, -v187, v183, 1.0
	v_bfi_b32 v176, s10, v180, v176
	v_bfi_b32 v177, s10, v181, v177
	v_bfi_b32 v178, s10, v182, v178
	v_bfi_b32 v179, s10, v183, v179
	v_add_f32_e32 v176, 1.0, v176
	v_add_f32_e32 v177, 1.0, v177
	v_add_f32_e32 v178, 1.0, v178
	v_add_f32_e32 v179, 1.0, v179
	v_mul_f32_e32 v188, v188, v176
	v_mul_f32_e32 v189, v189, v177
	v_mul_f32_e32 v190, v190, v178
	v_mul_f32_e32 v191, v191, v179
	v_cvt_pk_bf16_f32 v144, v188, v189
	v_cvt_pk_bf16_f32 v145, v190, v191
	v_mul_f32_e32 v176, 0x3f3504f3, v114
	v_mul_f32_e32 v177, 0x3f3504f3, v115
	v_mul_f32_e32 v178, 0x3f3504f3, v116
	v_mul_f32_e32 v179, 0x3f3504f3, v117
	v_fma_f32 v180, |v176|, s9, 1.0
	v_fma_f32 v181, |v177|, s9, 1.0
	v_fma_f32 v182, |v178|, s9, 1.0
	v_fma_f32 v183, |v179|, s9, 1.0
	v_rcp_f32_e32 v180, v180
	v_rcp_f32_e32 v181, v181
	v_rcp_f32_e32 v182, v182
	v_rcp_f32_e32 v183, v183
	v_mul_f32_e32 v188, 0.5, v114
	v_mul_f32_e32 v189, 0.5, v115
	v_mul_f32_e32 v190, 0.5, v116
	v_mul_f32_e32 v191, 0.5, v117
	v_fmamk_f32 v184, v180, 0x3f87dc22, v206
	v_fmamk_f32 v185, v181, 0x3f87dc22, v206
	v_fmamk_f32 v186, v182, 0x3f87dc22, v206
	v_fmamk_f32 v187, v183, 0x3f87dc22, v206
	v_fmaak_f32 v184, v184, v180, 0x3fb5f0e3
	v_fmaak_f32 v185, v185, v181, 0x3fb5f0e3
	v_fmaak_f32 v186, v186, v182, 0x3fb5f0e3
	v_fmaak_f32 v187, v187, v183, 0x3fb5f0e3
	v_fmaak_f32 v184, v184, v180, 0xbe91a98e
	v_fmaak_f32 v185, v185, v181, 0xbe91a98e
	v_fmaak_f32 v186, v186, v182, 0xbe91a98e
	v_fmaak_f32 v187, v187, v183, 0xbe91a98e
	v_fmaak_f32 v184, v184, v180, 0x3e827906
	v_fmaak_f32 v185, v185, v181, 0x3e827906
	v_fmaak_f32 v186, v186, v182, 0x3e827906
	v_fmaak_f32 v187, v187, v183, 0x3e827906
	v_mul_f32_e32 v180, v180, v184
	v_mul_f32_e32 v181, v181, v185
; __device__ __forceinline__ unsigned pack2(float a, float b) { const f32x2_t v = {a, b}; const bf16x2_t r = __builtin_convertvector(v, bf16x2_t); return __builtin_bit_cast(unsigned, r); }
; __device__ __forceinline__ float erf_fast(float x) {
;   const float ax = fabsf(x);
;   const float t = __builtin_amdgcn_rcpf(fmaf(0.3275911f, ax, 1.f));
;   float y = fmaf(1.061405429f, t, -1.453152027f);
;   y = fmaf(y, t, 1.421413741f);
;   y = fmaf(y, t, -0.284496736f);
;   y = fmaf(y, t, 0.254829592f);
;   y = 1.f - y * t * __expf(-ax * ax);
;   return copysignf(y, x);
; }
; __device__ __forceinline__ void ph_proj(const Params& p, int l, char* shm) {
;     ...
;           else if (act == 2) xv = 0.5f * xv * (1.f + erf_fast(xv * 0.70710678118654752f));
;           y[j] = xv;
;         }
;         *(uint2*)(p.P + (size_t)(brow + r) * NP + pn * 256 + c) = uint2{pack2(y[0], y[1]), pack2(y[2], y[3])};
	v_mul_f32_e32 v182, v182, v186
	v_mul_f32_e32 v183, v183, v187
	v_mul_f32_e64 v184, |v176|, |v176|
	v_mul_f32_e64 v185, |v177|, |v177|
	v_mul_f32_e64 v186, |v178|, |v178|
	v_mul_f32_e64 v187, |v179|, |v179|
	v_mul_f32_e32 v184, 0xbfb8aa3b, v184
	v_mul_f32_e32 v185, 0xbfb8aa3b, v185
	v_mul_f32_e32 v186, 0xbfb8aa3b, v186
	v_mul_f32_e32 v187, 0xbfb8aa3b, v187
	v_exp_f32_e32 v184, v184
	v_exp_f32_e32 v185, v185
	v_exp_f32_e32 v186, v186
	v_exp_f32_e32 v187, v187
	v_fma_f32 v180, -v184, v180, 1.0
	v_fma_f32 v181, -v185, v181, 1.0
	v_fma_f32 v182, -v186, v182, 1.0
	v_fma_f32 v183, -v187, v183, 1.0
	v_bfi_b32 v176, s10, v180, v176
	v_bfi_b32 v177, s10, v181, v177
	v_bfi_b32 v178, s10, v182, v178
	v_bfi_b32 v179, s10, v183, v179
	v_add_f32_e32 v176, 1.0, v176
	v_add_f32_e32 v177, 1.0, v177
	v_add_f32_e32 v178, 1.0, v178
	v_add_f32_e32 v179, 1.0, v179
	v_mul_f32_e32 v188, v188, v176
	v_mul_f32_e32 v189, v189, v177
	v_mul_f32_e32 v190, v190, v178
	v_mul_f32_e32 v191, v191, v179
	v_cvt_pk_bf16_f32 v146, v188, v189
	v_cvt_pk_bf16_f32 v147, v190, v191
	s_nop 1
	v_permlane16_swap_b32_e32 v140, v142
	v_permlane16_swap_b32_e32 v141, v143
	global_store_dwordx4 v[160:161], v[140:143], off
	v_mul_f32_e32 v176, 0x3f3504f3, v110
	v_mul_f32_e32 v177, 0x3f3504f3, v111
	v_mul_f32_e32 v178, 0x3f3504f3, v112
	v_mul_f32_e32 v179, 0x3f3504f3, v113
	v_fma_f32 v180, |v176|, s9, 1.0
	v_fma_f32 v181, |v177|, s9, 1.0
	v_fma_f32 v182, |v178|, s9, 1.0
	v_fma_f32 v183, |v179|, s9, 1.0
	v_rcp_f32_e32 v180, v180
	v_rcp_f32_e32 v181, v181
	v_rcp_f32_e32 v182, v182
	v_rcp_f32_e32 v183, v183
	v_mul_f32_e32 v188, 0.5, v110
	v_mul_f32_e32 v189, 0.5, v111
	v_mul_f32_e32 v190, 0.5, v112
	v_mul_f32_e32 v191, 0.5, v113
	v_fmamk_f32 v184, v180, 0x3f87dc22, v206
	v_fmamk_f32 v185, v181, 0x3f87dc22, v206
	v_fmamk_f32 v186, v182, 0x3f87dc22, v206
	v_fmamk_f32 v187, v183, 0x3f87dc22, v206
	v_fmaak_f32 v184, v184, v180, 0x3fb5f0e3
	v_fmaak_f32 v185, v185, v181, 0x3fb5f0e3
	v_fmaak_f32 v186, v186, v182, 0x3fb5f0e3
	v_fmaak_f32 v187, v187, v183, 0x3fb5f0e3
	v_fmaak_f32 v184, v184, v180, 0xbe91a98e
	v_fmaak_f32 v185, v185, v181, 0xbe91a98e
	v_fmaak_f32 v186, v186, v182, 0xbe91a98e
	v_fmaak_f32 v187, v187, v183, 0xbe91a98e
	v_fmaak_f32 v184, v184, v180, 0x3e827906
	v_fmaak_f32 v185, v185, v181, 0x3e827906
	v_fmaak_f32 v186, v186, v182, 0x3e827906
	v_fmaak_f32 v187, v187, v183, 0x3e827906
	v_mul_f32_e32 v180, v180, v184
	v_mul_f32_e32 v181, v181, v185
	v_mul_f32_e32 v182, v182, v186
	v_mul_f32_e32 v183, v183, v187
	v_mul_f32_e64 v184, |v176|, |v176|
	v_mul_f32_e64 v185, |v177|, |v177|
	v_mul_f32_e64 v186, |v178|, |v178|
	v_mul_f32_e64 v187, |v179|, |v179|
	v_mul_f32_e32 v184, 0xbfb8aa3b, v184
	v_mul_f32_e32 v185, 0xbfb8aa3b, v185
	v_mul_f32_e32 v186, 0xbfb8aa3b, v186
	v_mul_f32_e32 v187, 0xbfb8aa3b, v187
	v_exp_f32_e32 v184, v184
	v_exp_f32_e32 v185, v185
	v_exp_f32_e32 v186, v186
	v_exp_f32_e32 v187, v187
	v_fma_f32 v180, -v184, v180, 1.0
	v_fma_f32 v181, -v185, v181, 1.0
	v_fma_f32 v182, -v186, v182, 1.0
	v_fma_f32 v183, -v187, v183, 1.0
	v_bfi_b32 v176, s10, v180, v176
	v_bfi_b32 v177, s10, v181, v177
	v_bfi_b32 v178, s10, v182, v178
	v_bfi_b32 v179, s10, v183, v179
	v_add_f32_e32 v176, 1.0, v176
	v_add_f32_e32 v177, 1.0, v177
	v_add_f32_e32 v178, 1.0, v178
	v_add_f32_e32 v179, 1.0, v179
	v_mul_f32_e32 v188, v188, v176
	v_mul_f32_e32 v189, v189, v177
	v_mul_f32_e32 v190, v190, v178
	v_mul_f32_e32 v191, v191, v179
	v_cvt_pk_bf16_f32 v148, v188, v189
	v_cvt_pk_bf16_f32 v149, v190, v191
	v_mul_f32_e32 v176, 0x3f3504f3, v106
	v_mul_f32_e32 v177, 0x3f3504f3, v107
	v_mul_f32_e32 v178, 0x3f3504f3, v108
	v_mul_f32_e32 v179, 0x3f3504f3, v109
	v_fma_f32 v180, |v176|, s9, 1.0
	v_fma_f32 v181, |v177|, s9, 1.0
	v_fma_f32 v182, |v178|, s9, 1.0
	v_fma_f32 v183, |v179|, s9, 1.0
	v_rcp_f32_e32 v180, v180
	v_rcp_f32_e32 v181, v181
	v_rcp_f32_e32 v182, v182
	v_rcp_f32_e32 v183, v183
	v_mul_f32_e32 v188, 0.5, v106
	v_mul_f32_e32 v189, 0.5, v107
	v_mul_f32_e32 v190, 0.5, v108
	v_mul_f32_e32 v191, 0.5, v109
	v_fmamk_f32 v184, v180, 0x3f87dc22, v206
	v_fmamk_f32 v185, v181, 0x3f87dc22, v206
	v_fmamk_f32 v186, v182, 0x3f87dc22, v206
	v_fmamk_f32 v187, v183, 0x3f87dc22, v206
	v_fmaak_f32 v184, v184, v180, 0x3fb5f0e3
	v_fmaak_f32 v185, v185, v181, 0x3fb5f0e3
	v_fmaak_f32 v186, v186, v182, 0x3fb5f0e3
	v_fmaak_f32 v187, v187, v183, 0x3fb5f0e3
	v_fmaak_f32 v184, v184, v180, 0xbe91a98e
	v_fmaak_f32 v185, v185, v181, 0xbe91a98e
	v_fmaak_f32 v186, v186, v182, 0xbe91a98e
	v_fmaak_f32 v187, v187, v183, 0xbe91a98e
	v_fmaak_f32 v184, v184, v180, 0x3e827906
	v_fmaak_f32 v185, v185, v181, 0x3e827906
	v_fmaak_f32 v186, v186, v182, 0x3e827906
	v_fmaak_f32 v187, v187, v183, 0x3e827906
	v_mul_f32_e32 v180, v180, v184
	v_mul_f32_e32 v181, v181, v185
	v_mul_f32_e32 v182, v182, v186
	v_mul_f32_e32 v183, v183, v187
	v_mul_f32_e64 v184, |v176|, |v176|
	v_mul_f32_e64 v185, |v177|, |v177|
	v_mul_f32_e64 v186, |v178|, |v178|
	v_mul_f32_e64 v187, |v179|, |v179|
	v_mul_f32_e32 v184, 0xbfb8aa3b, v184
	v_mul_f32_e32 v185, 0xbfb8aa3b, v185
	v_mul_f32_e32 v186, 0xbfb8aa3b, v186
	v_mul_f32_e32 v187, 0xbfb8aa3b, v187
	v_exp_f32_e32 v184, v184
	v_exp_f32_e32 v185, v185
	v_exp_f32_e32 v186, v186
	v_exp_f32_e32 v187, v187
	v_fma_f32 v180, -v184, v180, 1.0
	v_fma_f32 v181, -v185, v181, 1.0
	v_fma_f32 v182, -v186, v182, 1.0
	v_fma_f32 v183, -v187, v183, 1.0
	v_bfi_b32 v176, s10, v180, v176
	v_bfi_b32 v177, s10, v181, v177
	v_bfi_b32 v178, s10, v182, v178
	v_bfi_b32 v179, s10, v183, v179
	v_add_f32_e32 v176, 1.0, v176
	v_add_f32_e32 v177, 1.0, v177
	v_add_f32_e32 v178, 1.0, v178
	v_add_f32_e32 v179, 1.0, v179
	v_mul_f32_e32 v188, v188, v176
; __device__ __forceinline__ unsigned pack2(float a, float b) { const f32x2_t v = {a, b}; const bf16x2_t r = __builtin_convertvector(v, bf16x2_t); return __builtin_bit_cast(unsigned, r); }
; __device__ __forceinline__ float erf_fast(float x) {
;   const float ax = fabsf(x);
;   const float t = __builtin_amdgcn_rcpf(fmaf(0.3275911f, ax, 1.f));
;   float y = fmaf(1.061405429f, t, -1.453152027f);
;   y = fmaf(y, t, 1.421413741f);
;   y = fmaf(y, t, -0.284496736f);
;   y = fmaf(y, t, 0.254829592f);
;   y = 1.f - y * t * __expf(-ax * ax);
;   return copysignf(y, x);
; }
; __device__ __forceinline__ void ph_proj(const Params& p, int l, char* shm) {
;     ...
;           else if (act == 2) xv = 0.5f * xv * (1.f + erf_fast(xv * 0.70710678118654752f));
;           y[j] = xv;
;         }
;         *(uint2*)(p.P + (size_t)(brow + r) * NP + pn * 256 + c) = uint2{pack2(y[0], y[1]), pack2(y[2], y[3])};
	v_mul_f32_e32 v189, v189, v177
	v_mul_f32_e32 v190, v190, v178
	v_mul_f32_e32 v191, v191, v179
	v_cvt_pk_bf16_f32 v150, v188, v189
	v_cvt_pk_bf16_f32 v151, v190, v191
	s_nop 1
	v_permlane16_swap_b32_e32 v144, v146
	v_permlane16_swap_b32_e32 v145, v147
	global_store_dwordx4 v[162:163], v[144:147], off
	v_mul_f32_e32 v176, 0x3f3504f3, v102
	v_mul_f32_e32 v177, 0x3f3504f3, v103
	v_mul_f32_e32 v178, 0x3f3504f3, v104
	v_mul_f32_e32 v179, 0x3f3504f3, v105
	v_fma_f32 v180, |v176|, s9, 1.0
	v_fma_f32 v181, |v177|, s9, 1.0
	v_fma_f32 v182, |v178|, s9, 1.0
	v_fma_f32 v183, |v179|, s9, 1.0
	v_rcp_f32_e32 v180, v180
	v_rcp_f32_e32 v181, v181
	v_rcp_f32_e32 v182, v182
	v_rcp_f32_e32 v183, v183
	v_mul_f32_e32 v188, 0.5, v102
	v_mul_f32_e32 v189, 0.5, v103
	v_mul_f32_e32 v190, 0.5, v104
	v_mul_f32_e32 v191, 0.5, v105
	v_fmamk_f32 v184, v180, 0x3f87dc22, v206
	v_fmamk_f32 v185, v181, 0x3f87dc22, v206
	v_fmamk_f32 v186, v182, 0x3f87dc22, v206
	v_fmamk_f32 v187, v183, 0x3f87dc22, v206
	v_fmaak_f32 v184, v184, v180, 0x3fb5f0e3
	v_fmaak_f32 v185, v185, v181, 0x3fb5f0e3
	v_fmaak_f32 v186, v186, v182, 0x3fb5f0e3
	v_fmaak_f32 v187, v187, v183, 0x3fb5f0e3
	v_fmaak_f32 v184, v184, v180, 0xbe91a98e
	v_fmaak_f32 v185, v185, v181, 0xbe91a98e
	v_fmaak_f32 v186, v186, v182, 0xbe91a98e
	v_fmaak_f32 v187, v187, v183, 0xbe91a98e
	v_fmaak_f32 v184, v184, v180, 0x3e827906
	v_fmaak_f32 v185, v185, v181, 0x3e827906
	v_fmaak_f32 v186, v186, v182, 0x3e827906
	v_fmaak_f32 v187, v187, v183, 0x3e827906
	v_mul_f32_e32 v180, v180, v184
	v_mul_f32_e32 v181, v181, v185
	v_mul_f32_e32 v182, v182, v186
	v_mul_f32_e32 v183, v183, v187
	v_mul_f32_e64 v184, |v176|, |v176|
	v_mul_f32_e64 v185, |v177|, |v177|
	v_mul_f32_e64 v186, |v178|, |v178|
	v_mul_f32_e64 v187, |v179|, |v179|
	v_mul_f32_e32 v184, 0xbfb8aa3b, v184
	v_mul_f32_e32 v185, 0xbfb8aa3b, v185
	v_mul_f32_e32 v186, 0xbfb8aa3b, v186
	v_mul_f32_e32 v187, 0xbfb8aa3b, v187
	v_exp_f32_e32 v184, v184
	v_exp_f32_e32 v185, v185
	v_exp_f32_e32 v186, v186
	v_exp_f32_e32 v187, v187
	v_fma_f32 v180, -v184, v180, 1.0
	v_fma_f32 v181, -v185, v181, 1.0
	v_fma_f32 v182, -v186, v182, 1.0
	v_fma_f32 v183, -v187, v183, 1.0
	v_bfi_b32 v176, s10, v180, v176
	v_bfi_b32 v177, s10, v181, v177
	v_bfi_b32 v178, s10, v182, v178
	v_bfi_b32 v179, s10, v183, v179
	v_add_f32_e32 v176, 1.0, v176
	v_add_f32_e32 v177, 1.0, v177
	v_add_f32_e32 v178, 1.0, v178
	v_add_f32_e32 v179, 1.0, v179
	v_mul_f32_e32 v188, v188, v176
	v_mul_f32_e32 v189, v189, v177
	v_mul_f32_e32 v190, v190, v178
	v_mul_f32_e32 v191, v191, v179
	v_cvt_pk_bf16_f32 v140, v188, v189
	v_cvt_pk_bf16_f32 v141, v190, v191
	v_mul_f32_e32 v176, 0x3f3504f3, v98
	v_mul_f32_e32 v177, 0x3f3504f3, v99
	v_mul_f32_e32 v178, 0x3f3504f3, v100
	v_mul_f32_e32 v179, 0x3f3504f3, v101
	v_fma_f32 v180, |v176|, s9, 1.0
	v_fma_f32 v181, |v177|, s9, 1.0
	v_fma_f32 v182, |v178|, s9, 1.0
	v_fma_f32 v183, |v179|, s9, 1.0
	v_rcp_f32_e32 v180, v180
	v_rcp_f32_e32 v181, v181
	v_rcp_f32_e32 v182, v182
	v_rcp_f32_e32 v183, v183
	v_mul_f32_e32 v188, 0.5, v98
	v_mul_f32_e32 v189, 0.5, v99
	v_mul_f32_e32 v190, 0.5, v100
	v_mul_f32_e32 v191, 0.5, v101
	v_fmamk_f32 v184, v180, 0x3f87dc22, v206
	v_fmamk_f32 v185, v181, 0x3f87dc22, v206
	v_fmamk_f32 v186, v182, 0x3f87dc22, v206
	v_fmamk_f32 v187, v183, 0x3f87dc22, v206
	v_fmaak_f32 v184, v184, v180, 0x3fb5f0e3
	v_fmaak_f32 v185, v185, v181, 0x3fb5f0e3
	v_fmaak_f32 v186, v186, v182, 0x3fb5f0e3
	v_fmaak_f32 v187, v187, v183, 0x3fb5f0e3
	v_fmaak_f32 v184, v184, v180, 0xbe91a98e
	v_fmaak_f32 v185, v185, v181, 0xbe91a98e
	v_fmaak_f32 v186, v186, v182, 0xbe91a98e
	v_fmaak_f32 v187, v187, v183, 0xbe91a98e
	v_fmaak_f32 v184, v184, v180, 0x3e827906
	v_fmaak_f32 v185, v185, v181, 0x3e827906
	v_fmaak_f32 v186, v186, v182, 0x3e827906
	v_fmaak_f32 v187, v187, v183, 0x3e827906
	v_mul_f32_e32 v180, v180, v184
	v_mul_f32_e32 v181, v181, v185
	v_mul_f32_e32 v182, v182, v186
	v_mul_f32_e32 v183, v183, v187
	v_mul_f32_e64 v184, |v176|, |v176|
	v_mul_f32_e64 v185, |v177|, |v177|
	v_mul_f32_e64 v186, |v178|, |v178|
	v_mul_f32_e64 v187, |v179|, |v179|
	v_mul_f32_e32 v184, 0xbfb8aa3b, v184
	v_mul_f32_e32 v185, 0xbfb8aa3b, v185
	v_mul_f32_e32 v186, 0xbfb8aa3b, v186
	v_mul_f32_e32 v187, 0xbfb8aa3b, v187
	v_exp_f32_e32 v184, v184
	v_exp_f32_e32 v185, v185
	v_exp_f32_e32 v186, v186
	v_exp_f32_e32 v187, v187
	v_fma_f32 v180, -v184, v180, 1.0
	v_fma_f32 v181, -v185, v181, 1.0
	v_fma_f32 v182, -v186, v182, 1.0
	v_fma_f32 v183, -v187, v183, 1.0
	v_bfi_b32 v176, s10, v180, v176
	v_bfi_b32 v177, s10, v181, v177
	v_bfi_b32 v178, s10, v182, v178
	v_bfi_b32 v179, s10, v183, v179
	v_add_f32_e32 v176, 1.0, v176
	v_add_f32_e32 v177, 1.0, v177
	v_add_f32_e32 v178, 1.0, v178
	v_add_f32_e32 v179, 1.0, v179
	v_mul_f32_e32 v188, v188, v176
	v_mul_f32_e32 v189, v189, v177
	v_mul_f32_e32 v190, v190, v178
	v_mul_f32_e32 v191, v191, v179
	v_cvt_pk_bf16_f32 v142, v188, v189
	v_cvt_pk_bf16_f32 v143, v190, v191
	s_nop 1
	v_permlane16_swap_b32_e32 v148, v150
	v_permlane16_swap_b32_e32 v149, v151
	global_store_dwordx4 v[164:165], v[148:151], off
	v_mul_f32_e32 v176, 0x3f3504f3, v94
	v_mul_f32_e32 v177, 0x3f3504f3, v95
	v_mul_f32_e32 v178, 0x3f3504f3, v96
	v_mul_f32_e32 v179, 0x3f3504f3, v97
	v_fma_f32 v180, |v176|, s9, 1.0
	v_fma_f32 v181, |v177|, s9, 1.0
	v_fma_f32 v182, |v178|, s9, 1.0
	v_fma_f32 v183, |v179|, s9, 1.0
	v_rcp_f32_e32 v180, v180
	v_rcp_f32_e32 v181, v181
	v_rcp_f32_e32 v182, v182
	v_rcp_f32_e32 v183, v183
	v_mul_f32_e32 v188, 0.5, v94
	v_mul_f32_e32 v189, 0.5, v95
	v_mul_f32_e32 v190, 0.5, v96
	v_mul_f32_e32 v191, 0.5, v97
	v_fmamk_f32 v184, v180, 0x3f87dc22, v206
	v_fmamk_f32 v185, v181, 0x3f87dc22, v206
; __device__ __forceinline__ unsigned pack2(float a, float b) { const f32x2_t v = {a, b}; const bf16x2_t r = __builtin_convertvector(v, bf16x2_t); return __builtin_bit_cast(unsigned, r); }
; __device__ __forceinline__ float erf_fast(float x) {
;   const float ax = fabsf(x);
;   const float t = __builtin_amdgcn_rcpf(fmaf(0.3275911f, ax, 1.f));
;   float y = fmaf(1.061405429f, t, -1.453152027f);
;   y = fmaf(y, t, 1.421413741f);
;   y = fmaf(y, t, -0.284496736f);
;   y = fmaf(y, t, 0.254829592f);
;   y = 1.f - y * t * __expf(-ax * ax);
;   return copysignf(y, x);
; }
; __device__ __forceinline__ void ph_proj(const Params& p, int l, char* shm) {
;     ...
;           else if (act == 2) xv = 0.5f * xv * (1.f + erf_fast(xv * 0.70710678118654752f));
;           y[j] = xv;
;         }
;         *(uint2*)(p.P + (size_t)(brow + r) * NP + pn * 256 + c) = uint2{pack2(y[0], y[1]), pack2(y[2], y[3])};
	v_fmamk_f32 v186, v182, 0x3f87dc22, v206
	v_fmamk_f32 v187, v183, 0x3f87dc22, v206
	v_fmaak_f32 v184, v184, v180, 0x3fb5f0e3
	v_fmaak_f32 v185, v185, v181, 0x3fb5f0e3
	v_fmaak_f32 v186, v186, v182, 0x3fb5f0e3
	v_fmaak_f32 v187, v187, v183, 0x3fb5f0e3
	v_fmaak_f32 v184, v184, v180, 0xbe91a98e
	v_fmaak_f32 v185, v185, v181, 0xbe91a98e
	v_fmaak_f32 v186, v186, v182, 0xbe91a98e
	v_fmaak_f32 v187, v187, v183, 0xbe91a98e
	v_fmaak_f32 v184, v184, v180, 0x3e827906
	v_fmaak_f32 v185, v185, v181, 0x3e827906
	v_fmaak_f32 v186, v186, v182, 0x3e827906
	v_fmaak_f32 v187, v187, v183, 0x3e827906
	v_mul_f32_e32 v180, v180, v184
	v_mul_f32_e32 v181, v181, v185
	v_mul_f32_e32 v182, v182, v186
	v_mul_f32_e32 v183, v183, v187
	v_mul_f32_e64 v184, |v176|, |v176|
	v_mul_f32_e64 v185, |v177|, |v177|
	v_mul_f32_e64 v186, |v178|, |v178|
	v_mul_f32_e64 v187, |v179|, |v179|
	v_mul_f32_e32 v184, 0xbfb8aa3b, v184
	v_mul_f32_e32 v185, 0xbfb8aa3b, v185
	v_mul_f32_e32 v186, 0xbfb8aa3b, v186
	v_mul_f32_e32 v187, 0xbfb8aa3b, v187
	v_exp_f32_e32 v184, v184
	v_exp_f32_e32 v185, v185
	v_exp_f32_e32 v186, v186
	v_exp_f32_e32 v187, v187
	v_fma_f32 v180, -v184, v180, 1.0
	v_fma_f32 v181, -v185, v181, 1.0
	v_fma_f32 v182, -v186, v182, 1.0
	v_fma_f32 v183, -v187, v183, 1.0
	v_bfi_b32 v176, s10, v180, v176
	v_bfi_b32 v177, s10, v181, v177
	v_bfi_b32 v178, s10, v182, v178
	v_bfi_b32 v179, s10, v183, v179
	v_add_f32_e32 v176, 1.0, v176
	v_add_f32_e32 v177, 1.0, v177
	v_add_f32_e32 v178, 1.0, v178
	v_add_f32_e32 v179, 1.0, v179
	v_mul_f32_e32 v188, v188, v176
	v_mul_f32_e32 v189, v189, v177
	v_mul_f32_e32 v190, v190, v178
	v_mul_f32_e32 v191, v191, v179
	v_cvt_pk_bf16_f32 v144, v188, v189
	v_cvt_pk_bf16_f32 v145, v190, v191
	v_mul_f32_e32 v176, 0x3f3504f3, v90
	v_mul_f32_e32 v177, 0x3f3504f3, v91
	v_mul_f32_e32 v178, 0x3f3504f3, v92
	v_mul_f32_e32 v179, 0x3f3504f3, v93
	v_fma_f32 v180, |v176|, s9, 1.0
	v_fma_f32 v181, |v177|, s9, 1.0
	v_fma_f32 v182, |v178|, s9, 1.0
	v_fma_f32 v183, |v179|, s9, 1.0
	v_rcp_f32_e32 v180, v180
	v_rcp_f32_e32 v181, v181
	v_rcp_f32_e32 v182, v182
	v_rcp_f32_e32 v183, v183
	v_mul_f32_e32 v188, 0.5, v90
	v_mul_f32_e32 v189, 0.5, v91
	v_mul_f32_e32 v190, 0.5, v92
	v_mul_f32_e32 v191, 0.5, v93
	v_fmamk_f32 v184, v180, 0x3f87dc22, v206
	v_fmamk_f32 v185, v181, 0x3f87dc22, v206
	v_fmamk_f32 v186, v182, 0x3f87dc22, v206
	v_fmamk_f32 v187, v183, 0x3f87dc22, v206
	v_fmaak_f32 v184, v184, v180, 0x3fb5f0e3
	v_fmaak_f32 v185, v185, v181, 0x3fb5f0e3
	v_fmaak_f32 v186, v186, v182, 0x3fb5f0e3
	v_fmaak_f32 v187, v187, v183, 0x3fb5f0e3
	v_fmaak_f32 v184, v184, v180, 0xbe91a98e
	v_fmaak_f32 v185, v185, v181, 0xbe91a98e
	v_fmaak_f32 v186, v186, v182, 0xbe91a98e
	v_fmaak_f32 v187, v187, v183, 0xbe91a98e
	v_fmaak_f32 v184, v184, v180, 0x3e827906
	v_fmaak_f32 v185, v185, v181, 0x3e827906
	v_fmaak_f32 v186, v186, v182, 0x3e827906
	v_fmaak_f32 v187, v187, v183, 0x3e827906
	v_mul_f32_e32 v180, v180, v184
	v_mul_f32_e32 v181, v181, v185
	v_mul_f32_e32 v182, v182, v186
	v_mul_f32_e32 v183, v183, v187
	v_mul_f32_e64 v184, |v176|, |v176|
	v_mul_f32_e64 v185, |v177|, |v177|
	v_mul_f32_e64 v186, |v178|, |v178|
	v_mul_f32_e64 v187, |v179|, |v179|
	v_mul_f32_e32 v184, 0xbfb8aa3b, v184
	v_mul_f32_e32 v185, 0xbfb8aa3b, v185
	v_mul_f32_e32 v186, 0xbfb8aa3b, v186
	v_mul_f32_e32 v187, 0xbfb8aa3b, v187
	v_exp_f32_e32 v184, v184
	v_exp_f32_e32 v185, v185
	v_exp_f32_e32 v186, v186
	v_exp_f32_e32 v187, v187
	v_fma_f32 v180, -v184, v180, 1.0
	v_fma_f32 v181, -v185, v181, 1.0
	v_fma_f32 v182, -v186, v182, 1.0
	v_fma_f32 v183, -v187, v183, 1.0
	v_bfi_b32 v176, s10, v180, v176
	v_bfi_b32 v177, s10, v181, v177
	v_bfi_b32 v178, s10, v182, v178
	v_bfi_b32 v179, s10, v183, v179
	v_add_f32_e32 v176, 1.0, v176
	v_add_f32_e32 v177, 1.0, v177
	v_add_f32_e32 v178, 1.0, v178
	v_add_f32_e32 v179, 1.0, v179
	v_mul_f32_e32 v188, v188, v176
	v_mul_f32_e32 v189, v189, v177
	v_mul_f32_e32 v190, v190, v178
	v_mul_f32_e32 v191, v191, v179
	v_cvt_pk_bf16_f32 v146, v188, v189
	v_cvt_pk_bf16_f32 v147, v190, v191
	s_nop 1
	v_permlane16_swap_b32_e32 v140, v142
	v_permlane16_swap_b32_e32 v141, v143
	global_store_dwordx4 v[166:167], v[140:143], off
	v_mul_f32_e32 v176, 0x3f3504f3, v86
	v_mul_f32_e32 v177, 0x3f3504f3, v87
	v_mul_f32_e32 v178, 0x3f3504f3, v88
	v_mul_f32_e32 v179, 0x3f3504f3, v89
	v_fma_f32 v180, |v176|, s9, 1.0
	v_fma_f32 v181, |v177|, s9, 1.0
	v_fma_f32 v182, |v178|, s9, 1.0
	v_fma_f32 v183, |v179|, s9, 1.0
	v_rcp_f32_e32 v180, v180
	v_rcp_f32_e32 v181, v181
	v_rcp_f32_e32 v182, v182
	v_rcp_f32_e32 v183, v183
	v_mul_f32_e32 v188, 0.5, v86
	v_mul_f32_e32 v189, 0.5, v87
	v_mul_f32_e32 v190, 0.5, v88
	v_mul_f32_e32 v191, 0.5, v89
	v_fmamk_f32 v184, v180, 0x3f87dc22, v206
	v_fmamk_f32 v185, v181, 0x3f87dc22, v206
	v_fmamk_f32 v186, v182, 0x3f87dc22, v206
	v_fmamk_f32 v187, v183, 0x3f87dc22, v206
	v_fmaak_f32 v184, v184, v180, 0x3fb5f0e3
	v_fmaak_f32 v185, v185, v181, 0x3fb5f0e3
	v_fmaak_f32 v186, v186, v182, 0x3fb5f0e3
	v_fmaak_f32 v187, v187, v183, 0x3fb5f0e3
	v_fmaak_f32 v184, v184, v180, 0xbe91a98e
	v_fmaak_f32 v185, v185, v181, 0xbe91a98e
	v_fmaak_f32 v186, v186, v182, 0xbe91a98e
	v_fmaak_f32 v187, v187, v183, 0xbe91a98e
	v_fmaak_f32 v184, v184, v180, 0x3e827906
	v_fmaak_f32 v185, v185, v181, 0x3e827906
	v_fmaak_f32 v186, v186, v182, 0x3e827906
	v_fmaak_f32 v187, v187, v183, 0x3e827906
	v_mul_f32_e32 v180, v180, v184
	v_mul_f32_e32 v181, v181, v185
	v_mul_f32_e32 v182, v182, v186
	v_mul_f32_e32 v183, v183, v187
	v_mul_f32_e64 v184, |v176|, |v176|
	v_mul_f32_e64 v185, |v177|, |v177|
	v_mul_f32_e64 v186, |v178|, |v178|
	v_mul_f32_e64 v187, |v179|, |v179|
	v_mul_f32_e32 v184, 0xbfb8aa3b, v184
; __device__ __forceinline__ unsigned pack2(float a, float b) { const f32x2_t v = {a, b}; const bf16x2_t r = __builtin_convertvector(v, bf16x2_t); return __builtin_bit_cast(unsigned, r); }
; __device__ __forceinline__ float erf_fast(float x) {
;   const float ax = fabsf(x);
;   const float t = __builtin_amdgcn_rcpf(fmaf(0.3275911f, ax, 1.f));
;   float y = fmaf(1.061405429f, t, -1.453152027f);
;   y = fmaf(y, t, 1.421413741f);
;   y = fmaf(y, t, -0.284496736f);
;   y = fmaf(y, t, 0.254829592f);
;   y = 1.f - y * t * __expf(-ax * ax);
;   return copysignf(y, x);
; }
; __device__ __forceinline__ void ph_proj(const Params& p, int l, char* shm) {
;     ...
;           else if (act == 2) xv = 0.5f * xv * (1.f + erf_fast(xv * 0.70710678118654752f));
;           y[j] = xv;
;         }
;         *(uint2*)(p.P + (size_t)(brow + r) * NP + pn * 256 + c) = uint2{pack2(y[0], y[1]), pack2(y[2], y[3])};
	v_mul_f32_e32 v185, 0xbfb8aa3b, v185
	v_mul_f32_e32 v186, 0xbfb8aa3b, v186
	v_mul_f32_e32 v187, 0xbfb8aa3b, v187
	v_exp_f32_e32 v184, v184
	v_exp_f32_e32 v185, v185
	v_exp_f32_e32 v186, v186
	v_exp_f32_e32 v187, v187
	v_fma_f32 v180, -v184, v180, 1.0
	v_fma_f32 v181, -v185, v181, 1.0
	v_fma_f32 v182, -v186, v182, 1.0
	v_fma_f32 v183, -v187, v183, 1.0
	v_bfi_b32 v176, s10, v180, v176
	v_bfi_b32 v177, s10, v181, v177
	v_bfi_b32 v178, s10, v182, v178
	v_bfi_b32 v179, s10, v183, v179
	v_add_f32_e32 v176, 1.0, v176
	v_add_f32_e32 v177, 1.0, v177
	v_add_f32_e32 v178, 1.0, v178
	v_add_f32_e32 v179, 1.0, v179
	v_mul_f32_e32 v188, v188, v176
	v_mul_f32_e32 v189, v189, v177
	v_mul_f32_e32 v190, v190, v178
	v_mul_f32_e32 v191, v191, v179
	v_cvt_pk_bf16_f32 v148, v188, v189
	v_cvt_pk_bf16_f32 v149, v190, v191
	v_mul_f32_e32 v176, 0x3f3504f3, v82
	v_mul_f32_e32 v177, 0x3f3504f3, v83
	v_mul_f32_e32 v178, 0x3f3504f3, v84
	v_mul_f32_e32 v179, 0x3f3504f3, v85
	v_fma_f32 v180, |v176|, s9, 1.0
	v_fma_f32 v181, |v177|, s9, 1.0
	v_fma_f32 v182, |v178|, s9, 1.0
	v_fma_f32 v183, |v179|, s9, 1.0
	v_rcp_f32_e32 v180, v180
	v_rcp_f32_e32 v181, v181
	v_rcp_f32_e32 v182, v182
	v_rcp_f32_e32 v183, v183
	v_mul_f32_e32 v188, 0.5, v82
	v_mul_f32_e32 v189, 0.5, v83
	v_mul_f32_e32 v190, 0.5, v84
	v_mul_f32_e32 v191, 0.5, v85
	v_fmamk_f32 v184, v180, 0x3f87dc22, v206
	v_fmamk_f32 v185, v181, 0x3f87dc22, v206
	v_fmamk_f32 v186, v182, 0x3f87dc22, v206
	v_fmamk_f32 v187, v183, 0x3f87dc22, v206
	v_fmaak_f32 v184, v184, v180, 0x3fb5f0e3
	v_fmaak_f32 v185, v185, v181, 0x3fb5f0e3
	v_fmaak_f32 v186, v186, v182, 0x3fb5f0e3
	v_fmaak_f32 v187, v187, v183, 0x3fb5f0e3
	v_fmaak_f32 v184, v184, v180, 0xbe91a98e
	v_fmaak_f32 v185, v185, v181, 0xbe91a98e
	v_fmaak_f32 v186, v186, v182, 0xbe91a98e
	v_fmaak_f32 v187, v187, v183, 0xbe91a98e
	v_fmaak_f32 v184, v184, v180, 0x3e827906
	v_fmaak_f32 v185, v185, v181, 0x3e827906
	v_fmaak_f32 v186, v186, v182, 0x3e827906
	v_fmaak_f32 v187, v187, v183, 0x3e827906
	v_mul_f32_e32 v180, v180, v184
	v_mul_f32_e32 v181, v181, v185
	v_mul_f32_e32 v182, v182, v186
	v_mul_f32_e32 v183, v183, v187
	v_mul_f32_e64 v184, |v176|, |v176|
	v_mul_f32_e64 v185, |v177|, |v177|
	v_mul_f32_e64 v186, |v178|, |v178|
	v_mul_f32_e64 v187, |v179|, |v179|
	v_mul_f32_e32 v184, 0xbfb8aa3b, v184
	v_mul_f32_e32 v185, 0xbfb8aa3b, v185
	v_mul_f32_e32 v186, 0xbfb8aa3b, v186
	v_mul_f32_e32 v187, 0xbfb8aa3b, v187
	v_exp_f32_e32 v184, v184
	v_exp_f32_e32 v185, v185
	v_exp_f32_e32 v186, v186
	v_exp_f32_e32 v187, v187
	v_fma_f32 v180, -v184, v180, 1.0
	v_fma_f32 v181, -v185, v181, 1.0
	v_fma_f32 v182, -v186, v182, 1.0
	v_fma_f32 v183, -v187, v183, 1.0
	v_bfi_b32 v176, s10, v180, v176
	v_bfi_b32 v177, s10, v181, v177
	v_bfi_b32 v178, s10, v182, v178
	v_bfi_b32 v179, s10, v183, v179
	v_add_f32_e32 v176, 1.0, v176
	v_add_f32_e32 v177, 1.0, v177
	v_add_f32_e32 v178, 1.0, v178
	v_add_f32_e32 v179, 1.0, v179
	v_mul_f32_e32 v188, v188, v176
	v_mul_f32_e32 v189, v189, v177
	v_mul_f32_e32 v190, v190, v178
	v_mul_f32_e32 v191, v191, v179
	v_cvt_pk_bf16_f32 v150, v188, v189
	v_cvt_pk_bf16_f32 v151, v190, v191
	s_nop 1
	v_permlane16_swap_b32_e32 v144, v146
	v_permlane16_swap_b32_e32 v145, v147
	global_store_dwordx4 v[160:161], v[144:147], off offset:256
	v_mul_f32_e32 v176, 0x3f3504f3, v78
	v_mul_f32_e32 v177, 0x3f3504f3, v79
	v_mul_f32_e32 v178, 0x3f3504f3, v80
	v_mul_f32_e32 v179, 0x3f3504f3, v81
	v_fma_f32 v180, |v176|, s9, 1.0
	v_fma_f32 v181, |v177|, s9, 1.0
	v_fma_f32 v182, |v178|, s9, 1.0
	v_fma_f32 v183, |v179|, s9, 1.0
	v_rcp_f32_e32 v180, v180
	v_rcp_f32_e32 v181, v181
	v_rcp_f32_e32 v182, v182
	v_rcp_f32_e32 v183, v183
	v_mul_f32_e32 v188, 0.5, v78
	v_mul_f32_e32 v189, 0.5, v79
	v_mul_f32_e32 v190, 0.5, v80
	v_mul_f32_e32 v191, 0.5, v81
	v_fmamk_f32 v184, v180, 0x3f87dc22, v206
	v_fmamk_f32 v185, v181, 0x3f87dc22, v206
	v_fmamk_f32 v186, v182, 0x3f87dc22, v206
	v_fmamk_f32 v187, v183, 0x3f87dc22, v206
	v_fmaak_f32 v184, v184, v180, 0x3fb5f0e3
	v_fmaak_f32 v185, v185, v181, 0x3fb5f0e3
	v_fmaak_f32 v186, v186, v182, 0x3fb5f0e3
	v_fmaak_f32 v187, v187, v183, 0x3fb5f0e3
	v_fmaak_f32 v184, v184, v180, 0xbe91a98e
	v_fmaak_f32 v185, v185, v181, 0xbe91a98e
	v_fmaak_f32 v186, v186, v182, 0xbe91a98e
	v_fmaak_f32 v187, v187, v183, 0xbe91a98e
	v_fmaak_f32 v184, v184, v180, 0x3e827906
	v_fmaak_f32 v185, v185, v181, 0x3e827906
	v_fmaak_f32 v186, v186, v182, 0x3e827906
	v_fmaak_f32 v187, v187, v183, 0x3e827906
	v_mul_f32_e32 v180, v180, v184
	v_mul_f32_e32 v181, v181, v185
	v_mul_f32_e32 v182, v182, v186
	v_mul_f32_e32 v183, v183, v187
	v_mul_f32_e64 v184, |v176|, |v176|
	v_mul_f32_e64 v185, |v177|, |v177|
	v_mul_f32_e64 v186, |v178|, |v178|
	v_mul_f32_e64 v187, |v179|, |v179|
	v_mul_f32_e32 v184, 0xbfb8aa3b, v184
	v_mul_f32_e32 v185, 0xbfb8aa3b, v185
	v_mul_f32_e32 v186, 0xbfb8aa3b, v186
	v_mul_f32_e32 v187, 0xbfb8aa3b, v187
	v_exp_f32_e32 v184, v184
	v_exp_f32_e32 v185, v185
	v_exp_f32_e32 v186, v186
	v_exp_f32_e32 v187, v187
	v_fma_f32 v180, -v184, v180, 1.0
	v_fma_f32 v181, -v185, v181, 1.0
	v_fma_f32 v182, -v186, v182, 1.0
	v_fma_f32 v183, -v187, v183, 1.0
	v_bfi_b32 v176, s10, v180, v176
	v_bfi_b32 v177, s10, v181, v177
	v_bfi_b32 v178, s10, v182, v178
	v_bfi_b32 v179, s10, v183, v179
	v_add_f32_e32 v176, 1.0, v176
	v_add_f32_e32 v177, 1.0, v177
	v_add_f32_e32 v178, 1.0, v178
	v_add_f32_e32 v179, 1.0, v179
	v_mul_f32_e32 v188, v188, v176
	v_mul_f32_e32 v189, v189, v177
	v_mul_f32_e32 v190, v190, v178
	v_mul_f32_e32 v191, v191, v179
	v_cvt_pk_bf16_f32 v140, v188, v189
	v_cvt_pk_bf16_f32 v141, v190, v191
	v_mul_f32_e32 v176, 0x3f3504f3, v74
	v_mul_f32_e32 v177, 0x3f3504f3, v75
; __device__ __forceinline__ unsigned pack2(float a, float b) { const f32x2_t v = {a, b}; const bf16x2_t r = __builtin_convertvector(v, bf16x2_t); return __builtin_bit_cast(unsigned, r); }
; __device__ __forceinline__ float erf_fast(float x) {
;   const float ax = fabsf(x);
;   const float t = __builtin_amdgcn_rcpf(fmaf(0.3275911f, ax, 1.f));
;   float y = fmaf(1.061405429f, t, -1.453152027f);
;   y = fmaf(y, t, 1.421413741f);
;   y = fmaf(y, t, -0.284496736f);
;   y = fmaf(y, t, 0.254829592f);
;   y = 1.f - y * t * __expf(-ax * ax);
;   return copysignf(y, x);
; }
; __device__ __forceinline__ void ph_proj(const Params& p, int l, char* shm) {
;     ...
;           else if (act == 2) xv = 0.5f * xv * (1.f + erf_fast(xv * 0.70710678118654752f));
;           y[j] = xv;
;         }
;         *(uint2*)(p.P + (size_t)(brow + r) * NP + pn * 256 + c) = uint2{pack2(y[0], y[1]), pack2(y[2], y[3])};
	v_mul_f32_e32 v178, 0x3f3504f3, v76
	v_mul_f32_e32 v179, 0x3f3504f3, v77
	v_fma_f32 v180, |v176|, s9, 1.0
	v_fma_f32 v181, |v177|, s9, 1.0
	v_fma_f32 v182, |v178|, s9, 1.0
	v_fma_f32 v183, |v179|, s9, 1.0
	v_rcp_f32_e32 v180, v180
	v_rcp_f32_e32 v181, v181
	v_rcp_f32_e32 v182, v182
	v_rcp_f32_e32 v183, v183
	v_mul_f32_e32 v188, 0.5, v74
	v_mul_f32_e32 v189, 0.5, v75
	v_mul_f32_e32 v190, 0.5, v76
	v_mul_f32_e32 v191, 0.5, v77
	v_fmamk_f32 v184, v180, 0x3f87dc22, v206
	v_fmamk_f32 v185, v181, 0x3f87dc22, v206
	v_fmamk_f32 v186, v182, 0x3f87dc22, v206
	v_fmamk_f32 v187, v183, 0x3f87dc22, v206
	v_fmaak_f32 v184, v184, v180, 0x3fb5f0e3
	v_fmaak_f32 v185, v185, v181, 0x3fb5f0e3
	v_fmaak_f32 v186, v186, v182, 0x3fb5f0e3
	v_fmaak_f32 v187, v187, v183, 0x3fb5f0e3
	v_fmaak_f32 v184, v184, v180, 0xbe91a98e
	v_fmaak_f32 v185, v185, v181, 0xbe91a98e
	v_fmaak_f32 v186, v186, v182, 0xbe91a98e
	v_fmaak_f32 v187, v187, v183, 0xbe91a98e
	v_fmaak_f32 v184, v184, v180, 0x3e827906
	v_fmaak_f32 v185, v185, v181, 0x3e827906
	v_fmaak_f32 v186, v186, v182, 0x3e827906
	v_fmaak_f32 v187, v187, v183, 0x3e827906
	v_mul_f32_e32 v180, v180, v184
	v_mul_f32_e32 v181, v181, v185
	v_mul_f32_e32 v182, v182, v186
	v_mul_f32_e32 v183, v183, v187
	v_mul_f32_e64 v184, |v176|, |v176|
	v_mul_f32_e64 v185, |v177|, |v177|
	v_mul_f32_e64 v186, |v178|, |v178|
	v_mul_f32_e64 v187, |v179|, |v179|
	v_mul_f32_e32 v184, 0xbfb8aa3b, v184
	v_mul_f32_e32 v185, 0xbfb8aa3b, v185
	v_mul_f32_e32 v186, 0xbfb8aa3b, v186
	v_mul_f32_e32 v187, 0xbfb8aa3b, v187
	v_exp_f32_e32 v184, v184
	v_exp_f32_e32 v185, v185
	v_exp_f32_e32 v186, v186
	v_exp_f32_e32 v187, v187
	v_fma_f32 v180, -v184, v180, 1.0
	v_fma_f32 v181, -v185, v181, 1.0
	v_fma_f32 v182, -v186, v182, 1.0
	v_fma_f32 v183, -v187, v183, 1.0
	v_bfi_b32 v176, s10, v180, v176
	v_bfi_b32 v177, s10, v181, v177
	v_bfi_b32 v178, s10, v182, v178
	v_bfi_b32 v179, s10, v183, v179
	v_add_f32_e32 v176, 1.0, v176
	v_add_f32_e32 v177, 1.0, v177
	v_add_f32_e32 v178, 1.0, v178
	v_add_f32_e32 v179, 1.0, v179
	v_mul_f32_e32 v188, v188, v176
	v_mul_f32_e32 v189, v189, v177
	v_mul_f32_e32 v190, v190, v178
	v_mul_f32_e32 v191, v191, v179
	v_cvt_pk_bf16_f32 v142, v188, v189
	v_cvt_pk_bf16_f32 v143, v190, v191
	s_nop 1
	v_permlane16_swap_b32_e32 v148, v150
	v_permlane16_swap_b32_e32 v149, v151
	global_store_dwordx4 v[162:163], v[148:151], off offset:256
	v_mul_f32_e32 v176, 0x3f3504f3, v70
	v_mul_f32_e32 v177, 0x3f3504f3, v71
	v_mul_f32_e32 v178, 0x3f3504f3, v72
	v_mul_f32_e32 v179, 0x3f3504f3, v73
	v_fma_f32 v180, |v176|, s9, 1.0
	v_fma_f32 v181, |v177|, s9, 1.0
	v_fma_f32 v182, |v178|, s9, 1.0
	v_fma_f32 v183, |v179|, s9, 1.0
	v_rcp_f32_e32 v180, v180
	v_rcp_f32_e32 v181, v181
	v_rcp_f32_e32 v182, v182
	v_rcp_f32_e32 v183, v183
	v_mul_f32_e32 v188, 0.5, v70
	v_mul_f32_e32 v189, 0.5, v71
	v_mul_f32_e32 v190, 0.5, v72
	v_mul_f32_e32 v191, 0.5, v73
	v_fmamk_f32 v184, v180, 0x3f87dc22, v206
	v_fmamk_f32 v185, v181, 0x3f87dc22, v206
	v_fmamk_f32 v186, v182, 0x3f87dc22, v206
	v_fmamk_f32 v187, v183, 0x3f87dc22, v206
	v_fmaak_f32 v184, v184, v180, 0x3fb5f0e3
	v_fmaak_f32 v185, v185, v181, 0x3fb5f0e3
	v_fmaak_f32 v186, v186, v182, 0x3fb5f0e3
	v_fmaak_f32 v187, v187, v183, 0x3fb5f0e3
	v_fmaak_f32 v184, v184, v180, 0xbe91a98e
	v_fmaak_f32 v185, v185, v181, 0xbe91a98e
	v_fmaak_f32 v186, v186, v182, 0xbe91a98e
	v_fmaak_f32 v187, v187, v183, 0xbe91a98e
	v_fmaak_f32 v184, v184, v180, 0x3e827906
	v_fmaak_f32 v185, v185, v181, 0x3e827906
	v_fmaak_f32 v186, v186, v182, 0x3e827906
	v_fmaak_f32 v187, v187, v183, 0x3e827906
	v_mul_f32_e32 v180, v180, v184
	v_mul_f32_e32 v181, v181, v185
	v_mul_f32_e32 v182, v182, v186
	v_mul_f32_e32 v183, v183, v187
	v_mul_f32_e64 v184, |v176|, |v176|
	v_mul_f32_e64 v185, |v177|, |v177|
	v_mul_f32_e64 v186, |v178|, |v178|
	v_mul_f32_e64 v187, |v179|, |v179|
	v_mul_f32_e32 v184, 0xbfb8aa3b, v184
	v_mul_f32_e32 v185, 0xbfb8aa3b, v185
	v_mul_f32_e32 v186, 0xbfb8aa3b, v186
	v_mul_f32_e32 v187, 0xbfb8aa3b, v187
	v_exp_f32_e32 v184, v184
	v_exp_f32_e32 v185, v185
	v_exp_f32_e32 v186, v186
	v_exp_f32_e32 v187, v187
	v_fma_f32 v180, -v184, v180, 1.0
	v_fma_f32 v181, -v185, v181, 1.0
	v_fma_f32 v182, -v186, v182, 1.0
	v_fma_f32 v183, -v187, v183, 1.0
	v_bfi_b32 v176, s10, v180, v176
	v_bfi_b32 v177, s10, v181, v177
	v_bfi_b32 v178, s10, v182, v178
	v_bfi_b32 v179, s10, v183, v179
	v_add_f32_e32 v176, 1.0, v176
	v_add_f32_e32 v177, 1.0, v177
	v_add_f32_e32 v178, 1.0, v178
	v_add_f32_e32 v179, 1.0, v179
	v_mul_f32_e32 v188, v188, v176
	v_mul_f32_e32 v189, v189, v177
	v_mul_f32_e32 v190, v190, v178
	v_mul_f32_e32 v191, v191, v179
	v_cvt_pk_bf16_f32 v144, v188, v189
	v_cvt_pk_bf16_f32 v145, v190, v191
	v_mul_f32_e32 v176, 0x3f3504f3, v66
	v_mul_f32_e32 v177, 0x3f3504f3, v67
	v_mul_f32_e32 v178, 0x3f3504f3, v68
	v_mul_f32_e32 v179, 0x3f3504f3, v69
	v_fma_f32 v180, |v176|, s9, 1.0
	v_fma_f32 v181, |v177|, s9, 1.0
	v_fma_f32 v182, |v178|, s9, 1.0
	v_fma_f32 v183, |v179|, s9, 1.0
	v_rcp_f32_e32 v180, v180
	v_rcp_f32_e32 v181, v181
	v_rcp_f32_e32 v182, v182
	v_rcp_f32_e32 v183, v183
	v_mul_f32_e32 v188, 0.5, v66
	v_mul_f32_e32 v189, 0.5, v67
	v_mul_f32_e32 v190, 0.5, v68
	v_mul_f32_e32 v191, 0.5, v69
	v_fmamk_f32 v184, v180, 0x3f87dc22, v206
	v_fmamk_f32 v185, v181, 0x3f87dc22, v206
	v_fmamk_f32 v186, v182, 0x3f87dc22, v206
	v_fmamk_f32 v187, v183, 0x3f87dc22, v206
	v_fmaak_f32 v184, v184, v180, 0x3fb5f0e3
	v_fmaak_f32 v185, v185, v181, 0x3fb5f0e3
	v_fmaak_f32 v186, v186, v182, 0x3fb5f0e3
	v_fmaak_f32 v187, v187, v183, 0x3fb5f0e3
	v_fmaak_f32 v184, v184, v180, 0xbe91a98e
	v_fmaak_f32 v185, v185, v181, 0xbe91a98e
	v_fmaak_f32 v186, v186, v182, 0xbe91a98e
; __device__ __forceinline__ unsigned pack2(float a, float b) { const f32x2_t v = {a, b}; const bf16x2_t r = __builtin_convertvector(v, bf16x2_t); return __builtin_bit_cast(unsigned, r); }
; __device__ __forceinline__ float erf_fast(float x) {
;   const float ax = fabsf(x);
;   const float t = __builtin_amdgcn_rcpf(fmaf(0.3275911f, ax, 1.f));
;   float y = fmaf(1.061405429f, t, -1.453152027f);
;   y = fmaf(y, t, 1.421413741f);
;   y = fmaf(y, t, -0.284496736f);
;   y = fmaf(y, t, 0.254829592f);
;   y = 1.f - y * t * __expf(-ax * ax);
;   return copysignf(y, x);
; }
; __device__ __forceinline__ void ph_proj(const Params& p, int l, char* shm) {
;     ...
;           else if (act == 2) xv = 0.5f * xv * (1.f + erf_fast(xv * 0.70710678118654752f));
;           y[j] = xv;
;         }
;         *(uint2*)(p.P + (size_t)(brow + r) * NP + pn * 256 + c) = uint2{pack2(y[0], y[1]), pack2(y[2], y[3])};
	v_fmaak_f32 v187, v187, v183, 0xbe91a98e
	v_fmaak_f32 v184, v184, v180, 0x3e827906
	v_fmaak_f32 v185, v185, v181, 0x3e827906
	v_fmaak_f32 v186, v186, v182, 0x3e827906
	v_fmaak_f32 v187, v187, v183, 0x3e827906
	v_mul_f32_e32 v180, v180, v184
	v_mul_f32_e32 v181, v181, v185
	v_mul_f32_e32 v182, v182, v186
	v_mul_f32_e32 v183, v183, v187
	v_mul_f32_e64 v184, |v176|, |v176|
	v_mul_f32_e64 v185, |v177|, |v177|
	v_mul_f32_e64 v186, |v178|, |v178|
	v_mul_f32_e64 v187, |v179|, |v179|
	v_mul_f32_e32 v184, 0xbfb8aa3b, v184
	v_mul_f32_e32 v185, 0xbfb8aa3b, v185
	v_mul_f32_e32 v186, 0xbfb8aa3b, v186
	v_mul_f32_e32 v187, 0xbfb8aa3b, v187
	v_exp_f32_e32 v184, v184
	v_exp_f32_e32 v185, v185
	v_exp_f32_e32 v186, v186
	v_exp_f32_e32 v187, v187
	v_fma_f32 v180, -v184, v180, 1.0
	v_fma_f32 v181, -v185, v181, 1.0
	v_fma_f32 v182, -v186, v182, 1.0
	v_fma_f32 v183, -v187, v183, 1.0
	v_bfi_b32 v176, s10, v180, v176
	v_bfi_b32 v177, s10, v181, v177
	v_bfi_b32 v178, s10, v182, v178
	v_bfi_b32 v179, s10, v183, v179
	v_add_f32_e32 v176, 1.0, v176
	v_add_f32_e32 v177, 1.0, v177
	v_add_f32_e32 v178, 1.0, v178
	v_add_f32_e32 v179, 1.0, v179
	v_mul_f32_e32 v188, v188, v176
	v_mul_f32_e32 v189, v189, v177
	v_mul_f32_e32 v190, v190, v178
	v_mul_f32_e32 v191, v191, v179
	v_cvt_pk_bf16_f32 v146, v188, v189
	v_cvt_pk_bf16_f32 v147, v190, v191
	s_nop 1
	v_permlane16_swap_b32_e32 v140, v142
	v_permlane16_swap_b32_e32 v141, v143
	global_store_dwordx4 v[164:165], v[140:143], off offset:256
	v_mul_f32_e32 v176, 0x3f3504f3, v62
	v_mul_f32_e32 v177, 0x3f3504f3, v63
	v_mul_f32_e32 v178, 0x3f3504f3, v64
	v_mul_f32_e32 v179, 0x3f3504f3, v65
	v_fma_f32 v180, |v176|, s9, 1.0
	v_fma_f32 v181, |v177|, s9, 1.0
	v_fma_f32 v182, |v178|, s9, 1.0
	v_fma_f32 v183, |v179|, s9, 1.0
	v_rcp_f32_e32 v180, v180
	v_rcp_f32_e32 v181, v181
	v_rcp_f32_e32 v182, v182
	v_rcp_f32_e32 v183, v183
	v_mul_f32_e32 v188, 0.5, v62
	v_mul_f32_e32 v189, 0.5, v63
	v_mul_f32_e32 v190, 0.5, v64
	v_mul_f32_e32 v191, 0.5, v65
	v_fmamk_f32 v184, v180, 0x3f87dc22, v206
	v_fmamk_f32 v185, v181, 0x3f87dc22, v206
	v_fmamk_f32 v186, v182, 0x3f87dc22, v206
	v_fmamk_f32 v187, v183, 0x3f87dc22, v206
	v_fmaak_f32 v184, v184, v180, 0x3fb5f0e3
	v_fmaak_f32 v185, v185, v181, 0x3fb5f0e3
	v_fmaak_f32 v186, v186, v182, 0x3fb5f0e3
	v_fmaak_f32 v187, v187, v183, 0x3fb5f0e3
	v_fmaak_f32 v184, v184, v180, 0xbe91a98e
	v_fmaak_f32 v185, v185, v181, 0xbe91a98e
	v_fmaak_f32 v186, v186, v182, 0xbe91a98e
	v_fmaak_f32 v187, v187, v183, 0xbe91a98e
	v_fmaak_f32 v184, v184, v180, 0x3e827906
	v_fmaak_f32 v185, v185, v181, 0x3e827906
	v_fmaak_f32 v186, v186, v182, 0x3e827906
	v_fmaak_f32 v187, v187, v183, 0x3e827906
	v_mul_f32_e32 v180, v180, v184
	v_mul_f32_e32 v181, v181, v185
	v_mul_f32_e32 v182, v182, v186
	v_mul_f32_e32 v183, v183, v187
	v_mul_f32_e64 v184, |v176|, |v176|
	v_mul_f32_e64 v185, |v177|, |v177|
	v_mul_f32_e64 v186, |v178|, |v178|
	v_mul_f32_e64 v187, |v179|, |v179|
	v_mul_f32_e32 v184, 0xbfb8aa3b, v184
	v_mul_f32_e32 v185, 0xbfb8aa3b, v185
	v_mul_f32_e32 v186, 0xbfb8aa3b, v186
	v_mul_f32_e32 v187, 0xbfb8aa3b, v187
	v_exp_f32_e32 v184, v184
	v_exp_f32_e32 v185, v185
	v_exp_f32_e32 v186, v186
	v_exp_f32_e32 v187, v187
	v_fma_f32 v180, -v184, v180, 1.0
	v_fma_f32 v181, -v185, v181, 1.0
	v_fma_f32 v182, -v186, v182, 1.0
	v_fma_f32 v183, -v187, v183, 1.0
	v_bfi_b32 v176, s10, v180, v176
	v_bfi_b32 v177, s10, v181, v177
	v_bfi_b32 v178, s10, v182, v178
	v_bfi_b32 v179, s10, v183, v179
	v_add_f32_e32 v176, 1.0, v176
	v_add_f32_e32 v177, 1.0, v177
	v_add_f32_e32 v178, 1.0, v178
	v_add_f32_e32 v179, 1.0, v179
	v_mul_f32_e32 v188, v188, v176
	v_mul_f32_e32 v189, v189, v177
	v_mul_f32_e32 v190, v190, v178
	v_mul_f32_e32 v191, v191, v179
	v_cvt_pk_bf16_f32 v148, v188, v189
	v_cvt_pk_bf16_f32 v149, v190, v191
	v_mul_f32_e32 v176, 0x3f3504f3, v58
	v_mul_f32_e32 v177, 0x3f3504f3, v59
	v_mul_f32_e32 v178, 0x3f3504f3, v60
	v_mul_f32_e32 v179, 0x3f3504f3, v61
	v_fma_f32 v180, |v176|, s9, 1.0
	v_fma_f32 v181, |v177|, s9, 1.0
	v_fma_f32 v182, |v178|, s9, 1.0
	v_fma_f32 v183, |v179|, s9, 1.0
	v_rcp_f32_e32 v180, v180
	v_rcp_f32_e32 v181, v181
	v_rcp_f32_e32 v182, v182
	v_rcp_f32_e32 v183, v183
	v_mul_f32_e32 v188, 0.5, v58
	v_mul_f32_e32 v189, 0.5, v59
	v_mul_f32_e32 v190, 0.5, v60
	v_mul_f32_e32 v191, 0.5, v61
	v_fmamk_f32 v184, v180, 0x3f87dc22, v206
	v_fmamk_f32 v185, v181, 0x3f87dc22, v206
	v_fmamk_f32 v186, v182, 0x3f87dc22, v206
	v_fmamk_f32 v187, v183, 0x3f87dc22, v206
	v_fmaak_f32 v184, v184, v180, 0x3fb5f0e3
	v_fmaak_f32 v185, v185, v181, 0x3fb5f0e3
	v_fmaak_f32 v186, v186, v182, 0x3fb5f0e3
	v_fmaak_f32 v187, v187, v183, 0x3fb5f0e3
	v_fmaak_f32 v184, v184, v180, 0xbe91a98e
	v_fmaak_f32 v185, v185, v181, 0xbe91a98e
	v_fmaak_f32 v186, v186, v182, 0xbe91a98e
	v_fmaak_f32 v187, v187, v183, 0xbe91a98e
	v_fmaak_f32 v184, v184, v180, 0x3e827906
	v_fmaak_f32 v185, v185, v181, 0x3e827906
	v_fmaak_f32 v186, v186, v182, 0x3e827906
	v_fmaak_f32 v187, v187, v183, 0x3e827906
	v_mul_f32_e32 v180, v180, v184
	v_mul_f32_e32 v181, v181, v185
	v_mul_f32_e32 v182, v182, v186
	v_mul_f32_e32 v183, v183, v187
	v_mul_f32_e64 v184, |v176|, |v176|
	v_mul_f32_e64 v185, |v177|, |v177|
	v_mul_f32_e64 v186, |v178|, |v178|
	v_mul_f32_e64 v187, |v179|, |v179|
	v_mul_f32_e32 v184, 0xbfb8aa3b, v184
	v_mul_f32_e32 v185, 0xbfb8aa3b, v185
	v_mul_f32_e32 v186, 0xbfb8aa3b, v186
	v_mul_f32_e32 v187, 0xbfb8aa3b, v187
	v_exp_f32_e32 v184, v184
	v_exp_f32_e32 v185, v185
	v_exp_f32_e32 v186, v186
	v_exp_f32_e32 v187, v187
	v_fma_f32 v180, -v184, v180, 1.0
	v_fma_f32 v181, -v185, v181, 1.0
	v_fma_f32 v182, -v186, v182, 1.0
	v_fma_f32 v183, -v187, v183, 1.0
	v_bfi_b32 v176, s10, v180, v176
; __device__ __forceinline__ unsigned pack2(float a, float b) { const f32x2_t v = {a, b}; const bf16x2_t r = __builtin_convertvector(v, bf16x2_t); return __builtin_bit_cast(unsigned, r); }
; __device__ __forceinline__ float erf_fast(float x) {
;   const float ax = fabsf(x);
;   const float t = __builtin_amdgcn_rcpf(fmaf(0.3275911f, ax, 1.f));
;   float y = fmaf(1.061405429f, t, -1.453152027f);
;   y = fmaf(y, t, 1.421413741f);
;   y = fmaf(y, t, -0.284496736f);
;   y = fmaf(y, t, 0.254829592f);
;   y = 1.f - y * t * __expf(-ax * ax);
;   return copysignf(y, x);
; }
; __device__ __forceinline__ void ph_proj(const Params& p, int l, char* shm) {
;     ...
;           else if (act == 2) xv = 0.5f * xv * (1.f + erf_fast(xv * 0.70710678118654752f));
;           y[j] = xv;
;         }
;         *(uint2*)(p.P + (size_t)(brow + r) * NP + pn * 256 + c) = uint2{pack2(y[0], y[1]), pack2(y[2], y[3])};
	v_bfi_b32 v177, s10, v181, v177
	v_bfi_b32 v178, s10, v182, v178
	v_bfi_b32 v179, s10, v183, v179
	v_add_f32_e32 v176, 1.0, v176
	v_add_f32_e32 v177, 1.0, v177
	v_add_f32_e32 v178, 1.0, v178
	v_add_f32_e32 v179, 1.0, v179
	v_mul_f32_e32 v188, v188, v176
	v_mul_f32_e32 v189, v189, v177
	v_mul_f32_e32 v190, v190, v178
	v_mul_f32_e32 v191, v191, v179
	v_cvt_pk_bf16_f32 v150, v188, v189
	v_cvt_pk_bf16_f32 v151, v190, v191
	s_nop 1
	v_permlane16_swap_b32_e32 v144, v146
	v_permlane16_swap_b32_e32 v145, v147
	global_store_dwordx4 v[166:167], v[144:147], off offset:256
	v_mul_f32_e32 v176, 0x3f3504f3, v54
	v_mul_f32_e32 v177, 0x3f3504f3, v55
	v_mul_f32_e32 v178, 0x3f3504f3, v56
	v_mul_f32_e32 v179, 0x3f3504f3, v57
	v_fma_f32 v180, |v176|, s9, 1.0
	v_fma_f32 v181, |v177|, s9, 1.0
	v_fma_f32 v182, |v178|, s9, 1.0
	v_fma_f32 v183, |v179|, s9, 1.0
	v_rcp_f32_e32 v180, v180
	v_rcp_f32_e32 v181, v181
	v_rcp_f32_e32 v182, v182
	v_rcp_f32_e32 v183, v183
	v_mul_f32_e32 v188, 0.5, v54
	v_mul_f32_e32 v189, 0.5, v55
	v_mul_f32_e32 v190, 0.5, v56
	v_mul_f32_e32 v191, 0.5, v57
	v_fmamk_f32 v184, v180, 0x3f87dc22, v206
	v_fmamk_f32 v185, v181, 0x3f87dc22, v206
	v_fmamk_f32 v186, v182, 0x3f87dc22, v206
	v_fmamk_f32 v187, v183, 0x3f87dc22, v206
	v_fmaak_f32 v184, v184, v180, 0x3fb5f0e3
	v_fmaak_f32 v185, v185, v181, 0x3fb5f0e3
	v_fmaak_f32 v186, v186, v182, 0x3fb5f0e3
	v_fmaak_f32 v187, v187, v183, 0x3fb5f0e3
	v_fmaak_f32 v184, v184, v180, 0xbe91a98e
	v_fmaak_f32 v185, v185, v181, 0xbe91a98e
	v_fmaak_f32 v186, v186, v182, 0xbe91a98e
	v_fmaak_f32 v187, v187, v183, 0xbe91a98e
	v_fmaak_f32 v184, v184, v180, 0x3e827906
	v_fmaak_f32 v185, v185, v181, 0x3e827906
	v_fmaak_f32 v186, v186, v182, 0x3e827906
	v_fmaak_f32 v187, v187, v183, 0x3e827906
	v_mul_f32_e32 v180, v180, v184
	v_mul_f32_e32 v181, v181, v185
	v_mul_f32_e32 v182, v182, v186
	v_mul_f32_e32 v183, v183, v187
	v_mul_f32_e64 v184, |v176|, |v176|
	v_mul_f32_e64 v185, |v177|, |v177|
	v_mul_f32_e64 v186, |v178|, |v178|
	v_mul_f32_e64 v187, |v179|, |v179|
	v_mul_f32_e32 v184, 0xbfb8aa3b, v184
	v_mul_f32_e32 v185, 0xbfb8aa3b, v185
	v_mul_f32_e32 v186, 0xbfb8aa3b, v186
	v_mul_f32_e32 v187, 0xbfb8aa3b, v187
	v_exp_f32_e32 v184, v184
	v_exp_f32_e32 v185, v185
	v_exp_f32_e32 v186, v186
	v_exp_f32_e32 v187, v187
	v_fma_f32 v180, -v184, v180, 1.0
	v_fma_f32 v181, -v185, v181, 1.0
	v_fma_f32 v182, -v186, v182, 1.0
	v_fma_f32 v183, -v187, v183, 1.0
	v_bfi_b32 v176, s10, v180, v176
	v_bfi_b32 v177, s10, v181, v177
	v_bfi_b32 v178, s10, v182, v178
	v_bfi_b32 v179, s10, v183, v179
	v_add_f32_e32 v176, 1.0, v176
	v_add_f32_e32 v177, 1.0, v177
	v_add_f32_e32 v178, 1.0, v178
	v_add_f32_e32 v179, 1.0, v179
	v_mul_f32_e32 v188, v188, v176
	v_mul_f32_e32 v189, v189, v177
	v_mul_f32_e32 v190, v190, v178
	v_mul_f32_e32 v191, v191, v179
	v_cvt_pk_bf16_f32 v140, v188, v189
	v_cvt_pk_bf16_f32 v141, v190, v191
	v_mul_f32_e32 v176, 0x3f3504f3, v50
	v_mul_f32_e32 v177, 0x3f3504f3, v51
	v_mul_f32_e32 v178, 0x3f3504f3, v52
	v_mul_f32_e32 v179, 0x3f3504f3, v53
	v_fma_f32 v180, |v176|, s9, 1.0
	v_fma_f32 v181, |v177|, s9, 1.0
	v_fma_f32 v182, |v178|, s9, 1.0
	v_fma_f32 v183, |v179|, s9, 1.0
	v_rcp_f32_e32 v180, v180
	v_rcp_f32_e32 v181, v181
	v_rcp_f32_e32 v182, v182
	v_rcp_f32_e32 v183, v183
	v_mul_f32_e32 v188, 0.5, v50
	v_mul_f32_e32 v189, 0.5, v51
	v_mul_f32_e32 v190, 0.5, v52
	v_mul_f32_e32 v191, 0.5, v53
	v_fmamk_f32 v184, v180, 0x3f87dc22, v206
	v_fmamk_f32 v185, v181, 0x3f87dc22, v206
	v_fmamk_f32 v186, v182, 0x3f87dc22, v206
	v_fmamk_f32 v187, v183, 0x3f87dc22, v206
	v_fmaak_f32 v184, v184, v180, 0x3fb5f0e3
	v_fmaak_f32 v185, v185, v181, 0x3fb5f0e3
	v_fmaak_f32 v186, v186, v182, 0x3fb5f0e3
	v_fmaak_f32 v187, v187, v183, 0x3fb5f0e3
	v_fmaak_f32 v184, v184, v180, 0xbe91a98e
	v_fmaak_f32 v185, v185, v181, 0xbe91a98e
	v_fmaak_f32 v186, v186, v182, 0xbe91a98e
	v_fmaak_f32 v187, v187, v183, 0xbe91a98e
	v_fmaak_f32 v184, v184, v180, 0x3e827906
	v_fmaak_f32 v185, v185, v181, 0x3e827906
	v_fmaak_f32 v186, v186, v182, 0x3e827906
	v_fmaak_f32 v187, v187, v183, 0x3e827906
	v_mul_f32_e32 v180, v180, v184
	v_mul_f32_e32 v181, v181, v185
	v_mul_f32_e32 v182, v182, v186
	v_mul_f32_e32 v183, v183, v187
	v_mul_f32_e64 v184, |v176|, |v176|
	v_mul_f32_e64 v185, |v177|, |v177|
	v_mul_f32_e64 v186, |v178|, |v178|
	v_mul_f32_e64 v187, |v179|, |v179|
	v_mul_f32_e32 v184, 0xbfb8aa3b, v184
	v_mul_f32_e32 v185, 0xbfb8aa3b, v185
	v_mul_f32_e32 v186, 0xbfb8aa3b, v186
	v_mul_f32_e32 v187, 0xbfb8aa3b, v187
	v_exp_f32_e32 v184, v184
	v_exp_f32_e32 v185, v185
	v_exp_f32_e32 v186, v186
	v_exp_f32_e32 v187, v187
	v_fma_f32 v180, -v184, v180, 1.0
	v_fma_f32 v181, -v185, v181, 1.0
	v_fma_f32 v182, -v186, v182, 1.0
	v_fma_f32 v183, -v187, v183, 1.0
	v_bfi_b32 v176, s10, v180, v176
	v_bfi_b32 v177, s10, v181, v177
	v_bfi_b32 v178, s10, v182, v178
	v_bfi_b32 v179, s10, v183, v179
	v_add_f32_e32 v176, 1.0, v176
	v_add_f32_e32 v177, 1.0, v177
	v_add_f32_e32 v178, 1.0, v178
	v_add_f32_e32 v179, 1.0, v179
	v_mul_f32_e32 v188, v188, v176
	v_mul_f32_e32 v189, v189, v177
	v_mul_f32_e32 v190, v190, v178
	v_mul_f32_e32 v191, v191, v179
	v_cvt_pk_bf16_f32 v142, v188, v189
	v_cvt_pk_bf16_f32 v143, v190, v191
	s_nop 1
	v_permlane16_swap_b32_e32 v148, v150
	v_permlane16_swap_b32_e32 v149, v151
	global_store_dwordx4 v[168:169], v[148:151], off
	v_mul_f32_e32 v176, 0x3f3504f3, v46
	v_mul_f32_e32 v177, 0x3f3504f3, v47
	v_mul_f32_e32 v178, 0x3f3504f3, v48
	v_mul_f32_e32 v179, 0x3f3504f3, v49
	v_fma_f32 v180, |v176|, s9, 1.0
	v_fma_f32 v181, |v177|, s9, 1.0
	v_fma_f32 v182, |v178|, s9, 1.0
	v_fma_f32 v183, |v179|, s9, 1.0
	v_rcp_f32_e32 v180, v180
	v_rcp_f32_e32 v181, v181
; __device__ __forceinline__ unsigned pack2(float a, float b) { const f32x2_t v = {a, b}; const bf16x2_t r = __builtin_convertvector(v, bf16x2_t); return __builtin_bit_cast(unsigned, r); }
; __device__ __forceinline__ float erf_fast(float x) {
;   const float ax = fabsf(x);
;   const float t = __builtin_amdgcn_rcpf(fmaf(0.3275911f, ax, 1.f));
;   float y = fmaf(1.061405429f, t, -1.453152027f);
;   y = fmaf(y, t, 1.421413741f);
;   y = fmaf(y, t, -0.284496736f);
;   y = fmaf(y, t, 0.254829592f);
;   y = 1.f - y * t * __expf(-ax * ax);
;   return copysignf(y, x);
; }
; __device__ __forceinline__ void ph_proj(const Params& p, int l, char* shm) {
;     ...
;           else if (act == 2) xv = 0.5f * xv * (1.f + erf_fast(xv * 0.70710678118654752f));
;           y[j] = xv;
;         }
;         *(uint2*)(p.P + (size_t)(brow + r) * NP + pn * 256 + c) = uint2{pack2(y[0], y[1]), pack2(y[2], y[3])};
	v_rcp_f32_e32 v182, v182
	v_rcp_f32_e32 v183, v183
	v_mul_f32_e32 v188, 0.5, v46
	v_mul_f32_e32 v189, 0.5, v47
	v_mul_f32_e32 v190, 0.5, v48
	v_mul_f32_e32 v191, 0.5, v49
	v_fmamk_f32 v184, v180, 0x3f87dc22, v206
	v_fmamk_f32 v185, v181, 0x3f87dc22, v206
	v_fmamk_f32 v186, v182, 0x3f87dc22, v206
	v_fmamk_f32 v187, v183, 0x3f87dc22, v206
	v_fmaak_f32 v184, v184, v180, 0x3fb5f0e3
	v_fmaak_f32 v185, v185, v181, 0x3fb5f0e3
	v_fmaak_f32 v186, v186, v182, 0x3fb5f0e3
	v_fmaak_f32 v187, v187, v183, 0x3fb5f0e3
	v_fmaak_f32 v184, v184, v180, 0xbe91a98e
	v_fmaak_f32 v185, v185, v181, 0xbe91a98e
	v_fmaak_f32 v186, v186, v182, 0xbe91a98e
	v_fmaak_f32 v187, v187, v183, 0xbe91a98e
	v_fmaak_f32 v184, v184, v180, 0x3e827906
	v_fmaak_f32 v185, v185, v181, 0x3e827906
	v_fmaak_f32 v186, v186, v182, 0x3e827906
	v_fmaak_f32 v187, v187, v183, 0x3e827906
	v_mul_f32_e32 v180, v180, v184
	v_mul_f32_e32 v181, v181, v185
	v_mul_f32_e32 v182, v182, v186
	v_mul_f32_e32 v183, v183, v187
	v_mul_f32_e64 v184, |v176|, |v176|
	v_mul_f32_e64 v185, |v177|, |v177|
	v_mul_f32_e64 v186, |v178|, |v178|
	v_mul_f32_e64 v187, |v179|, |v179|
	v_mul_f32_e32 v184, 0xbfb8aa3b, v184
	v_mul_f32_e32 v185, 0xbfb8aa3b, v185
	v_mul_f32_e32 v186, 0xbfb8aa3b, v186
	v_mul_f32_e32 v187, 0xbfb8aa3b, v187
	v_exp_f32_e32 v184, v184
	v_exp_f32_e32 v185, v185
	v_exp_f32_e32 v186, v186
	v_exp_f32_e32 v187, v187
	v_fma_f32 v180, -v184, v180, 1.0
	v_fma_f32 v181, -v185, v181, 1.0
	v_fma_f32 v182, -v186, v182, 1.0
	v_fma_f32 v183, -v187, v183, 1.0
	v_bfi_b32 v176, s10, v180, v176
	v_bfi_b32 v177, s10, v181, v177
	v_bfi_b32 v178, s10, v182, v178
	v_bfi_b32 v179, s10, v183, v179
	v_add_f32_e32 v176, 1.0, v176
	v_add_f32_e32 v177, 1.0, v177
	v_add_f32_e32 v178, 1.0, v178
	v_add_f32_e32 v179, 1.0, v179
	v_mul_f32_e32 v188, v188, v176
	v_mul_f32_e32 v189, v189, v177
	v_mul_f32_e32 v190, v190, v178
	v_mul_f32_e32 v191, v191, v179
	v_cvt_pk_bf16_f32 v144, v188, v189
	v_cvt_pk_bf16_f32 v145, v190, v191
	v_mul_f32_e32 v176, 0x3f3504f3, v42
	v_mul_f32_e32 v177, 0x3f3504f3, v43
	v_mul_f32_e32 v178, 0x3f3504f3, v44
	v_mul_f32_e32 v179, 0x3f3504f3, v45
	v_fma_f32 v180, |v176|, s9, 1.0
	v_fma_f32 v181, |v177|, s9, 1.0
	v_fma_f32 v182, |v178|, s9, 1.0
	v_fma_f32 v183, |v179|, s9, 1.0
	v_rcp_f32_e32 v180, v180
	v_rcp_f32_e32 v181, v181
	v_rcp_f32_e32 v182, v182
	v_rcp_f32_e32 v183, v183
	v_mul_f32_e32 v188, 0.5, v42
	v_mul_f32_e32 v189, 0.5, v43
	v_mul_f32_e32 v190, 0.5, v44
	v_mul_f32_e32 v191, 0.5, v45
	v_fmamk_f32 v184, v180, 0x3f87dc22, v206
	v_fmamk_f32 v185, v181, 0x3f87dc22, v206
	v_fmamk_f32 v186, v182, 0x3f87dc22, v206
	v_fmamk_f32 v187, v183, 0x3f87dc22, v206
	v_fmaak_f32 v184, v184, v180, 0x3fb5f0e3
	v_fmaak_f32 v185, v185, v181, 0x3fb5f0e3
	v_fmaak_f32 v186, v186, v182, 0x3fb5f0e3
	v_fmaak_f32 v187, v187, v183, 0x3fb5f0e3
	v_fmaak_f32 v184, v184, v180, 0xbe91a98e
	v_fmaak_f32 v185, v185, v181, 0xbe91a98e
	v_fmaak_f32 v186, v186, v182, 0xbe91a98e
	v_fmaak_f32 v187, v187, v183, 0xbe91a98e
	v_fmaak_f32 v184, v184, v180, 0x3e827906
	v_fmaak_f32 v185, v185, v181, 0x3e827906
	v_fmaak_f32 v186, v186, v182, 0x3e827906
	v_fmaak_f32 v187, v187, v183, 0x3e827906
	v_mul_f32_e32 v180, v180, v184
	v_mul_f32_e32 v181, v181, v185
	v_mul_f32_e32 v182, v182, v186
	v_mul_f32_e32 v183, v183, v187
	v_mul_f32_e64 v184, |v176|, |v176|
	v_mul_f32_e64 v185, |v177|, |v177|
	v_mul_f32_e64 v186, |v178|, |v178|
	v_mul_f32_e64 v187, |v179|, |v179|
	v_mul_f32_e32 v184, 0xbfb8aa3b, v184
	v_mul_f32_e32 v185, 0xbfb8aa3b, v185
	v_mul_f32_e32 v186, 0xbfb8aa3b, v186
	v_mul_f32_e32 v187, 0xbfb8aa3b, v187
	v_exp_f32_e32 v184, v184
	v_exp_f32_e32 v185, v185
	v_exp_f32_e32 v186, v186
	v_exp_f32_e32 v187, v187
	v_fma_f32 v180, -v184, v180, 1.0
	v_fma_f32 v181, -v185, v181, 1.0
	v_fma_f32 v182, -v186, v182, 1.0
	v_fma_f32 v183, -v187, v183, 1.0
	v_bfi_b32 v176, s10, v180, v176
	v_bfi_b32 v177, s10, v181, v177
	v_bfi_b32 v178, s10, v182, v178
	v_bfi_b32 v179, s10, v183, v179
	v_add_f32_e32 v176, 1.0, v176
	v_add_f32_e32 v177, 1.0, v177
	v_add_f32_e32 v178, 1.0, v178
	v_add_f32_e32 v179, 1.0, v179
	v_mul_f32_e32 v188, v188, v176
	v_mul_f32_e32 v189, v189, v177
	v_mul_f32_e32 v190, v190, v178
	v_mul_f32_e32 v191, v191, v179
	v_cvt_pk_bf16_f32 v146, v188, v189
	v_cvt_pk_bf16_f32 v147, v190, v191
	s_nop 1
	v_permlane16_swap_b32_e32 v140, v142
	v_permlane16_swap_b32_e32 v141, v143
	global_store_dwordx4 v[170:171], v[140:143], off
	v_mul_f32_e32 v176, 0x3f3504f3, v38
	v_mul_f32_e32 v177, 0x3f3504f3, v39
	v_mul_f32_e32 v178, 0x3f3504f3, v40
	v_mul_f32_e32 v179, 0x3f3504f3, v41
	v_fma_f32 v180, |v176|, s9, 1.0
	v_fma_f32 v181, |v177|, s9, 1.0
	v_fma_f32 v182, |v178|, s9, 1.0
	v_fma_f32 v183, |v179|, s9, 1.0
	v_rcp_f32_e32 v180, v180
	v_rcp_f32_e32 v181, v181
	v_rcp_f32_e32 v182, v182
	v_rcp_f32_e32 v183, v183
	v_mul_f32_e32 v188, 0.5, v38
	v_mul_f32_e32 v189, 0.5, v39
	v_mul_f32_e32 v190, 0.5, v40
	v_mul_f32_e32 v191, 0.5, v41
	v_fmamk_f32 v184, v180, 0x3f87dc22, v206
	v_fmamk_f32 v185, v181, 0x3f87dc22, v206
	v_fmamk_f32 v186, v182, 0x3f87dc22, v206
	v_fmamk_f32 v187, v183, 0x3f87dc22, v206
	v_fmaak_f32 v184, v184, v180, 0x3fb5f0e3
	v_fmaak_f32 v185, v185, v181, 0x3fb5f0e3
	v_fmaak_f32 v186, v186, v182, 0x3fb5f0e3
	v_fmaak_f32 v187, v187, v183, 0x3fb5f0e3
	v_fmaak_f32 v184, v184, v180, 0xbe91a98e
	v_fmaak_f32 v185, v185, v181, 0xbe91a98e
	v_fmaak_f32 v186, v186, v182, 0xbe91a98e
	v_fmaak_f32 v187, v187, v183, 0xbe91a98e
	v_fmaak_f32 v184, v184, v180, 0x3e827906
	v_fmaak_f32 v185, v185, v181, 0x3e827906
	v_fmaak_f32 v186, v186, v182, 0x3e827906
	v_fmaak_f32 v187, v187, v183, 0x3e827906
	v_mul_f32_e32 v180, v180, v184
	v_mul_f32_e32 v181, v181, v185
; __device__ __forceinline__ unsigned pack2(float a, float b) { const f32x2_t v = {a, b}; const bf16x2_t r = __builtin_convertvector(v, bf16x2_t); return __builtin_bit_cast(unsigned, r); }
; __device__ __forceinline__ float erf_fast(float x) {
;   const float ax = fabsf(x);
;   const float t = __builtin_amdgcn_rcpf(fmaf(0.3275911f, ax, 1.f));
;   float y = fmaf(1.061405429f, t, -1.453152027f);
;   y = fmaf(y, t, 1.421413741f);
;   y = fmaf(y, t, -0.284496736f);
;   y = fmaf(y, t, 0.254829592f);
;   y = 1.f - y * t * __expf(-ax * ax);
;   return copysignf(y, x);
; }
; __device__ __forceinline__ void ph_proj(const Params& p, int l, char* shm) {
;     ...
;           else if (act == 2) xv = 0.5f * xv * (1.f + erf_fast(xv * 0.70710678118654752f));
;           y[j] = xv;
;         }
;         *(uint2*)(p.P + (size_t)(brow + r) * NP + pn * 256 + c) = uint2{pack2(y[0], y[1]), pack2(y[2], y[3])};
	v_mul_f32_e32 v182, v182, v186
	v_mul_f32_e32 v183, v183, v187
	v_mul_f32_e64 v184, |v176|, |v176|
	v_mul_f32_e64 v185, |v177|, |v177|
	v_mul_f32_e64 v186, |v178|, |v178|
	v_mul_f32_e64 v187, |v179|, |v179|
	v_mul_f32_e32 v184, 0xbfb8aa3b, v184
	v_mul_f32_e32 v185, 0xbfb8aa3b, v185
	v_mul_f32_e32 v186, 0xbfb8aa3b, v186
	v_mul_f32_e32 v187, 0xbfb8aa3b, v187
	v_exp_f32_e32 v184, v184
	v_exp_f32_e32 v185, v185
	v_exp_f32_e32 v186, v186
	v_exp_f32_e32 v187, v187
	v_fma_f32 v180, -v184, v180, 1.0
	v_fma_f32 v181, -v185, v181, 1.0
	v_fma_f32 v182, -v186, v182, 1.0
	v_fma_f32 v183, -v187, v183, 1.0
	v_bfi_b32 v176, s10, v180, v176
	v_bfi_b32 v177, s10, v181, v177
	v_bfi_b32 v178, s10, v182, v178
	v_bfi_b32 v179, s10, v183, v179
	v_add_f32_e32 v176, 1.0, v176
	v_add_f32_e32 v177, 1.0, v177
	v_add_f32_e32 v178, 1.0, v178
	v_add_f32_e32 v179, 1.0, v179
	v_mul_f32_e32 v188, v188, v176
	v_mul_f32_e32 v189, v189, v177
	v_mul_f32_e32 v190, v190, v178
	v_mul_f32_e32 v191, v191, v179
	v_cvt_pk_bf16_f32 v148, v188, v189
	v_cvt_pk_bf16_f32 v149, v190, v191
	v_mul_f32_e32 v176, 0x3f3504f3, v34
	v_mul_f32_e32 v177, 0x3f3504f3, v35
	v_mul_f32_e32 v178, 0x3f3504f3, v36
	v_mul_f32_e32 v179, 0x3f3504f3, v37
	v_fma_f32 v180, |v176|, s9, 1.0
	v_fma_f32 v181, |v177|, s9, 1.0
	v_fma_f32 v182, |v178|, s9, 1.0
	v_fma_f32 v183, |v179|, s9, 1.0
	v_rcp_f32_e32 v180, v180
	v_rcp_f32_e32 v181, v181
	v_rcp_f32_e32 v182, v182
	v_rcp_f32_e32 v183, v183
	v_mul_f32_e32 v188, 0.5, v34
	v_mul_f32_e32 v189, 0.5, v35
	v_mul_f32_e32 v190, 0.5, v36
	v_mul_f32_e32 v191, 0.5, v37
	v_fmamk_f32 v184, v180, 0x3f87dc22, v206
	v_fmamk_f32 v185, v181, 0x3f87dc22, v206
	v_fmamk_f32 v186, v182, 0x3f87dc22, v206
	v_fmamk_f32 v187, v183, 0x3f87dc22, v206
	v_fmaak_f32 v184, v184, v180, 0x3fb5f0e3
	v_fmaak_f32 v185, v185, v181, 0x3fb5f0e3
	v_fmaak_f32 v186, v186, v182, 0x3fb5f0e3
	v_fmaak_f32 v187, v187, v183, 0x3fb5f0e3
	v_fmaak_f32 v184, v184, v180, 0xbe91a98e
	v_fmaak_f32 v185, v185, v181, 0xbe91a98e
	v_fmaak_f32 v186, v186, v182, 0xbe91a98e
	v_fmaak_f32 v187, v187, v183, 0xbe91a98e
	v_fmaak_f32 v184, v184, v180, 0x3e827906
	v_fmaak_f32 v185, v185, v181, 0x3e827906
	v_fmaak_f32 v186, v186, v182, 0x3e827906
	v_fmaak_f32 v187, v187, v183, 0x3e827906
	v_mul_f32_e32 v180, v180, v184
	v_mul_f32_e32 v181, v181, v185
	v_mul_f32_e32 v182, v182, v186
	v_mul_f32_e32 v183, v183, v187
	v_mul_f32_e64 v184, |v176|, |v176|
	v_mul_f32_e64 v185, |v177|, |v177|
	v_mul_f32_e64 v186, |v178|, |v178|
	v_mul_f32_e64 v187, |v179|, |v179|
	v_mul_f32_e32 v184, 0xbfb8aa3b, v184
	v_mul_f32_e32 v185, 0xbfb8aa3b, v185
	v_mul_f32_e32 v186, 0xbfb8aa3b, v186
	v_mul_f32_e32 v187, 0xbfb8aa3b, v187
	v_exp_f32_e32 v184, v184
	v_exp_f32_e32 v185, v185
	v_exp_f32_e32 v186, v186
	v_exp_f32_e32 v187, v187
	v_fma_f32 v180, -v184, v180, 1.0
	v_fma_f32 v181, -v185, v181, 1.0
	v_fma_f32 v182, -v186, v182, 1.0
	v_fma_f32 v183, -v187, v183, 1.0
	v_bfi_b32 v176, s10, v180, v176
	v_bfi_b32 v177, s10, v181, v177
	v_bfi_b32 v178, s10, v182, v178
	v_bfi_b32 v179, s10, v183, v179
	v_add_f32_e32 v176, 1.0, v176
	v_add_f32_e32 v177, 1.0, v177
	v_add_f32_e32 v178, 1.0, v178
	v_add_f32_e32 v179, 1.0, v179
	v_mul_f32_e32 v188, v188, v176
	v_mul_f32_e32 v189, v189, v177
	v_mul_f32_e32 v190, v190, v178
	v_mul_f32_e32 v191, v191, v179
	v_cvt_pk_bf16_f32 v150, v188, v189
	v_cvt_pk_bf16_f32 v151, v190, v191
	s_nop 1
	v_permlane16_swap_b32_e32 v144, v146
	v_permlane16_swap_b32_e32 v145, v147
	global_store_dwordx4 v[172:173], v[144:147], off
	v_mul_f32_e32 v176, 0x3f3504f3, v28
	v_mul_f32_e32 v177, 0x3f3504f3, v29
	v_mul_f32_e32 v178, 0x3f3504f3, v30
	v_mul_f32_e32 v179, 0x3f3504f3, v31
	v_fma_f32 v180, |v176|, s9, 1.0
	v_fma_f32 v181, |v177|, s9, 1.0
	v_fma_f32 v182, |v178|, s9, 1.0
	v_fma_f32 v183, |v179|, s9, 1.0
	v_rcp_f32_e32 v180, v180
	v_rcp_f32_e32 v181, v181
	v_rcp_f32_e32 v182, v182
	v_rcp_f32_e32 v183, v183
	v_mul_f32_e32 v188, 0.5, v28
	v_mul_f32_e32 v189, 0.5, v29
	v_mul_f32_e32 v190, 0.5, v30
	v_mul_f32_e32 v191, 0.5, v31
	v_fmamk_f32 v184, v180, 0x3f87dc22, v206
	v_fmamk_f32 v185, v181, 0x3f87dc22, v206
	v_fmamk_f32 v186, v182, 0x3f87dc22, v206
	v_fmamk_f32 v187, v183, 0x3f87dc22, v206
	v_fmaak_f32 v184, v184, v180, 0x3fb5f0e3
	v_fmaak_f32 v185, v185, v181, 0x3fb5f0e3
	v_fmaak_f32 v186, v186, v182, 0x3fb5f0e3
	v_fmaak_f32 v187, v187, v183, 0x3fb5f0e3
	v_fmaak_f32 v184, v184, v180, 0xbe91a98e
	v_fmaak_f32 v185, v185, v181, 0xbe91a98e
	v_fmaak_f32 v186, v186, v182, 0xbe91a98e
	v_fmaak_f32 v187, v187, v183, 0xbe91a98e
	v_fmaak_f32 v184, v184, v180, 0x3e827906
	v_fmaak_f32 v185, v185, v181, 0x3e827906
	v_fmaak_f32 v186, v186, v182, 0x3e827906
	v_fmaak_f32 v187, v187, v183, 0x3e827906
	v_mul_f32_e32 v180, v180, v184
	v_mul_f32_e32 v181, v181, v185
	v_mul_f32_e32 v182, v182, v186
	v_mul_f32_e32 v183, v183, v187
	v_mul_f32_e64 v184, |v176|, |v176|
	v_mul_f32_e64 v185, |v177|, |v177|
	v_mul_f32_e64 v186, |v178|, |v178|
	v_mul_f32_e64 v187, |v179|, |v179|
	v_mul_f32_e32 v184, 0xbfb8aa3b, v184
	v_mul_f32_e32 v185, 0xbfb8aa3b, v185
	v_mul_f32_e32 v186, 0xbfb8aa3b, v186
	v_mul_f32_e32 v187, 0xbfb8aa3b, v187
	v_exp_f32_e32 v184, v184
	v_exp_f32_e32 v185, v185
	v_exp_f32_e32 v186, v186
	v_exp_f32_e32 v187, v187
	v_fma_f32 v180, -v184, v180, 1.0
	v_fma_f32 v181, -v185, v181, 1.0
	v_fma_f32 v182, -v186, v182, 1.0
	v_fma_f32 v183, -v187, v183, 1.0
	v_bfi_b32 v176, s10, v180, v176
	v_bfi_b32 v177, s10, v181, v177
	v_bfi_b32 v178, s10, v182, v178
	v_bfi_b32 v179, s10, v183, v179
	v_add_f32_e32 v176, 1.0, v176
	v_add_f32_e32 v177, 1.0, v177
	v_add_f32_e32 v178, 1.0, v178
	v_add_f32_e32 v179, 1.0, v179
	v_mul_f32_e32 v188, v188, v176
	v_mul_f32_e32 v189, v189, v177
; __device__ __forceinline__ unsigned pack2(float a, float b) { const f32x2_t v = {a, b}; const bf16x2_t r = __builtin_convertvector(v, bf16x2_t); return __builtin_bit_cast(unsigned, r); }
; __device__ __forceinline__ float erf_fast(float x) {
;   const float ax = fabsf(x);
;   const float t = __builtin_amdgcn_rcpf(fmaf(0.3275911f, ax, 1.f));
;   float y = fmaf(1.061405429f, t, -1.453152027f);
;   y = fmaf(y, t, 1.421413741f);
;   y = fmaf(y, t, -0.284496736f);
;   y = fmaf(y, t, 0.254829592f);
;   y = 1.f - y * t * __expf(-ax * ax);
;   return copysignf(y, x);
; }
; __device__ __forceinline__ void ph_proj(const Params& p, int l, char* shm) {
;     ...
;           else if (act == 2) xv = 0.5f * xv * (1.f + erf_fast(xv * 0.70710678118654752f));
;           y[j] = xv;
;         }
;         *(uint2*)(p.P + (size_t)(brow + r) * NP + pn * 256 + c) = uint2{pack2(y[0], y[1]), pack2(y[2], y[3])};
	v_mul_f32_e32 v190, v190, v178
	v_mul_f32_e32 v191, v191, v179
	v_cvt_pk_bf16_f32 v140, v188, v189
	v_cvt_pk_bf16_f32 v141, v190, v191
	v_mul_f32_e32 v176, 0x3f3504f3, v24
	v_mul_f32_e32 v177, 0x3f3504f3, v25
	v_mul_f32_e32 v178, 0x3f3504f3, v26
	v_mul_f32_e32 v179, 0x3f3504f3, v27
	v_fma_f32 v180, |v176|, s9, 1.0
	v_fma_f32 v181, |v177|, s9, 1.0
	v_fma_f32 v182, |v178|, s9, 1.0
	v_fma_f32 v183, |v179|, s9, 1.0
	v_rcp_f32_e32 v180, v180
	v_rcp_f32_e32 v181, v181
	v_rcp_f32_e32 v182, v182
	v_rcp_f32_e32 v183, v183
	v_mul_f32_e32 v188, 0.5, v24
	v_mul_f32_e32 v189, 0.5, v25
	v_mul_f32_e32 v190, 0.5, v26
	v_mul_f32_e32 v191, 0.5, v27
	v_fmamk_f32 v184, v180, 0x3f87dc22, v206
	v_fmamk_f32 v185, v181, 0x3f87dc22, v206
	v_fmamk_f32 v186, v182, 0x3f87dc22, v206
	v_fmamk_f32 v187, v183, 0x3f87dc22, v206
	v_fmaak_f32 v184, v184, v180, 0x3fb5f0e3
	v_fmaak_f32 v185, v185, v181, 0x3fb5f0e3
	v_fmaak_f32 v186, v186, v182, 0x3fb5f0e3
	v_fmaak_f32 v187, v187, v183, 0x3fb5f0e3
	v_fmaak_f32 v184, v184, v180, 0xbe91a98e
	v_fmaak_f32 v185, v185, v181, 0xbe91a98e
	v_fmaak_f32 v186, v186, v182, 0xbe91a98e
	v_fmaak_f32 v187, v187, v183, 0xbe91a98e
	v_fmaak_f32 v184, v184, v180, 0x3e827906
	v_fmaak_f32 v185, v185, v181, 0x3e827906
	v_fmaak_f32 v186, v186, v182, 0x3e827906
	v_fmaak_f32 v187, v187, v183, 0x3e827906
	v_mul_f32_e32 v180, v180, v184
	v_mul_f32_e32 v181, v181, v185
	v_mul_f32_e32 v182, v182, v186
	v_mul_f32_e32 v183, v183, v187
	v_mul_f32_e64 v184, |v176|, |v176|
	v_mul_f32_e64 v185, |v177|, |v177|
	v_mul_f32_e64 v186, |v178|, |v178|
	v_mul_f32_e64 v187, |v179|, |v179|
	v_mul_f32_e32 v184, 0xbfb8aa3b, v184
	v_mul_f32_e32 v185, 0xbfb8aa3b, v185
	v_mul_f32_e32 v186, 0xbfb8aa3b, v186
	v_mul_f32_e32 v187, 0xbfb8aa3b, v187
	v_exp_f32_e32 v184, v184
	v_exp_f32_e32 v185, v185
	v_exp_f32_e32 v186, v186
	v_exp_f32_e32 v187, v187
	v_fma_f32 v180, -v184, v180, 1.0
	v_fma_f32 v181, -v185, v181, 1.0
	v_fma_f32 v182, -v186, v182, 1.0
	v_fma_f32 v183, -v187, v183, 1.0
	v_bfi_b32 v176, s10, v180, v176
	v_bfi_b32 v177, s10, v181, v177
	v_bfi_b32 v178, s10, v182, v178
	v_bfi_b32 v179, s10, v183, v179
	v_add_f32_e32 v176, 1.0, v176
	v_add_f32_e32 v177, 1.0, v177
	v_add_f32_e32 v178, 1.0, v178
	v_add_f32_e32 v179, 1.0, v179
	v_mul_f32_e32 v188, v188, v176
	v_mul_f32_e32 v189, v189, v177
	v_mul_f32_e32 v190, v190, v178
	v_mul_f32_e32 v191, v191, v179
	v_cvt_pk_bf16_f32 v142, v188, v189
	v_cvt_pk_bf16_f32 v143, v190, v191
	s_nop 1
	v_permlane16_swap_b32_e32 v148, v150
	v_permlane16_swap_b32_e32 v149, v151
	global_store_dwordx4 v[174:175], v[148:151], off
	v_mul_f32_e32 v176, 0x3f3504f3, v20
	v_mul_f32_e32 v177, 0x3f3504f3, v21
	v_mul_f32_e32 v178, 0x3f3504f3, v22
	v_mul_f32_e32 v179, 0x3f3504f3, v23
	v_fma_f32 v180, |v176|, s9, 1.0
	v_fma_f32 v181, |v177|, s9, 1.0
	v_fma_f32 v182, |v178|, s9, 1.0
	v_fma_f32 v183, |v179|, s9, 1.0
	v_rcp_f32_e32 v180, v180
	v_rcp_f32_e32 v181, v181
	v_rcp_f32_e32 v182, v182
	v_rcp_f32_e32 v183, v183
	v_mul_f32_e32 v188, 0.5, v20
	v_mul_f32_e32 v189, 0.5, v21
	v_mul_f32_e32 v190, 0.5, v22
	v_mul_f32_e32 v191, 0.5, v23
	v_fmamk_f32 v184, v180, 0x3f87dc22, v206
	v_fmamk_f32 v185, v181, 0x3f87dc22, v206
	v_fmamk_f32 v186, v182, 0x3f87dc22, v206
	v_fmamk_f32 v187, v183, 0x3f87dc22, v206
	v_fmaak_f32 v184, v184, v180, 0x3fb5f0e3
	v_fmaak_f32 v185, v185, v181, 0x3fb5f0e3
	v_fmaak_f32 v186, v186, v182, 0x3fb5f0e3
	v_fmaak_f32 v187, v187, v183, 0x3fb5f0e3
	v_fmaak_f32 v184, v184, v180, 0xbe91a98e
	v_fmaak_f32 v185, v185, v181, 0xbe91a98e
	v_fmaak_f32 v186, v186, v182, 0xbe91a98e
	v_fmaak_f32 v187, v187, v183, 0xbe91a98e
	v_fmaak_f32 v184, v184, v180, 0x3e827906
	v_fmaak_f32 v185, v185, v181, 0x3e827906
	v_fmaak_f32 v186, v186, v182, 0x3e827906
	v_fmaak_f32 v187, v187, v183, 0x3e827906
	v_mul_f32_e32 v180, v180, v184
	v_mul_f32_e32 v181, v181, v185
	v_mul_f32_e32 v182, v182, v186
	v_mul_f32_e32 v183, v183, v187
	v_mul_f32_e64 v184, |v176|, |v176|
	v_mul_f32_e64 v185, |v177|, |v177|
	v_mul_f32_e64 v186, |v178|, |v178|
	v_mul_f32_e64 v187, |v179|, |v179|
	v_mul_f32_e32 v184, 0xbfb8aa3b, v184
	v_mul_f32_e32 v185, 0xbfb8aa3b, v185
	v_mul_f32_e32 v186, 0xbfb8aa3b, v186
	v_mul_f32_e32 v187, 0xbfb8aa3b, v187
	v_exp_f32_e32 v184, v184
	v_exp_f32_e32 v185, v185
	v_exp_f32_e32 v186, v186
	v_exp_f32_e32 v187, v187
	v_fma_f32 v180, -v184, v180, 1.0
	v_fma_f32 v181, -v185, v181, 1.0
	v_fma_f32 v182, -v186, v182, 1.0
	v_fma_f32 v183, -v187, v183, 1.0
	v_bfi_b32 v176, s10, v180, v176
	v_bfi_b32 v177, s10, v181, v177
	v_bfi_b32 v178, s10, v182, v178
	v_bfi_b32 v179, s10, v183, v179
	v_add_f32_e32 v176, 1.0, v176
	v_add_f32_e32 v177, 1.0, v177
	v_add_f32_e32 v178, 1.0, v178
	v_add_f32_e32 v179, 1.0, v179
	v_mul_f32_e32 v188, v188, v176
	v_mul_f32_e32 v189, v189, v177
	v_mul_f32_e32 v190, v190, v178
	v_mul_f32_e32 v191, v191, v179
	v_cvt_pk_bf16_f32 v144, v188, v189
	v_cvt_pk_bf16_f32 v145, v190, v191
	v_mul_f32_e32 v176, 0x3f3504f3, v16
	v_mul_f32_e32 v177, 0x3f3504f3, v17
	v_mul_f32_e32 v178, 0x3f3504f3, v18
	v_mul_f32_e32 v179, 0x3f3504f3, v19
	v_fma_f32 v180, |v176|, s9, 1.0
	v_fma_f32 v181, |v177|, s9, 1.0
	v_fma_f32 v182, |v178|, s9, 1.0
	v_fma_f32 v183, |v179|, s9, 1.0
	v_rcp_f32_e32 v180, v180
	v_rcp_f32_e32 v181, v181
	v_rcp_f32_e32 v182, v182
	v_rcp_f32_e32 v183, v183
	v_mul_f32_e32 v188, 0.5, v16
	v_mul_f32_e32 v189, 0.5, v17
	v_mul_f32_e32 v190, 0.5, v18
	v_mul_f32_e32 v191, 0.5, v19
	v_fmamk_f32 v184, v180, 0x3f87dc22, v206
	v_fmamk_f32 v185, v181, 0x3f87dc22, v206
	v_fmamk_f32 v186, v182, 0x3f87dc22, v206
	v_fmamk_f32 v187, v183, 0x3f87dc22, v206
	v_fmaak_f32 v184, v184, v180, 0x3fb5f0e3
	v_fmaak_f32 v185, v185, v181, 0x3fb5f0e3
; __device__ __forceinline__ unsigned pack2(float a, float b) { const f32x2_t v = {a, b}; const bf16x2_t r = __builtin_convertvector(v, bf16x2_t); return __builtin_bit_cast(unsigned, r); }
; __device__ __forceinline__ float erf_fast(float x) {
;   const float ax = fabsf(x);
;   const float t = __builtin_amdgcn_rcpf(fmaf(0.3275911f, ax, 1.f));
;   float y = fmaf(1.061405429f, t, -1.453152027f);
;   y = fmaf(y, t, 1.421413741f);
;   y = fmaf(y, t, -0.284496736f);
;   y = fmaf(y, t, 0.254829592f);
;   y = 1.f - y * t * __expf(-ax * ax);
;   return copysignf(y, x);
; }
; __device__ __forceinline__ void ph_proj(const Params& p, int l, char* shm) {
;     ...
;           else if (act == 2) xv = 0.5f * xv * (1.f + erf_fast(xv * 0.70710678118654752f));
;           y[j] = xv;
;         }
;         *(uint2*)(p.P + (size_t)(brow + r) * NP + pn * 256 + c) = uint2{pack2(y[0], y[1]), pack2(y[2], y[3])};
	v_fmaak_f32 v186, v186, v182, 0x3fb5f0e3
	v_fmaak_f32 v187, v187, v183, 0x3fb5f0e3
	v_fmaak_f32 v184, v184, v180, 0xbe91a98e
	v_fmaak_f32 v185, v185, v181, 0xbe91a98e
	v_fmaak_f32 v186, v186, v182, 0xbe91a98e
	v_fmaak_f32 v187, v187, v183, 0xbe91a98e
	v_fmaak_f32 v184, v184, v180, 0x3e827906
	v_fmaak_f32 v185, v185, v181, 0x3e827906
	v_fmaak_f32 v186, v186, v182, 0x3e827906
	v_fmaak_f32 v187, v187, v183, 0x3e827906
	v_mul_f32_e32 v180, v180, v184
	v_mul_f32_e32 v181, v181, v185
	v_mul_f32_e32 v182, v182, v186
	v_mul_f32_e32 v183, v183, v187
	v_mul_f32_e64 v184, |v176|, |v176|
	v_mul_f32_e64 v185, |v177|, |v177|
	v_mul_f32_e64 v186, |v178|, |v178|
	v_mul_f32_e64 v187, |v179|, |v179|
	v_mul_f32_e32 v184, 0xbfb8aa3b, v184
	v_mul_f32_e32 v185, 0xbfb8aa3b, v185
	v_mul_f32_e32 v186, 0xbfb8aa3b, v186
	v_mul_f32_e32 v187, 0xbfb8aa3b, v187
	v_exp_f32_e32 v184, v184
	v_exp_f32_e32 v185, v185
	v_exp_f32_e32 v186, v186
	v_exp_f32_e32 v187, v187
	v_fma_f32 v180, -v184, v180, 1.0
	v_fma_f32 v181, -v185, v181, 1.0
	v_fma_f32 v182, -v186, v182, 1.0
	v_fma_f32 v183, -v187, v183, 1.0
	v_bfi_b32 v176, s10, v180, v176
	v_bfi_b32 v177, s10, v181, v177
	v_bfi_b32 v178, s10, v182, v178
	v_bfi_b32 v179, s10, v183, v179
	v_add_f32_e32 v176, 1.0, v176
	v_add_f32_e32 v177, 1.0, v177
	v_add_f32_e32 v178, 1.0, v178
	v_add_f32_e32 v179, 1.0, v179
	v_mul_f32_e32 v188, v188, v176
	v_mul_f32_e32 v189, v189, v177
	v_mul_f32_e32 v190, v190, v178
	v_mul_f32_e32 v191, v191, v179
	v_cvt_pk_bf16_f32 v146, v188, v189
	v_cvt_pk_bf16_f32 v147, v190, v191
	s_nop 1
	v_permlane16_swap_b32_e32 v140, v142
	v_permlane16_swap_b32_e32 v141, v143
	global_store_dwordx4 v[168:169], v[140:143], off offset:256
	v_mul_f32_e32 v176, 0x3f3504f3, v12
	v_mul_f32_e32 v177, 0x3f3504f3, v13
	v_mul_f32_e32 v178, 0x3f3504f3, v14
	v_mul_f32_e32 v179, 0x3f3504f3, v15
	v_fma_f32 v180, |v176|, s9, 1.0
	v_fma_f32 v181, |v177|, s9, 1.0
	v_fma_f32 v182, |v178|, s9, 1.0
	v_fma_f32 v183, |v179|, s9, 1.0
	v_rcp_f32_e32 v180, v180
	v_rcp_f32_e32 v181, v181
	v_rcp_f32_e32 v182, v182
	v_rcp_f32_e32 v183, v183
	v_mul_f32_e32 v188, 0.5, v12
	v_mul_f32_e32 v189, 0.5, v13
	v_mul_f32_e32 v190, 0.5, v14
	v_mul_f32_e32 v191, 0.5, v15
	v_fmamk_f32 v184, v180, 0x3f87dc22, v206
	v_fmamk_f32 v185, v181, 0x3f87dc22, v206
	v_fmamk_f32 v186, v182, 0x3f87dc22, v206
	v_fmamk_f32 v187, v183, 0x3f87dc22, v206
	v_fmaak_f32 v184, v184, v180, 0x3fb5f0e3
	v_fmaak_f32 v185, v185, v181, 0x3fb5f0e3
	v_fmaak_f32 v186, v186, v182, 0x3fb5f0e3
	v_fmaak_f32 v187, v187, v183, 0x3fb5f0e3
	v_fmaak_f32 v184, v184, v180, 0xbe91a98e
	v_fmaak_f32 v185, v185, v181, 0xbe91a98e
	v_fmaak_f32 v186, v186, v182, 0xbe91a98e
	v_fmaak_f32 v187, v187, v183, 0xbe91a98e
	v_fmaak_f32 v184, v184, v180, 0x3e827906
	v_fmaak_f32 v185, v185, v181, 0x3e827906
	v_fmaak_f32 v186, v186, v182, 0x3e827906
	v_fmaak_f32 v187, v187, v183, 0x3e827906
	v_mul_f32_e32 v180, v180, v184
	v_mul_f32_e32 v181, v181, v185
	v_mul_f32_e32 v182, v182, v186
	v_mul_f32_e32 v183, v183, v187
	v_mul_f32_e64 v184, |v176|, |v176|
	v_mul_f32_e64 v185, |v177|, |v177|
	v_mul_f32_e64 v186, |v178|, |v178|
	v_mul_f32_e64 v187, |v179|, |v179|
	v_mul_f32_e32 v184, 0xbfb8aa3b, v184
	v_mul_f32_e32 v185, 0xbfb8aa3b, v185
	v_mul_f32_e32 v186, 0xbfb8aa3b, v186
	v_mul_f32_e32 v187, 0xbfb8aa3b, v187
	v_exp_f32_e32 v184, v184
	v_exp_f32_e32 v185, v185
	v_exp_f32_e32 v186, v186
	v_exp_f32_e32 v187, v187
	v_fma_f32 v180, -v184, v180, 1.0
	v_fma_f32 v181, -v185, v181, 1.0
	v_fma_f32 v182, -v186, v182, 1.0
	v_fma_f32 v183, -v187, v183, 1.0
	v_bfi_b32 v176, s10, v180, v176
	v_bfi_b32 v177, s10, v181, v177
	v_bfi_b32 v178, s10, v182, v178
	v_bfi_b32 v179, s10, v183, v179
	v_add_f32_e32 v176, 1.0, v176
	v_add_f32_e32 v177, 1.0, v177
	v_add_f32_e32 v178, 1.0, v178
	v_add_f32_e32 v179, 1.0, v179
	v_mul_f32_e32 v188, v188, v176
	v_mul_f32_e32 v189, v189, v177
	v_mul_f32_e32 v190, v190, v178
	v_mul_f32_e32 v191, v191, v179
	v_cvt_pk_bf16_f32 v148, v188, v189
	v_cvt_pk_bf16_f32 v149, v190, v191
	v_mul_f32_e32 v176, 0x3f3504f3, v8
	v_mul_f32_e32 v177, 0x3f3504f3, v9
	v_mul_f32_e32 v178, 0x3f3504f3, v10
	v_mul_f32_e32 v179, 0x3f3504f3, v11
	v_fma_f32 v180, |v176|, s9, 1.0
	v_fma_f32 v181, |v177|, s9, 1.0
	v_fma_f32 v182, |v178|, s9, 1.0
	v_fma_f32 v183, |v179|, s9, 1.0
	v_rcp_f32_e32 v180, v180
	v_rcp_f32_e32 v181, v181
	v_rcp_f32_e32 v182, v182
	v_rcp_f32_e32 v183, v183
	v_mul_f32_e32 v188, 0.5, v8
	v_mul_f32_e32 v189, 0.5, v9
	v_mul_f32_e32 v190, 0.5, v10
	v_mul_f32_e32 v191, 0.5, v11
	v_fmamk_f32 v184, v180, 0x3f87dc22, v206
	v_fmamk_f32 v185, v181, 0x3f87dc22, v206
	v_fmamk_f32 v186, v182, 0x3f87dc22, v206
	v_fmamk_f32 v187, v183, 0x3f87dc22, v206
	v_fmaak_f32 v184, v184, v180, 0x3fb5f0e3
	v_fmaak_f32 v185, v185, v181, 0x3fb5f0e3
	v_fmaak_f32 v186, v186, v182, 0x3fb5f0e3
	v_fmaak_f32 v187, v187, v183, 0x3fb5f0e3
	v_fmaak_f32 v184, v184, v180, 0xbe91a98e
	v_fmaak_f32 v185, v185, v181, 0xbe91a98e
	v_fmaak_f32 v186, v186, v182, 0xbe91a98e
	v_fmaak_f32 v187, v187, v183, 0xbe91a98e
	v_fmaak_f32 v184, v184, v180, 0x3e827906
	v_fmaak_f32 v185, v185, v181, 0x3e827906
	v_fmaak_f32 v186, v186, v182, 0x3e827906
	v_fmaak_f32 v187, v187, v183, 0x3e827906
	v_mul_f32_e32 v180, v180, v184
	v_mul_f32_e32 v181, v181, v185
	v_mul_f32_e32 v182, v182, v186
	v_mul_f32_e32 v183, v183, v187
	v_mul_f32_e64 v184, |v176|, |v176|
	v_mul_f32_e64 v185, |v177|, |v177|
	v_mul_f32_e64 v186, |v178|, |v178|
	v_mul_f32_e64 v187, |v179|, |v179|
	v_mul_f32_e32 v184, 0xbfb8aa3b, v184
	v_mul_f32_e32 v185, 0xbfb8aa3b, v185
	v_mul_f32_e32 v186, 0xbfb8aa3b, v186
	v_mul_f32_e32 v187, 0xbfb8aa3b, v187
	v_exp_f32_e32 v184, v184
	v_exp_f32_e32 v185, v185
; __device__ __forceinline__ unsigned pack2(float a, float b) { const f32x2_t v = {a, b}; const bf16x2_t r = __builtin_convertvector(v, bf16x2_t); return __builtin_bit_cast(unsigned, r); }
; __device__ __forceinline__ float erf_fast(float x) {
;   const float ax = fabsf(x);
;   const float t = __builtin_amdgcn_rcpf(fmaf(0.3275911f, ax, 1.f));
;   float y = fmaf(1.061405429f, t, -1.453152027f);
;   y = fmaf(y, t, 1.421413741f);
;   y = fmaf(y, t, -0.284496736f);
;   y = fmaf(y, t, 0.254829592f);
;   y = 1.f - y * t * __expf(-ax * ax);
;   return copysignf(y, x);
; }
; __device__ __forceinline__ void ph_proj(const Params& p, int l, char* shm) {
;     ...
;           else if (act == 2) xv = 0.5f * xv * (1.f + erf_fast(xv * 0.70710678118654752f));
;           y[j] = xv;
;         }
;         *(uint2*)(p.P + (size_t)(brow + r) * NP + pn * 256 + c) = uint2{pack2(y[0], y[1]), pack2(y[2], y[3])};
	v_exp_f32_e32 v186, v186
	v_exp_f32_e32 v187, v187
	v_fma_f32 v180, -v184, v180, 1.0
	v_fma_f32 v181, -v185, v181, 1.0
	v_fma_f32 v182, -v186, v182, 1.0
	v_fma_f32 v183, -v187, v183, 1.0
	v_bfi_b32 v176, s10, v180, v176
	v_bfi_b32 v177, s10, v181, v177
	v_bfi_b32 v178, s10, v182, v178
	v_bfi_b32 v179, s10, v183, v179
	v_add_f32_e32 v176, 1.0, v176
	v_add_f32_e32 v177, 1.0, v177
	v_add_f32_e32 v178, 1.0, v178
	v_add_f32_e32 v179, 1.0, v179
	v_mul_f32_e32 v188, v188, v176
	v_mul_f32_e32 v189, v189, v177
	v_mul_f32_e32 v190, v190, v178
	v_mul_f32_e32 v191, v191, v179
	v_cvt_pk_bf16_f32 v150, v188, v189
	v_cvt_pk_bf16_f32 v151, v190, v191
	s_nop 1
	v_permlane16_swap_b32_e32 v144, v146
	v_permlane16_swap_b32_e32 v145, v147
	global_store_dwordx4 v[170:171], v[144:147], off offset:256
	v_mul_f32_e32 v176, 0x3f3504f3, v4
	v_mul_f32_e32 v177, 0x3f3504f3, v5
	v_mul_f32_e32 v178, 0x3f3504f3, v6
	v_mul_f32_e32 v179, 0x3f3504f3, v7
	v_fma_f32 v180, |v176|, s9, 1.0
	v_fma_f32 v181, |v177|, s9, 1.0
	v_fma_f32 v182, |v178|, s9, 1.0
	v_fma_f32 v183, |v179|, s9, 1.0
	v_rcp_f32_e32 v180, v180
	v_rcp_f32_e32 v181, v181
	v_rcp_f32_e32 v182, v182
	v_rcp_f32_e32 v183, v183
	v_mul_f32_e32 v188, 0.5, v4
	v_mul_f32_e32 v189, 0.5, v5
	v_mul_f32_e32 v190, 0.5, v6
	v_mul_f32_e32 v191, 0.5, v7
	v_fmamk_f32 v184, v180, 0x3f87dc22, v206
	v_fmamk_f32 v185, v181, 0x3f87dc22, v206
	v_fmamk_f32 v186, v182, 0x3f87dc22, v206
	v_fmamk_f32 v187, v183, 0x3f87dc22, v206
	v_fmaak_f32 v184, v184, v180, 0x3fb5f0e3
	v_fmaak_f32 v185, v185, v181, 0x3fb5f0e3
	v_fmaak_f32 v186, v186, v182, 0x3fb5f0e3
	v_fmaak_f32 v187, v187, v183, 0x3fb5f0e3
	v_fmaak_f32 v184, v184, v180, 0xbe91a98e
	v_fmaak_f32 v185, v185, v181, 0xbe91a98e
	v_fmaak_f32 v186, v186, v182, 0xbe91a98e
	v_fmaak_f32 v187, v187, v183, 0xbe91a98e
	v_fmaak_f32 v184, v184, v180, 0x3e827906
	v_fmaak_f32 v185, v185, v181, 0x3e827906
	v_fmaak_f32 v186, v186, v182, 0x3e827906
	v_fmaak_f32 v187, v187, v183, 0x3e827906
	v_mul_f32_e32 v180, v180, v184
	v_mul_f32_e32 v181, v181, v185
	v_mul_f32_e32 v182, v182, v186
	v_mul_f32_e32 v183, v183, v187
	v_mul_f32_e64 v184, |v176|, |v176|
	v_mul_f32_e64 v185, |v177|, |v177|
	v_mul_f32_e64 v186, |v178|, |v178|
	v_mul_f32_e64 v187, |v179|, |v179|
	v_mul_f32_e32 v184, 0xbfb8aa3b, v184
	v_mul_f32_e32 v185, 0xbfb8aa3b, v185
	v_mul_f32_e32 v186, 0xbfb8aa3b, v186
	v_mul_f32_e32 v187, 0xbfb8aa3b, v187
	v_exp_f32_e32 v184, v184
	v_exp_f32_e32 v185, v185
	v_exp_f32_e32 v186, v186
	v_exp_f32_e32 v187, v187
	v_fma_f32 v180, -v184, v180, 1.0
	v_fma_f32 v181, -v185, v181, 1.0
	v_fma_f32 v182, -v186, v182, 1.0
	v_fma_f32 v183, -v187, v183, 1.0
	v_bfi_b32 v176, s10, v180, v176
	v_bfi_b32 v177, s10, v181, v177
	v_bfi_b32 v178, s10, v182, v178
	v_bfi_b32 v179, s10, v183, v179
	v_add_f32_e32 v176, 1.0, v176
	v_add_f32_e32 v177, 1.0, v177
	v_add_f32_e32 v178, 1.0, v178
	v_add_f32_e32 v179, 1.0, v179
	v_mul_f32_e32 v188, v188, v176
	v_mul_f32_e32 v189, v189, v177
	v_mul_f32_e32 v190, v190, v178
	v_mul_f32_e32 v191, v191, v179
	v_cvt_pk_bf16_f32 v140, v188, v189
	v_cvt_pk_bf16_f32 v141, v190, v191
	v_mul_f32_e32 v176, 0x3f3504f3, v0
	v_mul_f32_e32 v177, 0x3f3504f3, v1
	v_mul_f32_e32 v178, 0x3f3504f3, v2
	v_mul_f32_e32 v179, 0x3f3504f3, v3
	v_fma_f32 v180, |v176|, s9, 1.0
	v_fma_f32 v181, |v177|, s9, 1.0
	v_fma_f32 v182, |v178|, s9, 1.0
	v_fma_f32 v183, |v179|, s9, 1.0
	v_rcp_f32_e32 v180, v180
	v_rcp_f32_e32 v181, v181
	v_rcp_f32_e32 v182, v182
	v_rcp_f32_e32 v183, v183
	v_mul_f32_e32 v188, 0.5, v0
	v_mul_f32_e32 v189, 0.5, v1
	v_mul_f32_e32 v190, 0.5, v2
	v_mul_f32_e32 v191, 0.5, v3
	v_fmamk_f32 v184, v180, 0x3f87dc22, v206
	v_fmamk_f32 v185, v181, 0x3f87dc22, v206
	v_fmamk_f32 v186, v182, 0x3f87dc22, v206
	v_fmamk_f32 v187, v183, 0x3f87dc22, v206
	v_fmaak_f32 v184, v184, v180, 0x3fb5f0e3
	v_fmaak_f32 v185, v185, v181, 0x3fb5f0e3
	v_fmaak_f32 v186, v186, v182, 0x3fb5f0e3
	v_fmaak_f32 v187, v187, v183, 0x3fb5f0e3
	v_fmaak_f32 v184, v184, v180, 0xbe91a98e
	v_fmaak_f32 v185, v185, v181, 0xbe91a98e
	v_fmaak_f32 v186, v186, v182, 0xbe91a98e
	v_fmaak_f32 v187, v187, v183, 0xbe91a98e
	v_fmaak_f32 v184, v184, v180, 0x3e827906
	v_fmaak_f32 v185, v185, v181, 0x3e827906
	v_fmaak_f32 v186, v186, v182, 0x3e827906
	v_fmaak_f32 v187, v187, v183, 0x3e827906
	v_mul_f32_e32 v180, v180, v184
	v_mul_f32_e32 v181, v181, v185
	v_mul_f32_e32 v182, v182, v186
	v_mul_f32_e32 v183, v183, v187
	v_mul_f32_e64 v184, |v176|, |v176|
	v_mul_f32_e64 v185, |v177|, |v177|
	v_mul_f32_e64 v186, |v178|, |v178|
	v_mul_f32_e64 v187, |v179|, |v179|
	v_mul_f32_e32 v184, 0xbfb8aa3b, v184
	v_mul_f32_e32 v185, 0xbfb8aa3b, v185
	v_mul_f32_e32 v186, 0xbfb8aa3b, v186
	v_mul_f32_e32 v187, 0xbfb8aa3b, v187
	v_exp_f32_e32 v184, v184
	v_exp_f32_e32 v185, v185
	v_exp_f32_e32 v186, v186
	v_exp_f32_e32 v187, v187
	v_fma_f32 v180, -v184, v180, 1.0
	v_fma_f32 v181, -v185, v181, 1.0
	v_fma_f32 v182, -v186, v182, 1.0
	v_fma_f32 v183, -v187, v183, 1.0
	v_bfi_b32 v176, s10, v180, v176
	v_bfi_b32 v177, s10, v181, v177
	v_bfi_b32 v178, s10, v182, v178
	v_bfi_b32 v179, s10, v183, v179
	v_add_f32_e32 v176, 1.0, v176
	v_add_f32_e32 v177, 1.0, v177
	v_add_f32_e32 v178, 1.0, v178
	v_add_f32_e32 v179, 1.0, v179
	v_mul_f32_e32 v188, v188, v176
	v_mul_f32_e32 v189, v189, v177
	v_mul_f32_e32 v190, v190, v178
	v_mul_f32_e32 v191, v191, v179
	v_cvt_pk_bf16_f32 v142, v188, v189
	v_cvt_pk_bf16_f32 v143, v190, v191
	s_nop 1
	v_permlane16_swap_b32_e32 v148, v150
	v_permlane16_swap_b32_e32 v149, v151
	global_store_dwordx4 v[172:173], v[148:151], off offset:256
	s_nop 1
	v_permlane16_swap_b32_e32 v140, v142
	v_permlane16_swap_b32_e32 v141, v143
	global_store_dwordx4 v[174:175], v[140:143], off offset:256
	s_branch .LBB0_958
; template <class Epi>
; __device__ __forceinline__ void gemm_tile8(const u16* __restrict__ A, long lda, const u16* __restrict__ Bt, long ldb, int K, char* shmc, Epi epi){
;     ...
; #pragma unroll
;   for(int ai=0;ai<2;++ai)
; #pragma unroll
;     for(int bj=0;bj<2;++bj)
; #pragma unroll
;       for(int m=0;m<4;++m)
; #pragma unroll
;         for(int n=0;n<2;++n) epi(ai*HALF+wr*64+m*16+fr, bj*HALF+wc*32+n*16+fq*4, acc[ai][bj][m][n]);
; __device__ __forceinline__ void ph_proj(const Params& p, int l, char* shm) {
;     ...
;       if (pn == 34) {
;         *(f32x4*)(p.KW + (size_t)(brow + r) * 256 + c) = v;
.Lpj_f32:
	v_add_u32_e32 v135, s8, v146
	v_mov_b32_e32 v137, v33
	v_mov_b32_e32 v139, v33
	v_readlane_b32 s0, v246, 63
	v_readlane_b32 s1, v245, 0
	v_lshlrev_b32_e32 v136, 2, v134
	v_mov_b32_e32 v138, v135
	v_lshlrev_b64 v[160:161], 10, v[138:139]
	v_lshl_add_u64 v[160:161], s[0:1], 0, v[160:161]
	v_lshl_add_u64 v[160:161], v[160:161], 0, v[136:137]
	v_add_u32_e32 v138, 16, v135
	v_lshlrev_b64 v[162:163], 10, v[138:139]
	v_lshl_add_u64 v[162:163], s[0:1], 0, v[162:163]
	v_lshl_add_u64 v[162:163], v[162:163], 0, v[136:137]
	v_add_u32_e32 v138, 32, v135
	v_lshlrev_b64 v[164:165], 10, v[138:139]
	v_lshl_add_u64 v[164:165], s[0:1], 0, v[164:165]
	v_lshl_add_u64 v[164:165], v[164:165], 0, v[136:137]
	v_add_u32_e32 v138, 48, v135
	v_lshlrev_b64 v[166:167], 10, v[138:139]
	v_lshl_add_u64 v[166:167], s[0:1], 0, v[166:167]
	v_lshl_add_u64 v[166:167], v[166:167], 0, v[136:137]
	v_add_u32_e32 v138, 0x80, v135
	v_lshlrev_b64 v[168:169], 10, v[138:139]
	v_lshl_add_u64 v[168:169], s[0:1], 0, v[168:169]
	v_lshl_add_u64 v[168:169], v[168:169], 0, v[136:137]
	v_add_u32_e32 v138, 0x90, v135
	v_lshlrev_b64 v[170:171], 10, v[138:139]
	v_lshl_add_u64 v[170:171], s[0:1], 0, v[170:171]
	v_lshl_add_u64 v[170:171], v[170:171], 0, v[136:137]
	v_add_u32_e32 v138, 0xa0, v135
	v_lshlrev_b64 v[172:173], 10, v[138:139]
	v_lshl_add_u64 v[172:173], s[0:1], 0, v[172:173]
	v_lshl_add_u64 v[172:173], v[172:173], 0, v[136:137]
	v_add_u32_e32 v138, 0xb0, v135
	v_lshlrev_b64 v[174:175], 10, v[138:139]
	v_lshl_add_u64 v[174:175], s[0:1], 0, v[174:175]
	v_lshl_add_u64 v[174:175], v[174:175], 0, v[136:137]
	global_store_dwordx4 v[160:161], v[126:129], off
	global_store_dwordx4 v[160:161], v[122:125], off offset:64
	global_store_dwordx4 v[162:163], v[118:121], off
	global_store_dwordx4 v[162:163], v[114:117], off offset:64
	global_store_dwordx4 v[164:165], v[110:113], off
	global_store_dwordx4 v[164:165], v[106:109], off offset:64
	global_store_dwordx4 v[166:167], v[102:105], off
	global_store_dwordx4 v[166:167], v[98:101], off offset:64
	global_store_dwordx4 v[160:161], v[94:97], off offset:512
	global_store_dwordx4 v[160:161], v[90:93], off offset:576
	global_store_dwordx4 v[162:163], v[86:89], off offset:512
	global_store_dwordx4 v[162:163], v[82:85], off offset:576
	global_store_dwordx4 v[164:165], v[78:81], off offset:512
	global_store_dwordx4 v[164:165], v[74:77], off offset:576
	global_store_dwordx4 v[166:167], v[70:73], off offset:512
	global_store_dwordx4 v[166:167], v[66:69], off offset:576
	global_store_dwordx4 v[168:169], v[62:65], off
	global_store_dwordx4 v[168:169], v[58:61], off offset:64
	global_store_dwordx4 v[170:171], v[54:57], off
	global_store_dwordx4 v[170:171], v[50:53], off offset:64
	global_store_dwordx4 v[172:173], v[46:49], off
	global_store_dwordx4 v[172:173], v[42:45], off offset:64
	global_store_dwordx4 v[174:175], v[38:41], off
	global_store_dwordx4 v[174:175], v[34:37], off offset:64
	global_store_dwordx4 v[168:169], v[28:31], off offset:512
	global_store_dwordx4 v[168:169], v[24:27], off offset:576
	global_store_dwordx4 v[170:171], v[20:23], off offset:512
	global_store_dwordx4 v[170:171], v[16:19], off offset:576
	global_store_dwordx4 v[172:173], v[12:15], off offset:512
	global_store_dwordx4 v[172:173], v[8:11], off offset:576
	global_store_dwordx4 v[174:175], v[4:7], off offset:512
	global_store_dwordx4 v[174:175], v[0:3], off offset:576
	s_branch .LBB0_958
